# GEMM super-phases: s_setprio 0 issued after the closing s_barrier instead of before it (on top of v004)
# baseline (speedup 1.0000x reference)
; #define PG8_STAGE(bufoff, gbase, voff) do { _Pragma("unroll") for (int _i = 0; _i < 2; ++_i) \
;         __builtin_amdgcn_global_load_lds((const unsigned*)((const char*)(gbase) + (voff)[_i]), (PG8_LAS unsigned*)(lds + (bufoff) + ldsw + _i * 8192), 16, 0, 0); } while (0)
; #define PG8_LDA(dst, b, h) do { _Pragma("unroll") for (int m = 0; m < 4; ++m) _Pragma("unroll") for (int k = 0; k < 2; ++k) dst[m][k] = *(const PG8_LAS bf16x8*)(lds + PG8_SA(b, h) + aoff + m * 2048 + k * 1024); } while (0)
; #define PG8_LDB(dst, b, h) do { _Pragma("unroll") for (int n = 0; n < 2; ++n) _Pragma("unroll") for (int k = 0; k < 2; ++k) dst[n][k] = *(const PG8_LAS bf16x8*)(lds + PG8_SB(b, h) + boff + n * 2048 + k * 1024); } while (0)
; #define PG8_MMA(ai, bj, At, Bt) do { __builtin_amdgcn_s_setprio(1); _Pragma("unroll") for (int m = 0; m < 4; ++m) _Pragma("unroll") for (int n = 0; n < 2; ++n) _Pragma("unroll") for (int k = 0; k < 2; ++k) \
;         acc[ai][bj][m][n] = __builtin_amdgcn_mfma_f32_16x16x32_bf16(Bt[n][k], At[m][k], acc[ai][bj][m][n], 0, 0, 0); __builtin_amdgcn_s_setprio(0); } while (0)
; #define PG8_BAR __builtin_amdgcn_s_barrier()
; template <class Epi, class Sched, bool ALIGN_EPI = false, bool SP2 = false>
; __device__ __forceinline__ void gemm_phase(PG8_LAS unsigned char* lds, const Gemm g, const Sched& S, const Epi& E, const int tid) {
;     ...
;             PG8_LDB(B0, 0, 0); PG8_LDB(B1, 0, 1); PG8_SCHED; PG8_LDA(At, 0, 0); PG8_STAGE(PG8_SA(1, 1), a1 + hstep, voffA);
;             PG8_WAIT_V(8); PG8_WAIT_L(0); PG8_BAR; PG8_MMA(0, 0, At, B0); PG8_MMA(0, 1, At, B1); PG8_BAR; PG8_SCHED;
;             PG8_LDA(At, 0, 1); PG8_STAGE(PG8_SB(0, 0), b2, voffB); PG8_STAGE(PG8_SB(0, 1), b2 + hstep, voffB); PG8_STAGE(PG8_SA(0, 0), a2, voffA);
;             PG8_WAIT_V(8); PG8_WAIT_L(0); PG8_BAR; PG8_MMA(1, 0, At, B0); PG8_MMA(1, 1, At, B1); PG8_BAR; PG8_SCHED;
;             PG8_LDB(B0, 1, 0); PG8_LDB(B1, 1, 1); PG8_SCHED; PG8_LDA(At, 1, 0); PG8_STAGE(PG8_SA(0, 1), a2 + hstep, voffA);
;             PG8_WAIT_V(8); PG8_WAIT_L(0); PG8_BAR; PG8_MMA(0, 0, At, B0); PG8_MMA(0, 1, At, B1); PG8_BAR; PG8_SCHED;
;             PG8_LDA(At, 1, 1); PG8_STAGE(PG8_SB(1, 0), b3, voffB); PG8_STAGE(PG8_SB(1, 1), b3 + hstep, voffB); PG8_STAGE(PG8_SA(1, 0), a3, voffA);
;             PG8_WAIT_V(8); PG8_WAIT_L(0); PG8_BAR; PG8_MMA(1, 0, At, B0); PG8_MMA(1, 1, At, B1); PG8_BAR; PG8_SCHED;
.LBB0_120:
	ds_read_b128 v[122:125], v191
	ds_read_b128 v[126:129], v192
	ds_read_b128 v[138:141], v193
	ds_read_b128 v[142:145], v194
	ds_read_b128 v[146:149], v195
	ds_read_b128 v[150:153], v196
	ds_read_b128 v[164:167], v197
	ds_read_b128 v[168:171], v198
	s_add_u32 s43, s30, 0xfffc0080
	s_addc_u32 s45, s31, -1
	s_cmp_eq_u32 s27, 12
	s_cselect_b32 s87, s5, s45
	s_cselect_b32 s86, s15, s43
	s_cselect_b32 s85, s20, s26
	s_cselect_b32 s84, s21, s24
	s_mov_b32 m0, s38
	v_lshl_add_u64 v[188:189], s[30:31], 0, v[160:161]
	ds_read_b128 v[172:175], v190
	ds_read_b128 v[176:179], v190 offset:1024
	ds_read_b128 v[180:183], v190 offset:2048
	ds_read_b128 v[184:187], v190 offset:3072
	ds_read_b128 v[214:217], v190 offset:4096
	ds_read_b128 v[218:221], v190 offset:5120
	ds_read_b128 v[222:225], v190 offset:6144
	ds_read_b128 v[226:229], v190 offset:7168
	global_load_lds_dwordx4 v[188:189], off
	v_lshl_add_u64 v[188:189], s[30:31], 0, v[162:163]
	s_mov_b32 m0, s0
	s_nop 0
	global_load_lds_dwordx4 v[188:189], off
	s_waitcnt vmcnt(8)
	s_waitcnt lgkmcnt(0)
	s_barrier
	s_setprio 1
	s_waitcnt lgkmcnt(0)
	v_mfma_f32_16x16x32_bf16 v[134:137], v[122:125], v[172:175], v[134:137]
	v_mfma_f32_16x16x32_bf16 v[130:133], v[138:141], v[172:175], v[130:133]
	v_mfma_f32_16x16x32_bf16 v[118:121], v[122:125], v[180:183], v[118:121]
	v_mfma_f32_16x16x32_bf16 v[114:117], v[138:141], v[180:183], v[114:117]
	v_mfma_f32_16x16x32_bf16 v[110:113], v[122:125], v[214:217], v[110:113]
	v_mfma_f32_16x16x32_bf16 v[106:109], v[138:141], v[214:217], v[106:109]
	v_mfma_f32_16x16x32_bf16 v[102:105], v[122:125], v[222:225], v[102:105]
	v_mfma_f32_16x16x32_bf16 v[98:101], v[138:141], v[222:225], v[98:101]
	v_mfma_f32_16x16x32_bf16 v[134:137], v[126:129], v[176:179], v[134:137]
	v_mfma_f32_16x16x32_bf16 v[130:133], v[142:145], v[176:179], v[130:133]
	v_mfma_f32_16x16x32_bf16 v[118:121], v[126:129], v[184:187], v[118:121]
	v_mfma_f32_16x16x32_bf16 v[114:117], v[142:145], v[184:187], v[114:117]
	v_mfma_f32_16x16x32_bf16 v[110:113], v[126:129], v[218:221], v[110:113]
	v_mfma_f32_16x16x32_bf16 v[106:109], v[142:145], v[218:221], v[106:109]
	v_mfma_f32_16x16x32_bf16 v[102:105], v[126:129], v[226:229], v[102:105]
	v_mfma_f32_16x16x32_bf16 v[98:101], v[142:145], v[226:229], v[98:101]
	s_setprio 0
	s_setprio 1
	v_mfma_f32_16x16x32_bf16 v[62:65], v[146:149], v[172:175], v[62:65]
	v_mfma_f32_16x16x32_bf16 v[58:61], v[164:167], v[172:175], v[58:61]
	v_mfma_f32_16x16x32_bf16 v[54:57], v[146:149], v[180:183], v[54:57]
	v_mfma_f32_16x16x32_bf16 v[50:53], v[164:167], v[180:183], v[50:53]
	v_mfma_f32_16x16x32_bf16 v[46:49], v[146:149], v[214:217], v[46:49]
	v_mfma_f32_16x16x32_bf16 v[42:45], v[164:167], v[214:217], v[42:45]
	v_mfma_f32_16x16x32_bf16 v[38:41], v[146:149], v[222:225], v[38:41]
	v_mfma_f32_16x16x32_bf16 v[34:37], v[164:167], v[222:225], v[34:37]
	v_mfma_f32_16x16x32_bf16 v[62:65], v[150:153], v[176:179], v[62:65]
	v_mfma_f32_16x16x32_bf16 v[58:61], v[168:171], v[176:179], v[58:61]
	v_mfma_f32_16x16x32_bf16 v[54:57], v[150:153], v[184:187], v[54:57]
	v_mfma_f32_16x16x32_bf16 v[50:53], v[168:171], v[184:187], v[50:53]
	v_mfma_f32_16x16x32_bf16 v[46:49], v[150:153], v[218:221], v[46:49]
	v_mfma_f32_16x16x32_bf16 v[42:45], v[168:171], v[218:221], v[42:45]
	v_mfma_f32_16x16x32_bf16 v[38:41], v[150:153], v[226:229], v[38:41]
	v_mfma_f32_16x16x32_bf16 v[34:37], v[168:171], v[226:229], v[34:37]
	s_barrier
	s_setprio 0
	s_mov_b32 m0, s6
	v_lshl_add_u64 v[188:189], s[84:85], 0, v[0:1]
	s_add_u32 s50, s84, 0x40000
	ds_read_b128 v[172:175], v190 offset:16384
	ds_read_b128 v[176:179], v190 offset:17408
	ds_read_b128 v[180:183], v190 offset:18432
	ds_read_b128 v[184:187], v190 offset:19456
	ds_read_b128 v[214:217], v190 offset:20480
	ds_read_b128 v[218:221], v190 offset:21504
	ds_read_b128 v[222:225], v190 offset:22528
	ds_read_b128 v[226:229], v190 offset:23552
	global_load_lds_dwordx4 v[188:189], off
	v_lshl_add_u64 v[208:209], s[84:85], 0, v[154:155]
	s_mov_b32 m0, s8
	s_addc_u32 s51, s85, 0
	global_load_lds_dwordx4 v[208:209], off
	v_lshl_add_u64 v[210:211], s[50:51], 0, v[0:1]
	s_mov_b32 m0, s9
	v_lshl_add_u64 v[212:213], s[86:87], 0, v[156:157]
	global_load_lds_dwordx4 v[210:211], off
	v_lshl_add_u64 v[210:211], s[50:51], 0, v[154:155]
	s_mov_b32 m0, s14
	s_nop 0
	global_load_lds_dwordx4 v[210:211], off
	v_lshl_add_u64 v[210:211], s[86:87], 0, v[158:159]
	s_mov_b32 m0, s17
	s_nop 0
	global_load_lds_dwordx4 v[210:211], off
	s_mov_b32 m0, s34
	s_nop 0
	global_load_lds_dwordx4 v[212:213], off
	s_waitcnt vmcnt(8)
	s_waitcnt lgkmcnt(0)
	s_barrier
; #define PG8_STAGE(bufoff, gbase, voff) do { _Pragma("unroll") for (int _i = 0; _i < 2; ++_i) \
;         __builtin_amdgcn_global_load_lds((const unsigned*)((const char*)(gbase) + (voff)[_i]), (PG8_LAS unsigned*)(lds + (bufoff) + ldsw + _i * 8192), 16, 0, 0); } while (0)
; #define PG8_LDA(dst, b, h) do { _Pragma("unroll") for (int m = 0; m < 4; ++m) _Pragma("unroll") for (int k = 0; k < 2; ++k) dst[m][k] = *(const PG8_LAS bf16x8*)(lds + PG8_SA(b, h) + aoff + m * 2048 + k * 1024); } while (0)
; #define PG8_LDB(dst, b, h) do { _Pragma("unroll") for (int n = 0; n < 2; ++n) _Pragma("unroll") for (int k = 0; k < 2; ++k) dst[n][k] = *(const PG8_LAS bf16x8*)(lds + PG8_SB(b, h) + boff + n * 2048 + k * 1024); } while (0)
; #define PG8_MMA(ai, bj, At, Bt) do { __builtin_amdgcn_s_setprio(1); _Pragma("unroll") for (int m = 0; m < 4; ++m) _Pragma("unroll") for (int n = 0; n < 2; ++n) _Pragma("unroll") for (int k = 0; k < 2; ++k) \
;         acc[ai][bj][m][n] = __builtin_amdgcn_mfma_f32_16x16x32_bf16(Bt[n][k], At[m][k], acc[ai][bj][m][n], 0, 0, 0); __builtin_amdgcn_s_setprio(0); } while (0)
; #define PG8_BAR __builtin_amdgcn_s_barrier()
; template <class Epi, class Sched, bool ALIGN_EPI = false, bool SP2 = false>
; __device__ __forceinline__ void gemm_phase(PG8_LAS unsigned char* lds, const Gemm g, const Sched& S, const Epi& E, const int tid) {
;     ...
;             PG8_LDB(B0, 0, 0); PG8_LDB(B1, 0, 1); PG8_SCHED; PG8_LDA(At, 0, 0); PG8_STAGE(PG8_SA(1, 1), a1 + hstep, voffA);
;             PG8_WAIT_V(8); PG8_WAIT_L(0); PG8_BAR; PG8_MMA(0, 0, At, B0); PG8_MMA(0, 1, At, B1); PG8_BAR; PG8_SCHED;
;             PG8_LDA(At, 0, 1); PG8_STAGE(PG8_SB(0, 0), b2, voffB); PG8_STAGE(PG8_SB(0, 1), b2 + hstep, voffB); PG8_STAGE(PG8_SA(0, 0), a2, voffA);
;             PG8_WAIT_V(8); PG8_WAIT_L(0); PG8_BAR; PG8_MMA(1, 0, At, B0); PG8_MMA(1, 1, At, B1); PG8_BAR; PG8_SCHED;
;             PG8_LDB(B0, 1, 0); PG8_LDB(B1, 1, 1); PG8_SCHED; PG8_LDA(At, 1, 0); PG8_STAGE(PG8_SA(0, 1), a2 + hstep, voffA);
;             PG8_WAIT_V(8); PG8_WAIT_L(0); PG8_BAR; PG8_MMA(0, 0, At, B0); PG8_MMA(0, 1, At, B1); PG8_BAR; PG8_SCHED;
;             PG8_LDA(At, 1, 1); PG8_STAGE(PG8_SB(1, 0), b3, voffB); PG8_STAGE(PG8_SB(1, 1), b3 + hstep, voffB); PG8_STAGE(PG8_SA(1, 0), a3, voffA);
;             PG8_WAIT_V(8); PG8_WAIT_L(0); PG8_BAR; PG8_MMA(1, 0, At, B0); PG8_MMA(1, 1, At, B1); PG8_BAR; PG8_SCHED;
	s_setprio 1
	s_waitcnt lgkmcnt(0)
	v_mfma_f32_16x16x32_bf16 v[94:97], v[122:125], v[172:175], v[94:97]
	v_mfma_f32_16x16x32_bf16 v[90:93], v[138:141], v[172:175], v[90:93]
	v_mfma_f32_16x16x32_bf16 v[86:89], v[122:125], v[180:183], v[86:89]
	v_mfma_f32_16x16x32_bf16 v[82:85], v[138:141], v[180:183], v[82:85]
	v_mfma_f32_16x16x32_bf16 v[78:81], v[122:125], v[214:217], v[78:81]
	v_mfma_f32_16x16x32_bf16 v[74:77], v[138:141], v[214:217], v[74:77]
	v_mfma_f32_16x16x32_bf16 v[70:73], v[122:125], v[222:225], v[70:73]
	v_mfma_f32_16x16x32_bf16 v[66:69], v[138:141], v[222:225], v[66:69]
	v_mfma_f32_16x16x32_bf16 v[94:97], v[126:129], v[176:179], v[94:97]
	v_mfma_f32_16x16x32_bf16 v[90:93], v[142:145], v[176:179], v[90:93]
	v_mfma_f32_16x16x32_bf16 v[86:89], v[126:129], v[184:187], v[86:89]
	v_mfma_f32_16x16x32_bf16 v[82:85], v[142:145], v[184:187], v[82:85]
	v_mfma_f32_16x16x32_bf16 v[78:81], v[126:129], v[218:221], v[78:81]
	v_mfma_f32_16x16x32_bf16 v[74:77], v[142:145], v[218:221], v[74:77]
	v_mfma_f32_16x16x32_bf16 v[70:73], v[126:129], v[226:229], v[70:73]
	v_mfma_f32_16x16x32_bf16 v[66:69], v[142:145], v[226:229], v[66:69]
	s_setprio 0
	s_setprio 1
	v_mfma_f32_16x16x32_bf16 v[30:33], v[146:149], v[172:175], v[30:33]
	v_mfma_f32_16x16x32_bf16 v[26:29], v[164:167], v[172:175], v[26:29]
	v_mfma_f32_16x16x32_bf16 v[22:25], v[146:149], v[180:183], v[22:25]
	v_mfma_f32_16x16x32_bf16 v[18:21], v[164:167], v[180:183], v[18:21]
	v_mfma_f32_16x16x32_bf16 v[14:17], v[146:149], v[214:217], v[14:17]
	v_mfma_f32_16x16x32_bf16 v[10:13], v[164:167], v[214:217], v[10:13]
	v_mfma_f32_16x16x32_bf16 v[6:9], v[146:149], v[222:225], v[6:9]
	v_mfma_f32_16x16x32_bf16 v[2:5], v[164:167], v[222:225], v[2:5]
	v_mfma_f32_16x16x32_bf16 v[30:33], v[150:153], v[176:179], v[30:33]
	v_mfma_f32_16x16x32_bf16 v[26:29], v[168:171], v[176:179], v[26:29]
	v_mfma_f32_16x16x32_bf16 v[22:25], v[150:153], v[184:187], v[22:25]
	v_mfma_f32_16x16x32_bf16 v[18:21], v[168:171], v[184:187], v[18:21]
	v_mfma_f32_16x16x32_bf16 v[14:17], v[150:153], v[218:221], v[14:17]
	v_mfma_f32_16x16x32_bf16 v[10:13], v[168:171], v[218:221], v[10:13]
	v_mfma_f32_16x16x32_bf16 v[6:9], v[150:153], v[226:229], v[6:9]
	v_mfma_f32_16x16x32_bf16 v[2:5], v[168:171], v[226:229], v[2:5]
	s_barrier
	s_setprio 0
	ds_read_b128 v[122:125], v199
	ds_read_b128 v[126:129], v200
	ds_read_b128 v[138:141], v201
	ds_read_b128 v[142:145], v202
	ds_read_b128 v[146:149], v203
	ds_read_b128 v[150:153], v204
	ds_read_b128 v[164:167], v205
	ds_read_b128 v[168:171], v206
	s_add_u32 s50, s86, 0x40000
	s_addc_u32 s51, s87, 0
	s_mov_b32 m0, s35
	v_lshl_add_u64 v[230:231], s[50:51], 0, v[158:159]
	ds_read_b128 v[172:175], v190 offset:32768
	ds_read_b128 v[176:179], v190 offset:33792
	ds_read_b128 v[180:183], v190 offset:34816
	ds_read_b128 v[184:187], v190 offset:35840
	ds_read_b128 v[214:217], v190 offset:36864
	ds_read_b128 v[218:221], v190 offset:37888
	ds_read_b128 v[222:225], v190 offset:38912
	ds_read_b128 v[226:229], v190 offset:39936
	global_load_lds_dwordx4 v[230:231], off
	v_lshl_add_u64 v[230:231], s[50:51], 0, v[156:157]
	s_mov_b32 m0, s88
	s_nop 0
	global_load_lds_dwordx4 v[230:231], off
	s_waitcnt vmcnt(8)
	s_waitcnt lgkmcnt(0)
	s_barrier
	s_setprio 1
	s_waitcnt lgkmcnt(0)
	v_mfma_f32_16x16x32_bf16 v[134:137], v[122:125], v[172:175], v[134:137]
	v_mfma_f32_16x16x32_bf16 v[130:133], v[138:141], v[172:175], v[130:133]
	v_mfma_f32_16x16x32_bf16 v[118:121], v[122:125], v[180:183], v[118:121]
	v_mfma_f32_16x16x32_bf16 v[114:117], v[138:141], v[180:183], v[114:117]
	v_mfma_f32_16x16x32_bf16 v[110:113], v[122:125], v[214:217], v[110:113]
	v_mfma_f32_16x16x32_bf16 v[106:109], v[138:141], v[214:217], v[106:109]
	v_mfma_f32_16x16x32_bf16 v[102:105], v[122:125], v[222:225], v[102:105]
	v_mfma_f32_16x16x32_bf16 v[98:101], v[138:141], v[222:225], v[98:101]
	v_mfma_f32_16x16x32_bf16 v[134:137], v[126:129], v[176:179], v[134:137]
	v_mfma_f32_16x16x32_bf16 v[130:133], v[142:145], v[176:179], v[130:133]
	v_mfma_f32_16x16x32_bf16 v[118:121], v[126:129], v[184:187], v[118:121]
	v_mfma_f32_16x16x32_bf16 v[114:117], v[142:145], v[184:187], v[114:117]
	v_mfma_f32_16x16x32_bf16 v[110:113], v[126:129], v[218:221], v[110:113]
	v_mfma_f32_16x16x32_bf16 v[106:109], v[142:145], v[218:221], v[106:109]
	v_mfma_f32_16x16x32_bf16 v[102:105], v[126:129], v[226:229], v[102:105]
	v_mfma_f32_16x16x32_bf16 v[98:101], v[142:145], v[226:229], v[98:101]
	s_setprio 0
	s_setprio 1
	v_mfma_f32_16x16x32_bf16 v[62:65], v[146:149], v[172:175], v[62:65]
	v_mfma_f32_16x16x32_bf16 v[58:61], v[164:167], v[172:175], v[58:61]
	v_mfma_f32_16x16x32_bf16 v[54:57], v[146:149], v[180:183], v[54:57]
	v_mfma_f32_16x16x32_bf16 v[50:53], v[164:167], v[180:183], v[50:53]
	v_mfma_f32_16x16x32_bf16 v[46:49], v[146:149], v[214:217], v[46:49]
	v_mfma_f32_16x16x32_bf16 v[42:45], v[164:167], v[214:217], v[42:45]
	v_mfma_f32_16x16x32_bf16 v[38:41], v[146:149], v[222:225], v[38:41]
	v_mfma_f32_16x16x32_bf16 v[34:37], v[164:167], v[222:225], v[34:37]
	v_mfma_f32_16x16x32_bf16 v[62:65], v[150:153], v[176:179], v[62:65]
	v_mfma_f32_16x16x32_bf16 v[58:61], v[168:171], v[176:179], v[58:61]
	v_mfma_f32_16x16x32_bf16 v[54:57], v[150:153], v[184:187], v[54:57]
	v_mfma_f32_16x16x32_bf16 v[50:53], v[168:171], v[184:187], v[50:53]
	v_mfma_f32_16x16x32_bf16 v[46:49], v[150:153], v[218:221], v[46:49]
	v_mfma_f32_16x16x32_bf16 v[42:45], v[168:171], v[218:221], v[42:45]
	v_mfma_f32_16x16x32_bf16 v[38:41], v[150:153], v[226:229], v[38:41]
	v_mfma_f32_16x16x32_bf16 v[34:37], v[168:171], v[226:229], v[34:37]
	s_barrier
; #define PG8_STAGE(bufoff, gbase, voff) do { _Pragma("unroll") for (int _i = 0; _i < 2; ++_i) \
;         __builtin_amdgcn_global_load_lds((const unsigned*)((const char*)(gbase) + (voff)[_i]), (PG8_LAS unsigned*)(lds + (bufoff) + ldsw + _i * 8192), 16, 0, 0); } while (0)
; #define PG8_LDA(dst, b, h) do { _Pragma("unroll") for (int m = 0; m < 4; ++m) _Pragma("unroll") for (int k = 0; k < 2; ++k) dst[m][k] = *(const PG8_LAS bf16x8*)(lds + PG8_SA(b, h) + aoff + m * 2048 + k * 1024); } while (0)
; #define PG8_LDB(dst, b, h) do { _Pragma("unroll") for (int n = 0; n < 2; ++n) _Pragma("unroll") for (int k = 0; k < 2; ++k) dst[n][k] = *(const PG8_LAS bf16x8*)(lds + PG8_SB(b, h) + boff + n * 2048 + k * 1024); } while (0)
; #define PG8_MMA(ai, bj, At, Bt) do { __builtin_amdgcn_s_setprio(1); _Pragma("unroll") for (int m = 0; m < 4; ++m) _Pragma("unroll") for (int n = 0; n < 2; ++n) _Pragma("unroll") for (int k = 0; k < 2; ++k) \
;         acc[ai][bj][m][n] = __builtin_amdgcn_mfma_f32_16x16x32_bf16(Bt[n][k], At[m][k], acc[ai][bj][m][n], 0, 0, 0); __builtin_amdgcn_s_setprio(0); } while (0)
; #define PG8_BAR __builtin_amdgcn_s_barrier()
; template <class Epi, class Sched, bool ALIGN_EPI = false, bool SP2 = false>
; __device__ __forceinline__ void gemm_phase(PG8_LAS unsigned char* lds, const Gemm g, const Sched& S, const Epi& E, const int tid) {
;     ...
;             PG8_LDB(B0, 0, 0); PG8_LDB(B1, 0, 1); PG8_SCHED; PG8_LDA(At, 0, 0); PG8_STAGE(PG8_SA(1, 1), a1 + hstep, voffA);
;             PG8_WAIT_V(8); PG8_WAIT_L(0); PG8_BAR; PG8_MMA(0, 0, At, B0); PG8_MMA(0, 1, At, B1); PG8_BAR; PG8_SCHED;
;             PG8_LDA(At, 0, 1); PG8_STAGE(PG8_SB(0, 0), b2, voffB); PG8_STAGE(PG8_SB(0, 1), b2 + hstep, voffB); PG8_STAGE(PG8_SA(0, 0), a2, voffA);
;             PG8_WAIT_V(8); PG8_WAIT_L(0); PG8_BAR; PG8_MMA(1, 0, At, B0); PG8_MMA(1, 1, At, B1); PG8_BAR; PG8_SCHED;
;             PG8_LDB(B0, 1, 0); PG8_LDB(B1, 1, 1); PG8_SCHED; PG8_LDA(At, 1, 0); PG8_STAGE(PG8_SA(0, 1), a2 + hstep, voffA);
;             PG8_WAIT_V(8); PG8_WAIT_L(0); PG8_BAR; PG8_MMA(0, 0, At, B0); PG8_MMA(0, 1, At, B1); PG8_BAR; PG8_SCHED;
;             PG8_LDA(At, 1, 1); PG8_STAGE(PG8_SB(1, 0), b3, voffB); PG8_STAGE(PG8_SB(1, 1), b3 + hstep, voffB); PG8_STAGE(PG8_SA(1, 0), a3, voffA);
;             PG8_WAIT_V(8); PG8_WAIT_L(0); PG8_BAR; PG8_MMA(1, 0, At, B0); PG8_MMA(1, 1, At, B1); PG8_BAR; PG8_SCHED;
	s_setprio 0
	s_mov_b32 m0, s89
	v_lshl_add_u64 v[188:189], v[188:189], 0, s[12:13]
	s_add_u32 s50, s84, 0x40080
	ds_read_b128 v[172:175], v190 offset:49152
	ds_read_b128 v[176:179], v190 offset:50176
	ds_read_b128 v[180:183], v190 offset:51200
	ds_read_b128 v[184:187], v190 offset:52224
	ds_read_b128 v[214:217], v190 offset:53248
	ds_read_b128 v[218:221], v190 offset:54272
	ds_read_b128 v[222:225], v190 offset:55296
	ds_read_b128 v[226:229], v190 offset:56320
	global_load_lds_dwordx4 v[188:189], off
	v_lshl_add_u64 v[188:189], v[208:209], 0, s[12:13]
	s_mov_b32 m0, s90
	s_addc_u32 s51, s85, 0
	global_load_lds_dwordx4 v[188:189], off
	v_lshl_add_u64 v[188:189], s[50:51], 0, v[0:1]
	s_mov_b32 m0, s41
	s_nop 0
	global_load_lds_dwordx4 v[188:189], off
	v_lshl_add_u64 v[188:189], s[50:51], 0, v[154:155]
	s_mov_b32 m0, s40
	s_nop 0
	global_load_lds_dwordx4 v[188:189], off
	v_lshl_add_u64 v[188:189], v[210:211], 0, s[12:13]
	s_mov_b32 m0, s91
	s_nop 0
	global_load_lds_dwordx4 v[188:189], off
	v_lshl_add_u64 v[188:189], v[212:213], 0, s[12:13]
	s_mov_b32 m0, s1
	s_nop 0
	global_load_lds_dwordx4 v[188:189], off
	s_waitcnt vmcnt(8)
	s_waitcnt lgkmcnt(0)
	s_barrier
	s_setprio 1
	s_waitcnt lgkmcnt(0)
	v_mfma_f32_16x16x32_bf16 v[94:97], v[122:125], v[172:175], v[94:97]
	v_mfma_f32_16x16x32_bf16 v[90:93], v[138:141], v[172:175], v[90:93]
	v_mfma_f32_16x16x32_bf16 v[86:89], v[122:125], v[180:183], v[86:89]
	v_mfma_f32_16x16x32_bf16 v[82:85], v[138:141], v[180:183], v[82:85]
	v_mfma_f32_16x16x32_bf16 v[78:81], v[122:125], v[214:217], v[78:81]
	v_mfma_f32_16x16x32_bf16 v[74:77], v[138:141], v[214:217], v[74:77]
	v_mfma_f32_16x16x32_bf16 v[70:73], v[122:125], v[222:225], v[70:73]
	v_mfma_f32_16x16x32_bf16 v[66:69], v[138:141], v[222:225], v[66:69]
	v_mfma_f32_16x16x32_bf16 v[94:97], v[126:129], v[176:179], v[94:97]
	v_mfma_f32_16x16x32_bf16 v[90:93], v[142:145], v[176:179], v[90:93]
	v_mfma_f32_16x16x32_bf16 v[86:89], v[126:129], v[184:187], v[86:89]
	v_mfma_f32_16x16x32_bf16 v[82:85], v[142:145], v[184:187], v[82:85]
	v_mfma_f32_16x16x32_bf16 v[78:81], v[126:129], v[218:221], v[78:81]
	v_mfma_f32_16x16x32_bf16 v[74:77], v[142:145], v[218:221], v[74:77]
	v_mfma_f32_16x16x32_bf16 v[70:73], v[126:129], v[226:229], v[70:73]
	v_mfma_f32_16x16x32_bf16 v[66:69], v[142:145], v[226:229], v[66:69]
	s_setprio 0
	s_setprio 1
	v_mfma_f32_16x16x32_bf16 v[30:33], v[146:149], v[172:175], v[30:33]
	v_mfma_f32_16x16x32_bf16 v[26:29], v[164:167], v[172:175], v[26:29]
	v_mfma_f32_16x16x32_bf16 v[22:25], v[146:149], v[180:183], v[22:25]
	v_mfma_f32_16x16x32_bf16 v[18:21], v[164:167], v[180:183], v[18:21]
	v_mfma_f32_16x16x32_bf16 v[14:17], v[146:149], v[214:217], v[14:17]
	v_mfma_f32_16x16x32_bf16 v[10:13], v[164:167], v[214:217], v[10:13]
	v_mfma_f32_16x16x32_bf16 v[6:9], v[146:149], v[222:225], v[6:9]
	v_mfma_f32_16x16x32_bf16 v[2:5], v[164:167], v[222:225], v[2:5]
	v_mfma_f32_16x16x32_bf16 v[30:33], v[150:153], v[176:179], v[30:33]
	v_mfma_f32_16x16x32_bf16 v[26:29], v[168:171], v[176:179], v[26:29]
	v_mfma_f32_16x16x32_bf16 v[22:25], v[150:153], v[184:187], v[22:25]
	v_mfma_f32_16x16x32_bf16 v[18:21], v[168:171], v[184:187], v[18:21]
	v_mfma_f32_16x16x32_bf16 v[14:17], v[150:153], v[218:221], v[14:17]
	v_mfma_f32_16x16x32_bf16 v[10:13], v[168:171], v[218:221], v[10:13]
	v_mfma_f32_16x16x32_bf16 v[6:9], v[150:153], v[226:229], v[6:9]
	v_mfma_f32_16x16x32_bf16 v[2:5], v[168:171], v[226:229], v[2:5]
	s_barrier
	s_setprio 0
	s_add_i32 s27, s27, 2
	s_add_u32 s30, s30, 0x100
	s_addc_u32 s31, s31, 0
	s_add_u32 s24, s24, 0x100
	s_addc_u32 s26, s26, 0
	s_cmp_gt_u32 s27, 13
	s_cbranch_scc0 .LBB0_120
	v_readlane_b32 s20, v255, 54
	v_readlane_b32 s21, v255, 55
	s_and_b64 vcc, exec, s[20:21]
	s_cbranch_vccz .LBB0_123
	s_barrier

; #define PG8_STAGE(bufoff, gbase, voff) do { _Pragma("unroll") for (int _i = 0; _i < 2; ++_i) \
;         __builtin_amdgcn_global_load_lds((const unsigned*)((const char*)(gbase) + (voff)[_i]), (PG8_LAS unsigned*)(lds + (bufoff) + ldsw + _i * 8192), 16, 0, 0); } while (0)
; #define PG8_LDA(dst, b, h) do { _Pragma("unroll") for (int m = 0; m < 4; ++m) _Pragma("unroll") for (int k = 0; k < 2; ++k) dst[m][k] = *(const PG8_LAS bf16x8*)(lds + PG8_SA(b, h) + aoff + m * 2048 + k * 1024); } while (0)
; #define PG8_LDB(dst, b, h) do { _Pragma("unroll") for (int n = 0; n < 2; ++n) _Pragma("unroll") for (int k = 0; k < 2; ++k) dst[n][k] = *(const PG8_LAS bf16x8*)(lds + PG8_SB(b, h) + boff + n * 2048 + k * 1024); } while (0)
; #define PG8_MMA(ai, bj, At, Bt) do { __builtin_amdgcn_s_setprio(1); _Pragma("unroll") for (int m = 0; m < 4; ++m) _Pragma("unroll") for (int n = 0; n < 2; ++n) _Pragma("unroll") for (int k = 0; k < 2; ++k) \
;         acc[ai][bj][m][n] = __builtin_amdgcn_mfma_f32_16x16x32_bf16(Bt[n][k], At[m][k], acc[ai][bj][m][n], 0, 0, 0); __builtin_amdgcn_s_setprio(0); } while (0)
; #define PG8_BAR __builtin_amdgcn_s_barrier()
; template <class Epi, class Sched, bool ALIGN_EPI = false, bool SP2 = false>
; __device__ __forceinline__ void gemm_phase(PG8_LAS unsigned char* lds, const Gemm g, const Sched& S, const Epi& E, const int tid) {
;     ...
;             PG8_LDB(B0, 0, 0); PG8_LDB(B1, 0, 1); PG8_SCHED; PG8_LDA(At, 0, 0); PG8_STAGE(PG8_SA(1, 1), a1 + hstep, voffA);
;             PG8_WAIT_V(8); PG8_WAIT_L(0); PG8_BAR; PG8_MMA(0, 0, At, B0); PG8_MMA(0, 1, At, B1); PG8_BAR; PG8_SCHED;
;             PG8_LDA(At, 0, 1); PG8_STAGE(PG8_SB(0, 0), b2, voffB); PG8_STAGE(PG8_SB(0, 1), b2 + hstep, voffB); PG8_STAGE(PG8_SA(0, 0), a2, voffA);
;             PG8_WAIT_V(8); PG8_WAIT_L(0); PG8_BAR; PG8_MMA(1, 0, At, B0); PG8_MMA(1, 1, At, B1); PG8_BAR; PG8_SCHED;
;             PG8_LDB(B0, 1, 0); PG8_LDB(B1, 1, 1); PG8_SCHED; PG8_LDA(At, 1, 0); PG8_STAGE(PG8_SA(0, 1), a2 + hstep, voffA);
;             PG8_WAIT_V(8); PG8_WAIT_L(0); PG8_BAR; PG8_MMA(0, 0, At, B0); PG8_MMA(0, 1, At, B1); PG8_BAR; PG8_SCHED;
;             PG8_LDA(At, 1, 1); PG8_STAGE(PG8_SB(1, 0), b3, voffB); PG8_STAGE(PG8_SB(1, 1), b3 + hstep, voffB); PG8_STAGE(PG8_SA(1, 0), a3, voffA);
;             PG8_WAIT_V(8); PG8_WAIT_L(0); PG8_BAR; PG8_MMA(1, 0, At, B0); PG8_MMA(1, 1, At, B1); PG8_BAR; PG8_SCHED;
.LBB0_355:
	v_or_b32_e32 v98, 0x10000, v187
	v_add_u32_e32 v102, 0x10400, v187
	v_add_u32_e32 v130, 0x10800, v187
	v_add_u32_e32 v142, 0x10c00, v187
	v_or_b32_e32 v146, 0x14000, v187
	v_add_u32_e32 v160, 0x14400, v187
	v_add_u32_e32 v164, 0x14800, v187
	v_add_u32_e32 v168, 0x14c00, v187
	ds_read_b128 v[98:101], v98
	ds_read_b128 v[102:105], v102
	ds_read_b128 v[130:133], v130
	ds_read_b128 v[142:145], v142
	ds_read_b128 v[146:149], v146
	ds_read_b128 v[160:163], v160
	ds_read_b128 v[164:167], v164
	ds_read_b128 v[168:171], v168
	s_add_u32 s26, s30, 0xfffc0080
	s_addc_u32 s27, s31, -1
	s_cmp_eq_u32 s24, 12
	s_cselect_b32 s87, s4, s27
	s_cselect_b32 s86, s5, s26
	s_cselect_b32 s85, s15, s21
	s_cselect_b32 s84, s17, s20
	v_lshl_add_u64 v[180:181], s[30:31], 0, v[156:157]
	s_add_i32 m0, s6, 0xc000
	ds_read_b128 v[172:175], v186
	ds_read_b128 v[176:179], v186 offset:1024
	ds_read_b128 v[188:191], v186 offset:2048
	ds_read_b128 v[192:195], v186 offset:3072
	ds_read_b128 v[196:199], v186 offset:4096
	ds_read_b128 v[200:203], v186 offset:5120
	ds_read_b128 v[204:207], v186 offset:6144
	ds_read_b128 v[214:217], v186 offset:7168
	global_load_lds_dwordx4 v[180:181], off
	v_lshl_add_u64 v[180:181], s[30:31], 0, v[158:159]
	s_add_i32 m0, s6, 0xe000
	s_nop 0
	global_load_lds_dwordx4 v[180:181], off
	s_waitcnt vmcnt(8)
	s_waitcnt lgkmcnt(0)
	s_barrier
	s_setprio 1
	s_waitcnt lgkmcnt(0)
	v_mfma_f32_16x16x32_bf16 v[138:141], v[98:101], v[172:175], v[138:141]
	v_mfma_f32_16x16x32_bf16 v[134:137], v[130:133], v[172:175], v[134:137]
	v_mfma_f32_16x16x32_bf16 v[126:129], v[98:101], v[188:191], v[126:129]
	v_mfma_f32_16x16x32_bf16 v[122:125], v[130:133], v[188:191], v[122:125]
	v_mfma_f32_16x16x32_bf16 v[118:121], v[98:101], v[196:199], v[118:121]
	v_mfma_f32_16x16x32_bf16 v[114:117], v[130:133], v[196:199], v[114:117]
	v_mfma_f32_16x16x32_bf16 v[110:113], v[98:101], v[204:207], v[110:113]
	v_mfma_f32_16x16x32_bf16 v[106:109], v[130:133], v[204:207], v[106:109]
	v_mfma_f32_16x16x32_bf16 v[138:141], v[102:105], v[176:179], v[138:141]
	v_mfma_f32_16x16x32_bf16 v[134:137], v[142:145], v[176:179], v[134:137]
	v_mfma_f32_16x16x32_bf16 v[126:129], v[102:105], v[192:195], v[126:129]
	v_mfma_f32_16x16x32_bf16 v[122:125], v[142:145], v[192:195], v[122:125]
	v_mfma_f32_16x16x32_bf16 v[118:121], v[102:105], v[200:203], v[118:121]
	v_mfma_f32_16x16x32_bf16 v[114:117], v[142:145], v[200:203], v[114:117]
	v_mfma_f32_16x16x32_bf16 v[110:113], v[102:105], v[214:217], v[110:113]
	v_mfma_f32_16x16x32_bf16 v[106:109], v[142:145], v[214:217], v[106:109]
	s_setprio 0
	s_setprio 1
	v_mfma_f32_16x16x32_bf16 v[62:65], v[146:149], v[172:175], v[62:65]
	v_mfma_f32_16x16x32_bf16 v[58:61], v[164:167], v[172:175], v[58:61]
	v_mfma_f32_16x16x32_bf16 v[54:57], v[146:149], v[188:191], v[54:57]
	v_mfma_f32_16x16x32_bf16 v[50:53], v[164:167], v[188:191], v[50:53]
	v_mfma_f32_16x16x32_bf16 v[46:49], v[146:149], v[196:199], v[46:49]
	v_mfma_f32_16x16x32_bf16 v[42:45], v[164:167], v[196:199], v[42:45]
	v_mfma_f32_16x16x32_bf16 v[38:41], v[146:149], v[204:207], v[38:41]
	v_mfma_f32_16x16x32_bf16 v[34:37], v[164:167], v[204:207], v[34:37]
	v_mfma_f32_16x16x32_bf16 v[62:65], v[160:163], v[176:179], v[62:65]
	v_mfma_f32_16x16x32_bf16 v[58:61], v[168:171], v[176:179], v[58:61]
	v_mfma_f32_16x16x32_bf16 v[54:57], v[160:163], v[192:195], v[54:57]
	v_mfma_f32_16x16x32_bf16 v[50:53], v[168:171], v[192:195], v[50:53]
	v_mfma_f32_16x16x32_bf16 v[46:49], v[160:163], v[200:203], v[46:49]
	v_mfma_f32_16x16x32_bf16 v[42:45], v[168:171], v[200:203], v[42:45]
	v_mfma_f32_16x16x32_bf16 v[38:41], v[160:163], v[214:217], v[38:41]
	v_mfma_f32_16x16x32_bf16 v[34:37], v[168:171], v[214:217], v[34:37]
	s_barrier
	s_setprio 0
	s_mov_b32 m0, s35
	v_lshl_add_u64 v[180:181], s[84:85], 0, v[0:1]
	s_add_u32 s26, s84, 0x40000
	ds_read_b128 v[172:175], v186 offset:16384
	ds_read_b128 v[176:179], v186 offset:17408
	ds_read_b128 v[188:191], v186 offset:18432
	ds_read_b128 v[192:195], v186 offset:19456
	ds_read_b128 v[196:199], v186 offset:20480
	ds_read_b128 v[200:203], v186 offset:21504
	ds_read_b128 v[204:207], v186 offset:22528
	ds_read_b128 v[214:217], v186 offset:23552
	global_load_lds_dwordx4 v[180:181], off
	v_lshl_add_u64 v[182:183], s[84:85], 0, v[150:151]
	s_mov_b32 m0, s88
	s_addc_u32 s27, s85, 0
	global_load_lds_dwordx4 v[182:183], off
	v_lshl_add_u64 v[184:185], s[26:27], 0, v[0:1]
	s_mov_b32 m0, s89
	v_lshl_add_u64 v[218:219], s[86:87], 0, v[152:153]
	global_load_lds_dwordx4 v[184:185], off
	v_lshl_add_u64 v[184:185], s[26:27], 0, v[150:151]
	s_mov_b32 m0, s90
	s_nop 0
	global_load_lds_dwordx4 v[184:185], off
	v_lshl_add_u64 v[184:185], s[86:87], 0, v[154:155]
	s_mov_b32 m0, s6
	s_nop 0
	global_load_lds_dwordx4 v[184:185], off
	s_mov_b32 m0, s91
	s_nop 0
	global_load_lds_dwordx4 v[218:219], off
	s_waitcnt vmcnt(8)
	s_waitcnt lgkmcnt(0)
	s_barrier
; #define PG8_STAGE(bufoff, gbase, voff) do { _Pragma("unroll") for (int _i = 0; _i < 2; ++_i) \
;         __builtin_amdgcn_global_load_lds((const unsigned*)((const char*)(gbase) + (voff)[_i]), (PG8_LAS unsigned*)(lds + (bufoff) + ldsw + _i * 8192), 16, 0, 0); } while (0)
; #define PG8_LDA(dst, b, h) do { _Pragma("unroll") for (int m = 0; m < 4; ++m) _Pragma("unroll") for (int k = 0; k < 2; ++k) dst[m][k] = *(const PG8_LAS bf16x8*)(lds + PG8_SA(b, h) + aoff + m * 2048 + k * 1024); } while (0)
; #define PG8_LDB(dst, b, h) do { _Pragma("unroll") for (int n = 0; n < 2; ++n) _Pragma("unroll") for (int k = 0; k < 2; ++k) dst[n][k] = *(const PG8_LAS bf16x8*)(lds + PG8_SB(b, h) + boff + n * 2048 + k * 1024); } while (0)
; #define PG8_MMA(ai, bj, At, Bt) do { __builtin_amdgcn_s_setprio(1); _Pragma("unroll") for (int m = 0; m < 4; ++m) _Pragma("unroll") for (int n = 0; n < 2; ++n) _Pragma("unroll") for (int k = 0; k < 2; ++k) \
;         acc[ai][bj][m][n] = __builtin_amdgcn_mfma_f32_16x16x32_bf16(Bt[n][k], At[m][k], acc[ai][bj][m][n], 0, 0, 0); __builtin_amdgcn_s_setprio(0); } while (0)
; #define PG8_BAR __builtin_amdgcn_s_barrier()
; template <class Epi, class Sched, bool ALIGN_EPI = false, bool SP2 = false>
; __device__ __forceinline__ void gemm_phase(PG8_LAS unsigned char* lds, const Gemm g, const Sched& S, const Epi& E, const int tid) {
;     ...
;             PG8_LDB(B0, 0, 0); PG8_LDB(B1, 0, 1); PG8_SCHED; PG8_LDA(At, 0, 0); PG8_STAGE(PG8_SA(1, 1), a1 + hstep, voffA);
;             PG8_WAIT_V(8); PG8_WAIT_L(0); PG8_BAR; PG8_MMA(0, 0, At, B0); PG8_MMA(0, 1, At, B1); PG8_BAR; PG8_SCHED;
;             PG8_LDA(At, 0, 1); PG8_STAGE(PG8_SB(0, 0), b2, voffB); PG8_STAGE(PG8_SB(0, 1), b2 + hstep, voffB); PG8_STAGE(PG8_SA(0, 0), a2, voffA);
;             PG8_WAIT_V(8); PG8_WAIT_L(0); PG8_BAR; PG8_MMA(1, 0, At, B0); PG8_MMA(1, 1, At, B1); PG8_BAR; PG8_SCHED;
;             PG8_LDB(B0, 1, 0); PG8_LDB(B1, 1, 1); PG8_SCHED; PG8_LDA(At, 1, 0); PG8_STAGE(PG8_SA(0, 1), a2 + hstep, voffA);
;             PG8_WAIT_V(8); PG8_WAIT_L(0); PG8_BAR; PG8_MMA(0, 0, At, B0); PG8_MMA(0, 1, At, B1); PG8_BAR; PG8_SCHED;
;             PG8_LDA(At, 1, 1); PG8_STAGE(PG8_SB(1, 0), b3, voffB); PG8_STAGE(PG8_SB(1, 1), b3 + hstep, voffB); PG8_STAGE(PG8_SA(1, 0), a3, voffA);
;             PG8_WAIT_V(8); PG8_WAIT_L(0); PG8_BAR; PG8_MMA(1, 0, At, B0); PG8_MMA(1, 1, At, B1); PG8_BAR; PG8_SCHED;
	s_setprio 1
	s_waitcnt lgkmcnt(0)
	v_mfma_f32_16x16x32_bf16 v[94:97], v[98:101], v[172:175], v[94:97]
	v_mfma_f32_16x16x32_bf16 v[90:93], v[130:133], v[172:175], v[90:93]
	v_mfma_f32_16x16x32_bf16 v[86:89], v[98:101], v[188:191], v[86:89]
	v_mfma_f32_16x16x32_bf16 v[82:85], v[130:133], v[188:191], v[82:85]
	v_mfma_f32_16x16x32_bf16 v[78:81], v[98:101], v[196:199], v[78:81]
	v_mfma_f32_16x16x32_bf16 v[74:77], v[130:133], v[196:199], v[74:77]
	v_mfma_f32_16x16x32_bf16 v[70:73], v[98:101], v[204:207], v[70:73]
	v_mfma_f32_16x16x32_bf16 v[66:69], v[130:133], v[204:207], v[66:69]
	v_mfma_f32_16x16x32_bf16 v[94:97], v[102:105], v[176:179], v[94:97]
	v_mfma_f32_16x16x32_bf16 v[90:93], v[142:145], v[176:179], v[90:93]
	v_mfma_f32_16x16x32_bf16 v[86:89], v[102:105], v[192:195], v[86:89]
	v_mfma_f32_16x16x32_bf16 v[82:85], v[142:145], v[192:195], v[82:85]
	v_mfma_f32_16x16x32_bf16 v[78:81], v[102:105], v[200:203], v[78:81]
	v_mfma_f32_16x16x32_bf16 v[74:77], v[142:145], v[200:203], v[74:77]
	v_mfma_f32_16x16x32_bf16 v[70:73], v[102:105], v[214:217], v[70:73]
	v_mfma_f32_16x16x32_bf16 v[66:69], v[142:145], v[214:217], v[66:69]
	s_setprio 0
	s_setprio 1
	v_mfma_f32_16x16x32_bf16 v[30:33], v[146:149], v[172:175], v[30:33]
	v_mfma_f32_16x16x32_bf16 v[26:29], v[164:167], v[172:175], v[26:29]
	v_mfma_f32_16x16x32_bf16 v[22:25], v[146:149], v[188:191], v[22:25]
	v_mfma_f32_16x16x32_bf16 v[18:21], v[164:167], v[188:191], v[18:21]
	v_mfma_f32_16x16x32_bf16 v[14:17], v[146:149], v[196:199], v[14:17]
	v_mfma_f32_16x16x32_bf16 v[10:13], v[164:167], v[196:199], v[10:13]
	v_mfma_f32_16x16x32_bf16 v[6:9], v[146:149], v[204:207], v[6:9]
	v_mfma_f32_16x16x32_bf16 v[2:5], v[164:167], v[204:207], v[2:5]
	v_mfma_f32_16x16x32_bf16 v[30:33], v[160:163], v[176:179], v[30:33]
	v_mfma_f32_16x16x32_bf16 v[26:29], v[168:171], v[176:179], v[26:29]
	v_mfma_f32_16x16x32_bf16 v[22:25], v[160:163], v[192:195], v[22:25]
	v_mfma_f32_16x16x32_bf16 v[18:21], v[168:171], v[192:195], v[18:21]
	v_mfma_f32_16x16x32_bf16 v[14:17], v[160:163], v[200:203], v[14:17]
	v_mfma_f32_16x16x32_bf16 v[10:13], v[168:171], v[200:203], v[10:13]
	v_mfma_f32_16x16x32_bf16 v[6:9], v[160:163], v[214:217], v[6:9]
	v_mfma_f32_16x16x32_bf16 v[2:5], v[168:171], v[214:217], v[2:5]
	s_barrier
	s_setprio 0
	v_or_b32_e32 v98, 0x18000, v187
	v_add_u32_e32 v102, 0x18400, v187
	v_add_u32_e32 v130, 0x18800, v187
	v_add_u32_e32 v142, 0x18c00, v187
	v_or_b32_e32 v146, 0x1c000, v187
	v_add_u32_e32 v160, 0x1c400, v187
	v_add_u32_e32 v164, 0x1c800, v187
	v_add_u32_e32 v168, 0x1cc00, v187
	ds_read_b128 v[98:101], v98
	ds_read_b128 v[102:105], v102
	ds_read_b128 v[130:133], v130
	ds_read_b128 v[142:145], v142
	ds_read_b128 v[146:149], v146
	ds_read_b128 v[160:163], v160
	ds_read_b128 v[164:167], v164
	ds_read_b128 v[168:171], v168
	s_add_u32 s26, s86, 0x40000
	s_addc_u32 s27, s87, 0
	s_mov_b32 m0, s42
	v_lshl_add_u64 v[220:221], s[26:27], 0, v[154:155]
	ds_read_b128 v[172:175], v186 offset:32768
	ds_read_b128 v[176:179], v186 offset:33792
	ds_read_b128 v[188:191], v186 offset:34816
	ds_read_b128 v[192:195], v186 offset:35840
	ds_read_b128 v[196:199], v186 offset:36864
	ds_read_b128 v[200:203], v186 offset:37888
	ds_read_b128 v[204:207], v186 offset:38912
	ds_read_b128 v[214:217], v186 offset:39936
	global_load_lds_dwordx4 v[220:221], off
	v_lshl_add_u64 v[220:221], s[26:27], 0, v[152:153]
	s_mov_b32 m0, s43
	s_nop 0
	global_load_lds_dwordx4 v[220:221], off
	s_waitcnt vmcnt(8)
	s_waitcnt lgkmcnt(0)
	s_barrier
	s_setprio 1
	s_waitcnt lgkmcnt(0)
	v_mfma_f32_16x16x32_bf16 v[138:141], v[98:101], v[172:175], v[138:141]
	v_mfma_f32_16x16x32_bf16 v[134:137], v[130:133], v[172:175], v[134:137]
	v_mfma_f32_16x16x32_bf16 v[126:129], v[98:101], v[188:191], v[126:129]
	v_mfma_f32_16x16x32_bf16 v[122:125], v[130:133], v[188:191], v[122:125]
	v_mfma_f32_16x16x32_bf16 v[118:121], v[98:101], v[196:199], v[118:121]
	v_mfma_f32_16x16x32_bf16 v[114:117], v[130:133], v[196:199], v[114:117]
	v_mfma_f32_16x16x32_bf16 v[110:113], v[98:101], v[204:207], v[110:113]
	v_mfma_f32_16x16x32_bf16 v[106:109], v[130:133], v[204:207], v[106:109]
	v_mfma_f32_16x16x32_bf16 v[138:141], v[102:105], v[176:179], v[138:141]
	v_mfma_f32_16x16x32_bf16 v[134:137], v[142:145], v[176:179], v[134:137]
	v_mfma_f32_16x16x32_bf16 v[126:129], v[102:105], v[192:195], v[126:129]
	v_mfma_f32_16x16x32_bf16 v[122:125], v[142:145], v[192:195], v[122:125]
	v_mfma_f32_16x16x32_bf16 v[118:121], v[102:105], v[200:203], v[118:121]
	v_mfma_f32_16x16x32_bf16 v[114:117], v[142:145], v[200:203], v[114:117]
	v_mfma_f32_16x16x32_bf16 v[110:113], v[102:105], v[214:217], v[110:113]
	v_mfma_f32_16x16x32_bf16 v[106:109], v[142:145], v[214:217], v[106:109]
	s_setprio 0
	s_setprio 1
	v_mfma_f32_16x16x32_bf16 v[62:65], v[146:149], v[172:175], v[62:65]
	v_mfma_f32_16x16x32_bf16 v[58:61], v[164:167], v[172:175], v[58:61]
	v_mfma_f32_16x16x32_bf16 v[54:57], v[146:149], v[188:191], v[54:57]
	v_mfma_f32_16x16x32_bf16 v[50:53], v[164:167], v[188:191], v[50:53]
	v_mfma_f32_16x16x32_bf16 v[46:49], v[146:149], v[196:199], v[46:49]
	v_mfma_f32_16x16x32_bf16 v[42:45], v[164:167], v[196:199], v[42:45]
	v_mfma_f32_16x16x32_bf16 v[38:41], v[146:149], v[204:207], v[38:41]
	v_mfma_f32_16x16x32_bf16 v[34:37], v[164:167], v[204:207], v[34:37]
	v_mfma_f32_16x16x32_bf16 v[62:65], v[160:163], v[176:179], v[62:65]
	v_mfma_f32_16x16x32_bf16 v[58:61], v[168:171], v[176:179], v[58:61]
	v_mfma_f32_16x16x32_bf16 v[54:57], v[160:163], v[192:195], v[54:57]
	v_mfma_f32_16x16x32_bf16 v[50:53], v[168:171], v[192:195], v[50:53]
	v_mfma_f32_16x16x32_bf16 v[46:49], v[160:163], v[200:203], v[46:49]
	v_mfma_f32_16x16x32_bf16 v[42:45], v[168:171], v[200:203], v[42:45]
	v_mfma_f32_16x16x32_bf16 v[38:41], v[160:163], v[214:217], v[38:41]
	v_mfma_f32_16x16x32_bf16 v[34:37], v[168:171], v[214:217], v[34:37]
	s_barrier
; #define PG8_STAGE(bufoff, gbase, voff) do { _Pragma("unroll") for (int _i = 0; _i < 2; ++_i) \
;         __builtin_amdgcn_global_load_lds((const unsigned*)((const char*)(gbase) + (voff)[_i]), (PG8_LAS unsigned*)(lds + (bufoff) + ldsw + _i * 8192), 16, 0, 0); } while (0)
; #define PG8_LDA(dst, b, h) do { _Pragma("unroll") for (int m = 0; m < 4; ++m) _Pragma("unroll") for (int k = 0; k < 2; ++k) dst[m][k] = *(const PG8_LAS bf16x8*)(lds + PG8_SA(b, h) + aoff + m * 2048 + k * 1024); } while (0)
; #define PG8_LDB(dst, b, h) do { _Pragma("unroll") for (int n = 0; n < 2; ++n) _Pragma("unroll") for (int k = 0; k < 2; ++k) dst[n][k] = *(const PG8_LAS bf16x8*)(lds + PG8_SB(b, h) + boff + n * 2048 + k * 1024); } while (0)
; #define PG8_MMA(ai, bj, At, Bt) do { __builtin_amdgcn_s_setprio(1); _Pragma("unroll") for (int m = 0; m < 4; ++m) _Pragma("unroll") for (int n = 0; n < 2; ++n) _Pragma("unroll") for (int k = 0; k < 2; ++k) \
;         acc[ai][bj][m][n] = __builtin_amdgcn_mfma_f32_16x16x32_bf16(Bt[n][k], At[m][k], acc[ai][bj][m][n], 0, 0, 0); __builtin_amdgcn_s_setprio(0); } while (0)
; #define PG8_BAR __builtin_amdgcn_s_barrier()
; template <class Epi, class Sched, bool ALIGN_EPI = false, bool SP2 = false>
; __device__ __forceinline__ void gemm_phase(PG8_LAS unsigned char* lds, const Gemm g, const Sched& S, const Epi& E, const int tid) {
;     ...
;             PG8_LDB(B0, 0, 0); PG8_LDB(B1, 0, 1); PG8_SCHED; PG8_LDA(At, 0, 0); PG8_STAGE(PG8_SA(1, 1), a1 + hstep, voffA);
;             PG8_WAIT_V(8); PG8_WAIT_L(0); PG8_BAR; PG8_MMA(0, 0, At, B0); PG8_MMA(0, 1, At, B1); PG8_BAR; PG8_SCHED;
;             PG8_LDA(At, 0, 1); PG8_STAGE(PG8_SB(0, 0), b2, voffB); PG8_STAGE(PG8_SB(0, 1), b2 + hstep, voffB); PG8_STAGE(PG8_SA(0, 0), a2, voffA);
;             PG8_WAIT_V(8); PG8_WAIT_L(0); PG8_BAR; PG8_MMA(1, 0, At, B0); PG8_MMA(1, 1, At, B1); PG8_BAR; PG8_SCHED;
;             PG8_LDB(B0, 1, 0); PG8_LDB(B1, 1, 1); PG8_SCHED; PG8_LDA(At, 1, 0); PG8_STAGE(PG8_SA(0, 1), a2 + hstep, voffA);
;             PG8_WAIT_V(8); PG8_WAIT_L(0); PG8_BAR; PG8_MMA(0, 0, At, B0); PG8_MMA(0, 1, At, B1); PG8_BAR; PG8_SCHED;
;             PG8_LDA(At, 1, 1); PG8_STAGE(PG8_SB(1, 0), b3, voffB); PG8_STAGE(PG8_SB(1, 1), b3 + hstep, voffB); PG8_STAGE(PG8_SA(1, 0), a3, voffA);
;             PG8_WAIT_V(8); PG8_WAIT_L(0); PG8_BAR; PG8_MMA(1, 0, At, B0); PG8_MMA(1, 1, At, B1); PG8_BAR; PG8_SCHED;
	s_setprio 0
	s_mov_b32 m0, s40
	v_lshl_add_u64 v[180:181], v[180:181], 0, s[12:13]
	s_add_u32 s26, s84, 0x40080
	ds_read_b128 v[172:175], v186 offset:49152
	ds_read_b128 v[176:179], v186 offset:50176
	ds_read_b128 v[188:191], v186 offset:51200
	ds_read_b128 v[192:195], v186 offset:52224
	ds_read_b128 v[196:199], v186 offset:53248
	ds_read_b128 v[200:203], v186 offset:54272
	ds_read_b128 v[204:207], v186 offset:55296
	ds_read_b128 v[214:217], v186 offset:56320
	global_load_lds_dwordx4 v[180:181], off
	v_lshl_add_u64 v[180:181], v[182:183], 0, s[12:13]
	s_mov_b32 m0, s41
	s_addc_u32 s27, s85, 0
	global_load_lds_dwordx4 v[180:181], off
	v_lshl_add_u64 v[180:181], s[26:27], 0, v[0:1]
	s_mov_b32 m0, s34
	s_nop 0
	global_load_lds_dwordx4 v[180:181], off
	v_lshl_add_u64 v[180:181], s[26:27], 0, v[150:151]
	s_mov_b32 m0, s8
	s_nop 0
	global_load_lds_dwordx4 v[180:181], off
	v_lshl_add_u64 v[180:181], v[184:185], 0, s[12:13]
	s_mov_b32 m0, s1
	s_nop 0
	global_load_lds_dwordx4 v[180:181], off
	v_lshl_add_u64 v[180:181], v[218:219], 0, s[12:13]
	s_mov_b32 m0, s14
	s_nop 0
	global_load_lds_dwordx4 v[180:181], off
	s_waitcnt vmcnt(8)
	s_waitcnt lgkmcnt(0)
	s_barrier
	s_setprio 1
	s_waitcnt lgkmcnt(0)
	v_mfma_f32_16x16x32_bf16 v[94:97], v[98:101], v[172:175], v[94:97]
	v_mfma_f32_16x16x32_bf16 v[90:93], v[130:133], v[172:175], v[90:93]
	v_mfma_f32_16x16x32_bf16 v[86:89], v[98:101], v[188:191], v[86:89]
	v_mfma_f32_16x16x32_bf16 v[82:85], v[130:133], v[188:191], v[82:85]
	v_mfma_f32_16x16x32_bf16 v[78:81], v[98:101], v[196:199], v[78:81]
	v_mfma_f32_16x16x32_bf16 v[74:77], v[130:133], v[196:199], v[74:77]
	v_mfma_f32_16x16x32_bf16 v[70:73], v[98:101], v[204:207], v[70:73]
	v_mfma_f32_16x16x32_bf16 v[66:69], v[130:133], v[204:207], v[66:69]
	v_mfma_f32_16x16x32_bf16 v[94:97], v[102:105], v[176:179], v[94:97]
	v_mfma_f32_16x16x32_bf16 v[90:93], v[142:145], v[176:179], v[90:93]
	v_mfma_f32_16x16x32_bf16 v[86:89], v[102:105], v[192:195], v[86:89]
	v_mfma_f32_16x16x32_bf16 v[82:85], v[142:145], v[192:195], v[82:85]
	v_mfma_f32_16x16x32_bf16 v[78:81], v[102:105], v[200:203], v[78:81]
	v_mfma_f32_16x16x32_bf16 v[74:77], v[142:145], v[200:203], v[74:77]
	v_mfma_f32_16x16x32_bf16 v[70:73], v[102:105], v[214:217], v[70:73]
	v_mfma_f32_16x16x32_bf16 v[66:69], v[142:145], v[214:217], v[66:69]
	s_setprio 0
	s_setprio 1
	v_mfma_f32_16x16x32_bf16 v[30:33], v[146:149], v[172:175], v[30:33]
	v_mfma_f32_16x16x32_bf16 v[26:29], v[164:167], v[172:175], v[26:29]
	v_mfma_f32_16x16x32_bf16 v[22:25], v[146:149], v[188:191], v[22:25]
	v_mfma_f32_16x16x32_bf16 v[18:21], v[164:167], v[188:191], v[18:21]
	v_mfma_f32_16x16x32_bf16 v[14:17], v[146:149], v[196:199], v[14:17]
	v_mfma_f32_16x16x32_bf16 v[10:13], v[164:167], v[196:199], v[10:13]
	v_mfma_f32_16x16x32_bf16 v[6:9], v[146:149], v[204:207], v[6:9]
	v_mfma_f32_16x16x32_bf16 v[2:5], v[164:167], v[204:207], v[2:5]
	v_mfma_f32_16x16x32_bf16 v[30:33], v[160:163], v[176:179], v[30:33]
	v_mfma_f32_16x16x32_bf16 v[26:29], v[168:171], v[176:179], v[26:29]
	v_mfma_f32_16x16x32_bf16 v[22:25], v[160:163], v[192:195], v[22:25]
	v_mfma_f32_16x16x32_bf16 v[18:21], v[168:171], v[192:195], v[18:21]
	v_mfma_f32_16x16x32_bf16 v[14:17], v[160:163], v[200:203], v[14:17]
	v_mfma_f32_16x16x32_bf16 v[10:13], v[168:171], v[200:203], v[10:13]
	v_mfma_f32_16x16x32_bf16 v[6:9], v[160:163], v[214:217], v[6:9]
	v_mfma_f32_16x16x32_bf16 v[2:5], v[168:171], v[214:217], v[2:5]
	s_barrier
	s_setprio 0
	s_add_i32 s24, s24, 2
	s_add_u32 s30, s30, 0x100
	s_addc_u32 s31, s31, 0
	s_add_u32 s20, s20, 0x100
	s_addc_u32 s21, s21, 0
	s_cmp_gt_u32 s24, 13
	s_cbranch_scc0 .LBB0_355
	v_readlane_b32 s4, v255, 54
	v_readlane_b32 s5, v255, 55
	s_and_b64 vcc, exec, s[4:5]
	s_cbranch_vccz .LBB0_358
	s_barrier

; #define PG8_STAGE(bufoff, gbase, voff) do { _Pragma("unroll") for (int _i = 0; _i < 2; ++_i) \
;         __builtin_amdgcn_global_load_lds((const unsigned*)((const char*)(gbase) + (voff)[_i]), (PG8_LAS unsigned*)(lds + (bufoff) + ldsw + _i * 8192), 16, 0, 0); } while (0)
; #define PG8_LDA(dst, b, h) do { _Pragma("unroll") for (int m = 0; m < 4; ++m) _Pragma("unroll") for (int k = 0; k < 2; ++k) dst[m][k] = *(const PG8_LAS bf16x8*)(lds + PG8_SA(b, h) + aoff + m * 2048 + k * 1024); } while (0)
; #define PG8_LDB(dst, b, h) do { _Pragma("unroll") for (int n = 0; n < 2; ++n) _Pragma("unroll") for (int k = 0; k < 2; ++k) dst[n][k] = *(const PG8_LAS bf16x8*)(lds + PG8_SB(b, h) + boff + n * 2048 + k * 1024); } while (0)
; #define PG8_MMA(ai, bj, At, Bt) do { __builtin_amdgcn_s_setprio(1); _Pragma("unroll") for (int m = 0; m < 4; ++m) _Pragma("unroll") for (int n = 0; n < 2; ++n) _Pragma("unroll") for (int k = 0; k < 2; ++k) \
;         acc[ai][bj][m][n] = __builtin_amdgcn_mfma_f32_16x16x32_bf16(Bt[n][k], At[m][k], acc[ai][bj][m][n], 0, 0, 0); __builtin_amdgcn_s_setprio(0); } while (0)
; #define PG8_BAR __builtin_amdgcn_s_barrier()
; template <class Epi, class Sched, bool ALIGN_EPI = false, bool SP2 = false>
; __device__ __forceinline__ void gemm_phase(PG8_LAS unsigned char* lds, const Gemm g, const Sched& S, const Epi& E, const int tid) {
;     ...
;             PG8_LDB(B0, 0, 0); PG8_LDB(B1, 0, 1); PG8_SCHED; PG8_LDA(At, 0, 0); PG8_STAGE(PG8_SA(1, 1), a1 + hstep, voffA);
;             PG8_WAIT_V(8); PG8_WAIT_L(0); PG8_BAR; PG8_MMA(0, 0, At, B0); PG8_MMA(0, 1, At, B1); PG8_BAR; PG8_SCHED;
;             PG8_LDA(At, 0, 1); PG8_STAGE(PG8_SB(0, 0), b2, voffB); PG8_STAGE(PG8_SB(0, 1), b2 + hstep, voffB); PG8_STAGE(PG8_SA(0, 0), a2, voffA);
;             PG8_WAIT_V(8); PG8_WAIT_L(0); PG8_BAR; PG8_MMA(1, 0, At, B0); PG8_MMA(1, 1, At, B1); PG8_BAR; PG8_SCHED;
;             PG8_LDB(B0, 1, 0); PG8_LDB(B1, 1, 1); PG8_SCHED; PG8_LDA(At, 1, 0); PG8_STAGE(PG8_SA(0, 1), a2 + hstep, voffA);
;             PG8_WAIT_V(8); PG8_WAIT_L(0); PG8_BAR; PG8_MMA(0, 0, At, B0); PG8_MMA(0, 1, At, B1); PG8_BAR; PG8_SCHED;
;             PG8_LDA(At, 1, 1); PG8_STAGE(PG8_SB(1, 0), b3, voffB); PG8_STAGE(PG8_SB(1, 1), b3 + hstep, voffB); PG8_STAGE(PG8_SA(1, 0), a3, voffA);
;             PG8_WAIT_V(8); PG8_WAIT_L(0); PG8_BAR; PG8_MMA(1, 0, At, B0); PG8_MMA(1, 1, At, B1); PG8_BAR; PG8_SCHED;
.LBB0_370:
	s_ashr_i32 s43, s42, 31
	s_lshl_b64 s[44:45], s[42:43], 17
	v_readlane_b32 s41, v253, 63
	s_add_u32 s44, s41, s44
	v_readlane_b32 s41, v254, 0
	s_addc_u32 s45, s41, s45
	s_and_b64 s[46:47], s[36:37], exec
	v_or_b32_e32 v208, 0x10000, v139
	v_add_u32_e32 v210, 0x10800, v139
	v_or_b32_e32 v212, 0x14000, v139
	v_add_u32_e32 v218, 0x14800, v139
	s_cselect_b32 s87, s45, s89
	s_cselect_b32 s86, s44, s88
	s_ashr_i32 s41, s40, 31
	v_add_u32_e32 v209, 0x10400, v139
	ds_read_b128 v[2:5], v208
	ds_read_b128 v[6:9], v209
	v_add_u32_e32 v211, 0x10c00, v139
	ds_read_b128 v[10:13], v210
	ds_read_b128 v[14:17], v211
	v_add_u32_e32 v213, 0x14400, v139
	ds_read_b128 v[18:21], v212
	ds_read_b128 v[22:25], v213
	v_add_u32_e32 v219, 0x14c00, v139
	ds_read_b128 v[26:29], v218
	ds_read_b128 v[30:33], v219
	s_lshl_b64 s[46:47], s[40:41], 17
	v_readlane_b32 s50, v253, 59
	v_readlane_b32 s51, v253, 60
	s_add_u32 s46, s50, s46
	s_addc_u32 s47, s51, s47
	s_and_b64 s[50:51], s[36:37], exec
	s_cselect_b32 s85, s47, s91
	s_cselect_b32 s84, s46, s90
	s_add_u32 s50, s88, 0x10080
	s_addc_u32 s51, s89, 0
	s_add_i32 s43, s0, 0xc000
	v_lshl_add_u64 v[66:67], s[50:51], 0, v[134:135]
	s_mov_b32 m0, s43
	s_add_i32 s41, s0, 0xe000
	ds_read_b128 v[34:37], v138
	ds_read_b128 v[38:41], v138 offset:1024
	ds_read_b128 v[42:45], v138 offset:2048
	ds_read_b128 v[46:49], v138 offset:3072
	ds_read_b128 v[50:53], v138 offset:4096
	ds_read_b128 v[54:57], v138 offset:5120
	ds_read_b128 v[58:61], v138 offset:6144
	ds_read_b128 v[62:65], v138 offset:7168
	global_load_lds_dwordx4 v[66:67], off
	v_lshl_add_u64 v[66:67], s[50:51], 0, v[132:133]
	s_mov_b32 m0, s41
	s_nop 0
	global_load_lds_dwordx4 v[66:67], off
	s_waitcnt vmcnt(8)
	s_waitcnt lgkmcnt(0)
	s_barrier
	s_setprio 1
	s_waitcnt lgkmcnt(0)
	v_mfma_f32_16x16x32_bf16 v[66:69], v[2:5], v[34:37], 0
	v_mfma_f32_16x16x32_bf16 v[70:73], v[10:13], v[34:37], 0
	v_mfma_f32_16x16x32_bf16 v[74:77], v[2:5], v[42:45], 0
	v_mfma_f32_16x16x32_bf16 v[78:81], v[10:13], v[42:45], 0
	v_mfma_f32_16x16x32_bf16 v[82:85], v[2:5], v[50:53], 0
	v_mfma_f32_16x16x32_bf16 v[86:89], v[10:13], v[50:53], 0
	v_mfma_f32_16x16x32_bf16 v[90:93], v[2:5], v[58:61], 0
	v_mfma_f32_16x16x32_bf16 v[94:97], v[10:13], v[58:61], 0
	v_mfma_f32_16x16x32_bf16 v[66:69], v[6:9], v[38:41], v[66:69]
	v_mfma_f32_16x16x32_bf16 v[70:73], v[14:17], v[38:41], v[70:73]
	v_mfma_f32_16x16x32_bf16 v[74:77], v[6:9], v[46:49], v[74:77]
	v_mfma_f32_16x16x32_bf16 v[78:81], v[14:17], v[46:49], v[78:81]
	v_mfma_f32_16x16x32_bf16 v[82:85], v[6:9], v[54:57], v[82:85]
	v_mfma_f32_16x16x32_bf16 v[86:89], v[14:17], v[54:57], v[86:89]
	v_mfma_f32_16x16x32_bf16 v[90:93], v[6:9], v[62:65], v[90:93]
	v_mfma_f32_16x16x32_bf16 v[94:97], v[14:17], v[62:65], v[94:97]
	s_setprio 0
	s_setprio 1
	v_mfma_f32_16x16x32_bf16 v[98:101], v[18:21], v[34:37], 0
	v_mfma_f32_16x16x32_bf16 v[34:37], v[26:29], v[34:37], 0
	v_mfma_f32_16x16x32_bf16 v[98:101], v[22:25], v[38:41], v[98:101]
	v_mfma_f32_16x16x32_bf16 v[34:37], v[30:33], v[38:41], v[34:37]
	v_mfma_f32_16x16x32_bf16 v[38:41], v[18:21], v[42:45], 0
	v_mfma_f32_16x16x32_bf16 v[42:45], v[26:29], v[42:45], 0
	v_mfma_f32_16x16x32_bf16 v[38:41], v[22:25], v[46:49], v[38:41]
	v_mfma_f32_16x16x32_bf16 v[42:45], v[30:33], v[46:49], v[42:45]
	v_mfma_f32_16x16x32_bf16 v[46:49], v[18:21], v[50:53], 0
	v_mfma_f32_16x16x32_bf16 v[50:53], v[26:29], v[50:53], 0
	v_mfma_f32_16x16x32_bf16 v[46:49], v[22:25], v[54:57], v[46:49]
	v_mfma_f32_16x16x32_bf16 v[50:53], v[30:33], v[54:57], v[50:53]
	v_mfma_f32_16x16x32_bf16 v[54:57], v[18:21], v[58:61], 0
	v_mfma_f32_16x16x32_bf16 v[58:61], v[26:29], v[58:61], 0
	v_mfma_f32_16x16x32_bf16 v[54:57], v[22:25], v[62:65], v[54:57]
	v_mfma_f32_16x16x32_bf16 v[58:61], v[30:33], v[62:65], v[58:61]
	s_barrier
	s_setprio 0
	v_lshl_add_u64 v[136:137], s[90:91], 0, v[0:1]
	s_mov_b64 s[92:93], 0x100
	s_mov_b32 m0, s1
	v_lshl_add_u64 v[140:141], v[136:137], 0, s[92:93]
	v_lshl_add_u64 v[180:181], s[90:91], 0, v[130:131]
	s_add_u32 s50, s90, 0x10100
	ds_read_b128 v[62:65], v138 offset:16384
	ds_read_b128 v[102:105], v138 offset:17408
	ds_read_b128 v[106:109], v138 offset:18432
	ds_read_b128 v[110:113], v138 offset:19456
	ds_read_b128 v[114:117], v138 offset:20480
	ds_read_b128 v[118:121], v138 offset:21504
	ds_read_b128 v[122:125], v138 offset:22528
	ds_read_b128 v[126:129], v138 offset:23552
	global_load_lds_dwordx4 v[140:141], off
	v_lshl_add_u64 v[140:141], v[180:181], 0, s[92:93]
	s_mov_b32 m0, s2
	s_addc_u32 s51, s91, 0
	global_load_lds_dwordx4 v[140:141], off
	v_lshl_add_u64 v[140:141], s[50:51], 0, v[0:1]
	s_mov_b32 m0, s4
	v_lshl_add_u64 v[182:183], s[88:89], 0, v[134:135]
	global_load_lds_dwordx4 v[140:141], off
	v_lshl_add_u64 v[140:141], s[50:51], 0, v[130:131]
	s_mov_b32 m0, s5
	v_lshl_add_u64 v[214:215], s[88:89], 0, v[132:133]
	global_load_lds_dwordx4 v[140:141], off
	v_lshl_add_u64 v[140:141], v[182:183], 0, s[92:93]
	s_mov_b32 m0, s0
	s_nop 0
	global_load_lds_dwordx4 v[140:141], off
	v_lshl_add_u64 v[140:141], v[214:215], 0, s[92:93]
	s_mov_b32 m0, s6
	s_nop 0
	global_load_lds_dwordx4 v[140:141], off
	s_waitcnt vmcnt(8)
	s_waitcnt lgkmcnt(0)
	s_barrier
; #define PG8_STAGE(bufoff, gbase, voff) do { _Pragma("unroll") for (int _i = 0; _i < 2; ++_i) \
;         __builtin_amdgcn_global_load_lds((const unsigned*)((const char*)(gbase) + (voff)[_i]), (PG8_LAS unsigned*)(lds + (bufoff) + ldsw + _i * 8192), 16, 0, 0); } while (0)
; #define PG8_LDA(dst, b, h) do { _Pragma("unroll") for (int m = 0; m < 4; ++m) _Pragma("unroll") for (int k = 0; k < 2; ++k) dst[m][k] = *(const PG8_LAS bf16x8*)(lds + PG8_SA(b, h) + aoff + m * 2048 + k * 1024); } while (0)
; #define PG8_LDB(dst, b, h) do { _Pragma("unroll") for (int n = 0; n < 2; ++n) _Pragma("unroll") for (int k = 0; k < 2; ++k) dst[n][k] = *(const PG8_LAS bf16x8*)(lds + PG8_SB(b, h) + boff + n * 2048 + k * 1024); } while (0)
; #define PG8_MMA(ai, bj, At, Bt) do { __builtin_amdgcn_s_setprio(1); _Pragma("unroll") for (int m = 0; m < 4; ++m) _Pragma("unroll") for (int n = 0; n < 2; ++n) _Pragma("unroll") for (int k = 0; k < 2; ++k) \
;         acc[ai][bj][m][n] = __builtin_amdgcn_mfma_f32_16x16x32_bf16(Bt[n][k], At[m][k], acc[ai][bj][m][n], 0, 0, 0); __builtin_amdgcn_s_setprio(0); } while (0)
; #define PG8_BAR __builtin_amdgcn_s_barrier()
; template <class Epi, class Sched, bool ALIGN_EPI = false, bool SP2 = false>
; __device__ __forceinline__ void gemm_phase(PG8_LAS unsigned char* lds, const Gemm g, const Sched& S, const Epi& E, const int tid) {
;     ...
;             PG8_LDB(B0, 0, 0); PG8_LDB(B1, 0, 1); PG8_SCHED; PG8_LDA(At, 0, 0); PG8_STAGE(PG8_SA(1, 1), a1 + hstep, voffA);
;             PG8_WAIT_V(8); PG8_WAIT_L(0); PG8_BAR; PG8_MMA(0, 0, At, B0); PG8_MMA(0, 1, At, B1); PG8_BAR; PG8_SCHED;
;             PG8_LDA(At, 0, 1); PG8_STAGE(PG8_SB(0, 0), b2, voffB); PG8_STAGE(PG8_SB(0, 1), b2 + hstep, voffB); PG8_STAGE(PG8_SA(0, 0), a2, voffA);
;             PG8_WAIT_V(8); PG8_WAIT_L(0); PG8_BAR; PG8_MMA(1, 0, At, B0); PG8_MMA(1, 1, At, B1); PG8_BAR; PG8_SCHED;
;             PG8_LDB(B0, 1, 0); PG8_LDB(B1, 1, 1); PG8_SCHED; PG8_LDA(At, 1, 0); PG8_STAGE(PG8_SA(0, 1), a2 + hstep, voffA);
;             PG8_WAIT_V(8); PG8_WAIT_L(0); PG8_BAR; PG8_MMA(0, 0, At, B0); PG8_MMA(0, 1, At, B1); PG8_BAR; PG8_SCHED;
;             PG8_LDA(At, 1, 1); PG8_STAGE(PG8_SB(1, 0), b3, voffB); PG8_STAGE(PG8_SB(1, 1), b3 + hstep, voffB); PG8_STAGE(PG8_SA(1, 0), a3, voffA);
;             PG8_WAIT_V(8); PG8_WAIT_L(0); PG8_BAR; PG8_MMA(1, 0, At, B0); PG8_MMA(1, 1, At, B1); PG8_BAR; PG8_SCHED;
	s_setprio 1
	s_waitcnt lgkmcnt(0)
	v_mfma_f32_16x16x32_bf16 v[140:143], v[2:5], v[62:65], 0
	v_mfma_f32_16x16x32_bf16 v[148:151], v[2:5], v[106:109], 0
	v_mfma_f32_16x16x32_bf16 v[156:159], v[2:5], v[114:117], 0
	v_mfma_f32_16x16x32_bf16 v[2:5], v[2:5], v[122:125], 0
	v_mfma_f32_16x16x32_bf16 v[140:143], v[6:9], v[102:105], v[140:143]
	v_mfma_f32_16x16x32_bf16 v[148:151], v[6:9], v[110:113], v[148:151]
	v_mfma_f32_16x16x32_bf16 v[156:159], v[6:9], v[118:121], v[156:159]
	v_mfma_f32_16x16x32_bf16 v[2:5], v[6:9], v[126:129], v[2:5]
	v_mfma_f32_16x16x32_bf16 v[6:9], v[10:13], v[122:125], 0
	v_mfma_f32_16x16x32_bf16 v[144:147], v[10:13], v[62:65], 0
	v_mfma_f32_16x16x32_bf16 v[152:155], v[10:13], v[106:109], 0
	v_mfma_f32_16x16x32_bf16 v[160:163], v[10:13], v[114:117], 0
	v_mfma_f32_16x16x32_bf16 v[6:9], v[14:17], v[126:129], v[6:9]
	v_mfma_f32_16x16x32_bf16 v[144:147], v[14:17], v[102:105], v[144:147]
	v_mfma_f32_16x16x32_bf16 v[152:155], v[14:17], v[110:113], v[152:155]
	v_mfma_f32_16x16x32_bf16 v[160:163], v[14:17], v[118:121], v[160:163]
	s_setprio 0
	s_setprio 1
	v_mfma_f32_16x16x32_bf16 v[10:13], v[18:21], v[62:65], 0
	v_mfma_f32_16x16x32_bf16 v[14:17], v[26:29], v[62:65], 0
	v_mfma_f32_16x16x32_bf16 v[10:13], v[22:25], v[102:105], v[10:13]
	v_mfma_f32_16x16x32_bf16 v[14:17], v[30:33], v[102:105], v[14:17]
	v_mfma_f32_16x16x32_bf16 v[62:65], v[18:21], v[106:109], 0
	v_mfma_f32_16x16x32_bf16 v[102:105], v[26:29], v[106:109], 0
	v_mfma_f32_16x16x32_bf16 v[106:109], v[18:21], v[114:117], 0
	v_mfma_f32_16x16x32_bf16 v[18:21], v[18:21], v[122:125], 0
	v_mfma_f32_16x16x32_bf16 v[62:65], v[22:25], v[110:113], v[62:65]
	v_mfma_f32_16x16x32_bf16 v[102:105], v[30:33], v[110:113], v[102:105]
	v_mfma_f32_16x16x32_bf16 v[106:109], v[22:25], v[118:121], v[106:109]
	v_mfma_f32_16x16x32_bf16 v[110:113], v[26:29], v[114:117], 0
	v_mfma_f32_16x16x32_bf16 v[18:21], v[22:25], v[126:129], v[18:21]
	v_mfma_f32_16x16x32_bf16 v[22:25], v[26:29], v[122:125], 0
	v_mfma_f32_16x16x32_bf16 v[110:113], v[30:33], v[118:121], v[110:113]
	v_mfma_f32_16x16x32_bf16 v[22:25], v[30:33], v[126:129], v[22:25]
	s_barrier
	s_setprio 0
	v_or_b32_e32 v222, 0x18000, v139
	v_add_u32_e32 v224, 0x18800, v139
	v_or_b32_e32 v226, 0x1c000, v139
	v_add_u32_e32 v228, 0x1c800, v139
	v_add_u32_e32 v223, 0x18400, v139
	ds_read_b128 v[26:29], v222
	ds_read_b128 v[30:33], v223
	v_add_u32_e32 v225, 0x18c00, v139
	ds_read_b128 v[114:117], v224
	ds_read_b128 v[118:121], v225
	v_add_u32_e32 v227, 0x1c400, v139
	ds_read_b128 v[122:125], v226
	ds_read_b128 v[126:129], v227
	v_add_u32_e32 v230, 0x1cc00, v139
	ds_read_b128 v[164:167], v228
	ds_read_b128 v[168:171], v230
	s_add_u32 s50, s88, 0x10100
	s_addc_u32 s51, s89, 0
	s_mov_b32 m0, s8
	v_lshl_add_u64 v[216:217], s[50:51], 0, v[134:135]
	ds_read_b128 v[172:175], v138 offset:32768
	ds_read_b128 v[176:179], v138 offset:33792
	ds_read_b128 v[184:187], v138 offset:34816
	ds_read_b128 v[188:191], v138 offset:35840
	ds_read_b128 v[192:195], v138 offset:36864
	ds_read_b128 v[196:199], v138 offset:37888
	ds_read_b128 v[200:203], v138 offset:38912
	ds_read_b128 v[204:207], v138 offset:39936
	global_load_lds_dwordx4 v[216:217], off
	v_lshl_add_u64 v[216:217], s[50:51], 0, v[132:133]
	s_mov_b32 m0, s9
	s_nop 0
	global_load_lds_dwordx4 v[216:217], off
	s_waitcnt vmcnt(8)
	s_waitcnt lgkmcnt(0)
	s_barrier
	s_setprio 1
	s_waitcnt lgkmcnt(0)
	v_mfma_f32_16x16x32_bf16 v[66:69], v[26:29], v[172:175], v[66:69]
	v_mfma_f32_16x16x32_bf16 v[70:73], v[114:117], v[172:175], v[70:73]
	v_mfma_f32_16x16x32_bf16 v[74:77], v[26:29], v[184:187], v[74:77]
	v_mfma_f32_16x16x32_bf16 v[78:81], v[114:117], v[184:187], v[78:81]
	v_mfma_f32_16x16x32_bf16 v[82:85], v[26:29], v[192:195], v[82:85]
	v_mfma_f32_16x16x32_bf16 v[86:89], v[114:117], v[192:195], v[86:89]
	v_mfma_f32_16x16x32_bf16 v[90:93], v[26:29], v[200:203], v[90:93]
	v_mfma_f32_16x16x32_bf16 v[94:97], v[114:117], v[200:203], v[94:97]
	v_mfma_f32_16x16x32_bf16 v[66:69], v[30:33], v[176:179], v[66:69]
	v_mfma_f32_16x16x32_bf16 v[70:73], v[118:121], v[176:179], v[70:73]
	v_mfma_f32_16x16x32_bf16 v[74:77], v[30:33], v[188:191], v[74:77]
	v_mfma_f32_16x16x32_bf16 v[78:81], v[118:121], v[188:191], v[78:81]
	v_mfma_f32_16x16x32_bf16 v[82:85], v[30:33], v[196:199], v[82:85]
	v_mfma_f32_16x16x32_bf16 v[86:89], v[118:121], v[196:199], v[86:89]
	v_mfma_f32_16x16x32_bf16 v[90:93], v[30:33], v[204:207], v[90:93]
	v_mfma_f32_16x16x32_bf16 v[94:97], v[118:121], v[204:207], v[94:97]
	s_setprio 0
	s_setprio 1
	v_mfma_f32_16x16x32_bf16 v[98:101], v[122:125], v[172:175], v[98:101]
	v_mfma_f32_16x16x32_bf16 v[34:37], v[164:167], v[172:175], v[34:37]
	v_mfma_f32_16x16x32_bf16 v[38:41], v[122:125], v[184:187], v[38:41]
	v_mfma_f32_16x16x32_bf16 v[42:45], v[164:167], v[184:187], v[42:45]
	v_mfma_f32_16x16x32_bf16 v[46:49], v[122:125], v[192:195], v[46:49]
	v_mfma_f32_16x16x32_bf16 v[50:53], v[164:167], v[192:195], v[50:53]
	v_mfma_f32_16x16x32_bf16 v[54:57], v[122:125], v[200:203], v[54:57]
	v_mfma_f32_16x16x32_bf16 v[58:61], v[164:167], v[200:203], v[58:61]
	v_mfma_f32_16x16x32_bf16 v[98:101], v[126:129], v[176:179], v[98:101]
	v_mfma_f32_16x16x32_bf16 v[34:37], v[168:171], v[176:179], v[34:37]
	v_mfma_f32_16x16x32_bf16 v[38:41], v[126:129], v[188:191], v[38:41]
	v_mfma_f32_16x16x32_bf16 v[42:45], v[168:171], v[188:191], v[42:45]
	v_mfma_f32_16x16x32_bf16 v[46:49], v[126:129], v[196:199], v[46:49]
	v_mfma_f32_16x16x32_bf16 v[50:53], v[168:171], v[196:199], v[50:53]
	v_mfma_f32_16x16x32_bf16 v[54:57], v[126:129], v[204:207], v[54:57]
	v_mfma_f32_16x16x32_bf16 v[58:61], v[168:171], v[204:207], v[58:61]
	s_barrier
; #define PG8_STAGE(bufoff, gbase, voff) do { _Pragma("unroll") for (int _i = 0; _i < 2; ++_i) \
;         __builtin_amdgcn_global_load_lds((const unsigned*)((const char*)(gbase) + (voff)[_i]), (PG8_LAS unsigned*)(lds + (bufoff) + ldsw + _i * 8192), 16, 0, 0); } while (0)
; #define PG8_LDA(dst, b, h) do { _Pragma("unroll") for (int m = 0; m < 4; ++m) _Pragma("unroll") for (int k = 0; k < 2; ++k) dst[m][k] = *(const PG8_LAS bf16x8*)(lds + PG8_SA(b, h) + aoff + m * 2048 + k * 1024); } while (0)
; #define PG8_LDB(dst, b, h) do { _Pragma("unroll") for (int n = 0; n < 2; ++n) _Pragma("unroll") for (int k = 0; k < 2; ++k) dst[n][k] = *(const PG8_LAS bf16x8*)(lds + PG8_SB(b, h) + boff + n * 2048 + k * 1024); } while (0)
; #define PG8_MMA(ai, bj, At, Bt) do { __builtin_amdgcn_s_setprio(1); _Pragma("unroll") for (int m = 0; m < 4; ++m) _Pragma("unroll") for (int n = 0; n < 2; ++n) _Pragma("unroll") for (int k = 0; k < 2; ++k) \
;         acc[ai][bj][m][n] = __builtin_amdgcn_mfma_f32_16x16x32_bf16(Bt[n][k], At[m][k], acc[ai][bj][m][n], 0, 0, 0); __builtin_amdgcn_s_setprio(0); } while (0)
; #define PG8_BAR __builtin_amdgcn_s_barrier()
; template <class Epi, class Sched, bool ALIGN_EPI = false, bool SP2 = false>
; __device__ __forceinline__ void gemm_phase(PG8_LAS unsigned char* lds, const Gemm g, const Sched& S, const Epi& E, const int tid) {
;     ...
;             PG8_LDB(B0, 0, 0); PG8_LDB(B1, 0, 1); PG8_SCHED; PG8_LDA(At, 0, 0); PG8_STAGE(PG8_SA(1, 1), a1 + hstep, voffA);
;             PG8_WAIT_V(8); PG8_WAIT_L(0); PG8_BAR; PG8_MMA(0, 0, At, B0); PG8_MMA(0, 1, At, B1); PG8_BAR; PG8_SCHED;
;             PG8_LDA(At, 0, 1); PG8_STAGE(PG8_SB(0, 0), b2, voffB); PG8_STAGE(PG8_SB(0, 1), b2 + hstep, voffB); PG8_STAGE(PG8_SA(0, 0), a2, voffA);
;             PG8_WAIT_V(8); PG8_WAIT_L(0); PG8_BAR; PG8_MMA(1, 0, At, B0); PG8_MMA(1, 1, At, B1); PG8_BAR; PG8_SCHED;
;             PG8_LDB(B0, 1, 0); PG8_LDB(B1, 1, 1); PG8_SCHED; PG8_LDA(At, 1, 0); PG8_STAGE(PG8_SA(0, 1), a2 + hstep, voffA);
;             PG8_WAIT_V(8); PG8_WAIT_L(0); PG8_BAR; PG8_MMA(0, 0, At, B0); PG8_MMA(0, 1, At, B1); PG8_BAR; PG8_SCHED;
;             PG8_LDA(At, 1, 1); PG8_STAGE(PG8_SB(1, 0), b3, voffB); PG8_STAGE(PG8_SB(1, 1), b3 + hstep, voffB); PG8_STAGE(PG8_SA(1, 0), a3, voffA);
;             PG8_WAIT_V(8); PG8_WAIT_L(0); PG8_BAR; PG8_MMA(1, 0, At, B0); PG8_MMA(1, 1, At, B1); PG8_BAR; PG8_SCHED;
	s_setprio 0
	s_mov_b64 s[92:93], 0x180
	s_mov_b32 m0, s17
	v_lshl_add_u64 v[136:137], v[136:137], 0, s[92:93]
	s_add_u32 s50, s90, 0x10180
	ds_read_b128 v[172:175], v138 offset:49152
	ds_read_b128 v[176:179], v138 offset:50176
	ds_read_b128 v[184:187], v138 offset:51200
	ds_read_b128 v[188:191], v138 offset:52224
	ds_read_b128 v[192:195], v138 offset:53248
	ds_read_b128 v[196:199], v138 offset:54272
	ds_read_b128 v[200:203], v138 offset:55296
	ds_read_b128 v[204:207], v138 offset:56320
	global_load_lds_dwordx4 v[136:137], off
	v_lshl_add_u64 v[136:137], v[180:181], 0, s[92:93]
	s_mov_b32 m0, s20
	s_addc_u32 s51, s91, 0
	global_load_lds_dwordx4 v[136:137], off
	v_lshl_add_u64 v[136:137], s[50:51], 0, v[0:1]
	s_mov_b32 m0, s26
	s_nop 0
	global_load_lds_dwordx4 v[136:137], off
	v_lshl_add_u64 v[136:137], s[50:51], 0, v[130:131]
	s_mov_b32 m0, s27
	s_nop 0
	global_load_lds_dwordx4 v[136:137], off
	v_lshl_add_u64 v[136:137], v[182:183], 0, s[92:93]
	s_mov_b32 m0, s21
	s_nop 0
	global_load_lds_dwordx4 v[136:137], off
	v_lshl_add_u64 v[136:137], v[214:215], 0, s[92:93]
	s_mov_b32 m0, s24
	s_nop 0
	global_load_lds_dwordx4 v[136:137], off
	s_waitcnt vmcnt(8)
	s_waitcnt lgkmcnt(0)
	s_barrier
	s_setprio 1
	s_waitcnt lgkmcnt(0)
	v_mfma_f32_16x16x32_bf16 v[2:5], v[26:29], v[200:203], v[2:5]
	v_mfma_f32_16x16x32_bf16 v[6:9], v[114:117], v[200:203], v[6:9]
	v_mfma_f32_16x16x32_bf16 v[140:143], v[26:29], v[172:175], v[140:143]
	v_mfma_f32_16x16x32_bf16 v[144:147], v[114:117], v[172:175], v[144:147]
	v_mfma_f32_16x16x32_bf16 v[148:151], v[26:29], v[184:187], v[148:151]
	v_mfma_f32_16x16x32_bf16 v[152:155], v[114:117], v[184:187], v[152:155]
	v_mfma_f32_16x16x32_bf16 v[156:159], v[26:29], v[192:195], v[156:159]
	v_mfma_f32_16x16x32_bf16 v[160:163], v[114:117], v[192:195], v[160:163]
	v_mfma_f32_16x16x32_bf16 v[2:5], v[30:33], v[204:207], v[2:5]
	v_mfma_f32_16x16x32_bf16 v[6:9], v[118:121], v[204:207], v[6:9]
	v_mfma_f32_16x16x32_bf16 v[140:143], v[30:33], v[176:179], v[140:143]
	v_mfma_f32_16x16x32_bf16 v[144:147], v[118:121], v[176:179], v[144:147]
	v_mfma_f32_16x16x32_bf16 v[148:151], v[30:33], v[188:191], v[148:151]
	v_mfma_f32_16x16x32_bf16 v[152:155], v[118:121], v[188:191], v[152:155]
	v_mfma_f32_16x16x32_bf16 v[156:159], v[30:33], v[196:199], v[156:159]
	v_mfma_f32_16x16x32_bf16 v[160:163], v[118:121], v[196:199], v[160:163]
	s_setprio 0
	s_setprio 1
	v_mfma_f32_16x16x32_bf16 v[10:13], v[122:125], v[172:175], v[10:13]
	v_mfma_f32_16x16x32_bf16 v[14:17], v[164:167], v[172:175], v[14:17]
	v_mfma_f32_16x16x32_bf16 v[26:29], v[122:125], v[184:187], v[62:65]
	v_mfma_f32_16x16x32_bf16 v[30:33], v[164:167], v[184:187], v[102:105]
	v_mfma_f32_16x16x32_bf16 v[62:65], v[122:125], v[192:195], v[106:109]
	v_mfma_f32_16x16x32_bf16 v[102:105], v[164:167], v[192:195], v[110:113]
	v_mfma_f32_16x16x32_bf16 v[18:21], v[122:125], v[200:203], v[18:21]
	v_mfma_f32_16x16x32_bf16 v[22:25], v[164:167], v[200:203], v[22:25]
	v_mfma_f32_16x16x32_bf16 v[10:13], v[126:129], v[176:179], v[10:13]
	v_mfma_f32_16x16x32_bf16 v[14:17], v[168:171], v[176:179], v[14:17]
	v_mfma_f32_16x16x32_bf16 v[26:29], v[126:129], v[188:191], v[26:29]
	v_mfma_f32_16x16x32_bf16 v[30:33], v[168:171], v[188:191], v[30:33]
	v_mfma_f32_16x16x32_bf16 v[62:65], v[126:129], v[196:199], v[62:65]
	v_mfma_f32_16x16x32_bf16 v[102:105], v[168:171], v[196:199], v[102:105]
	v_mfma_f32_16x16x32_bf16 v[18:21], v[126:129], v[204:207], v[18:21]
	v_mfma_f32_16x16x32_bf16 v[22:25], v[168:171], v[204:207], v[22:25]
	s_barrier
	s_setprio 0
	ds_read_b128 v[106:109], v208
	ds_read_b128 v[110:113], v209
	ds_read_b128 v[114:117], v210
	ds_read_b128 v[118:121], v211
	ds_read_b128 v[122:125], v212
	ds_read_b128 v[126:129], v213
	ds_read_b128 v[164:167], v218
	ds_read_b128 v[168:171], v219
	s_add_u32 s50, s88, 0x10180
	s_addc_u32 s51, s89, 0
	s_mov_b32 m0, s43
	v_lshl_add_u64 v[136:137], s[50:51], 0, v[134:135]
	ds_read_b128 v[172:175], v138
	ds_read_b128 v[176:179], v138 offset:1024
	ds_read_b128 v[184:187], v138 offset:2048
	ds_read_b128 v[188:191], v138 offset:3072
	ds_read_b128 v[192:195], v138 offset:4096
	ds_read_b128 v[196:199], v138 offset:5120
	ds_read_b128 v[200:203], v138 offset:6144
	ds_read_b128 v[204:207], v138 offset:7168
	global_load_lds_dwordx4 v[136:137], off
	v_lshl_add_u64 v[136:137], s[50:51], 0, v[132:133]
	s_mov_b32 m0, s41
	s_nop 0
	global_load_lds_dwordx4 v[136:137], off
	s_waitcnt vmcnt(8)
	s_waitcnt lgkmcnt(0)
	s_barrier
	s_setprio 1
	s_waitcnt lgkmcnt(0)
	v_mfma_f32_16x16x32_bf16 v[66:69], v[106:109], v[172:175], v[66:69]
	v_mfma_f32_16x16x32_bf16 v[70:73], v[114:117], v[172:175], v[70:73]
	v_mfma_f32_16x16x32_bf16 v[74:77], v[106:109], v[184:187], v[74:77]
	v_mfma_f32_16x16x32_bf16 v[78:81], v[114:117], v[184:187], v[78:81]
	v_mfma_f32_16x16x32_bf16 v[82:85], v[106:109], v[192:195], v[82:85]
	v_mfma_f32_16x16x32_bf16 v[86:89], v[114:117], v[192:195], v[86:89]
	v_mfma_f32_16x16x32_bf16 v[90:93], v[106:109], v[200:203], v[90:93]
	v_mfma_f32_16x16x32_bf16 v[66:69], v[110:113], v[176:179], v[66:69]
	v_mfma_f32_16x16x32_bf16 v[70:73], v[118:121], v[176:179], v[70:73]
	v_mfma_f32_16x16x32_bf16 v[74:77], v[110:113], v[188:191], v[74:77]
	v_mfma_f32_16x16x32_bf16 v[78:81], v[118:121], v[188:191], v[78:81]
	v_mfma_f32_16x16x32_bf16 v[82:85], v[110:113], v[196:199], v[82:85]
	v_mfma_f32_16x16x32_bf16 v[86:89], v[118:121], v[196:199], v[86:89]
	v_mfma_f32_16x16x32_bf16 v[90:93], v[110:113], v[204:207], v[90:93]
	v_mfma_f32_16x16x32_bf16 v[94:97], v[114:117], v[200:203], v[94:97]
	v_mfma_f32_16x16x32_bf16 v[214:217], v[118:121], v[204:207], v[94:97]
	s_setprio 0
	s_setprio 1
	v_mfma_f32_16x16x32_bf16 v[94:97], v[122:125], v[172:175], v[98:101]
	v_mfma_f32_16x16x32_bf16 v[34:37], v[164:167], v[172:175], v[34:37]
	v_mfma_f32_16x16x32_bf16 v[38:41], v[122:125], v[184:187], v[38:41]
	v_mfma_f32_16x16x32_bf16 v[42:45], v[164:167], v[184:187], v[42:45]
	v_mfma_f32_16x16x32_bf16 v[46:49], v[122:125], v[192:195], v[46:49]
	v_mfma_f32_16x16x32_bf16 v[50:53], v[164:167], v[192:195], v[50:53]
	v_mfma_f32_16x16x32_bf16 v[54:57], v[122:125], v[200:203], v[54:57]
	v_mfma_f32_16x16x32_bf16 v[98:101], v[126:129], v[176:179], v[94:97]
	v_mfma_f32_16x16x32_bf16 v[34:37], v[168:171], v[176:179], v[34:37]
	v_mfma_f32_16x16x32_bf16 v[38:41], v[126:129], v[188:191], v[38:41]
	v_mfma_f32_16x16x32_bf16 v[42:45], v[168:171], v[188:191], v[42:45]
	v_mfma_f32_16x16x32_bf16 v[46:49], v[126:129], v[196:199], v[46:49]
	v_mfma_f32_16x16x32_bf16 v[50:53], v[168:171], v[196:199], v[50:53]
	v_mfma_f32_16x16x32_bf16 v[172:175], v[126:129], v[204:207], v[54:57]
	v_mfma_f32_16x16x32_bf16 v[54:57], v[164:167], v[200:203], v[58:61]
	v_mfma_f32_16x16x32_bf16 v[176:179], v[168:171], v[204:207], v[54:57]
	s_barrier
; #define PG8_STAGE(bufoff, gbase, voff) do { _Pragma("unroll") for (int _i = 0; _i < 2; ++_i) \
;         __builtin_amdgcn_global_load_lds((const unsigned*)((const char*)(gbase) + (voff)[_i]), (PG8_LAS unsigned*)(lds + (bufoff) + ldsw + _i * 8192), 16, 0, 0); } while (0)
; #define PG8_LDA(dst, b, h) do { _Pragma("unroll") for (int m = 0; m < 4; ++m) _Pragma("unroll") for (int k = 0; k < 2; ++k) dst[m][k] = *(const PG8_LAS bf16x8*)(lds + PG8_SA(b, h) + aoff + m * 2048 + k * 1024); } while (0)
; #define PG8_LDB(dst, b, h) do { _Pragma("unroll") for (int n = 0; n < 2; ++n) _Pragma("unroll") for (int k = 0; k < 2; ++k) dst[n][k] = *(const PG8_LAS bf16x8*)(lds + PG8_SB(b, h) + boff + n * 2048 + k * 1024); } while (0)
; #define PG8_MMA(ai, bj, At, Bt) do { __builtin_amdgcn_s_setprio(1); _Pragma("unroll") for (int m = 0; m < 4; ++m) _Pragma("unroll") for (int n = 0; n < 2; ++n) _Pragma("unroll") for (int k = 0; k < 2; ++k) \
;         acc[ai][bj][m][n] = __builtin_amdgcn_mfma_f32_16x16x32_bf16(Bt[n][k], At[m][k], acc[ai][bj][m][n], 0, 0, 0); __builtin_amdgcn_s_setprio(0); } while (0)
; #define PG8_BAR __builtin_amdgcn_s_barrier()
; template <class Epi, class Sched, bool ALIGN_EPI = false, bool SP2 = false>
; __device__ __forceinline__ void gemm_phase(PG8_LAS unsigned char* lds, const Gemm g, const Sched& S, const Epi& E, const int tid) {
;     ...
;             PG8_LDB(B0, 0, 0); PG8_LDB(B1, 0, 1); PG8_SCHED; PG8_LDA(At, 0, 0); PG8_STAGE(PG8_SA(1, 1), a1 + hstep, voffA);
;             PG8_WAIT_V(8); PG8_WAIT_L(0); PG8_BAR; PG8_MMA(0, 0, At, B0); PG8_MMA(0, 1, At, B1); PG8_BAR; PG8_SCHED;
;             PG8_LDA(At, 0, 1); PG8_STAGE(PG8_SB(0, 0), b2, voffB); PG8_STAGE(PG8_SB(0, 1), b2 + hstep, voffB); PG8_STAGE(PG8_SA(0, 0), a2, voffA);
;             PG8_WAIT_V(8); PG8_WAIT_L(0); PG8_BAR; PG8_MMA(1, 0, At, B0); PG8_MMA(1, 1, At, B1); PG8_BAR; PG8_SCHED;
;             PG8_LDB(B0, 1, 0); PG8_LDB(B1, 1, 1); PG8_SCHED; PG8_LDA(At, 1, 0); PG8_STAGE(PG8_SA(0, 1), a2 + hstep, voffA);
;             PG8_WAIT_V(8); PG8_WAIT_L(0); PG8_BAR; PG8_MMA(0, 0, At, B0); PG8_MMA(0, 1, At, B1); PG8_BAR; PG8_SCHED;
;             PG8_LDA(At, 1, 1); PG8_STAGE(PG8_SB(1, 0), b3, voffB); PG8_STAGE(PG8_SB(1, 1), b3 + hstep, voffB); PG8_STAGE(PG8_SA(1, 0), a3, voffA);
;             PG8_WAIT_V(8); PG8_WAIT_L(0); PG8_BAR; PG8_MMA(1, 0, At, B0); PG8_MMA(1, 1, At, B1); PG8_BAR; PG8_SCHED;
	s_setprio 0
	s_mov_b32 m0, s1
	v_lshl_add_u64 v[136:137], s[84:85], 0, v[0:1]
	s_add_u32 s50, s84, 0x10000
	s_nop 1
	ds_read_b128 v[54:57], v138 offset:16384
	ds_read_b128 v[58:61], v138 offset:17408
	ds_read_b128 v[94:97], v138 offset:18432
	ds_read_b128 v[184:187], v138 offset:19456
	ds_read_b128 v[188:191], v138 offset:20480
	ds_read_b128 v[192:195], v138 offset:21504
	ds_read_b128 v[196:199], v138 offset:22528
	ds_read_b128 v[200:203], v138 offset:23552
	global_load_lds_dwordx4 v[136:137], off
	v_lshl_add_u64 v[208:209], s[84:85], 0, v[130:131]
	s_mov_b32 m0, s2
	s_addc_u32 s51, s85, 0
	global_load_lds_dwordx4 v[208:209], off
	v_lshl_add_u64 v[180:181], s[50:51], 0, v[0:1]
	s_mov_b32 m0, s4
	v_lshl_add_u64 v[210:211], s[86:87], 0, v[134:135]
	global_load_lds_dwordx4 v[180:181], off
	v_lshl_add_u64 v[180:181], s[50:51], 0, v[130:131]
	s_mov_b32 m0, s5
	v_lshl_add_u64 v[212:213], s[86:87], 0, v[132:133]
	global_load_lds_dwordx4 v[180:181], off
	s_mov_b32 m0, s0
	s_nop 0
	global_load_lds_dwordx4 v[210:211], off
	s_mov_b32 m0, s6
	s_nop 0
	global_load_lds_dwordx4 v[212:213], off
	s_waitcnt vmcnt(8)
	s_waitcnt lgkmcnt(0)
	s_barrier
	s_setprio 1
	s_waitcnt lgkmcnt(0)
	v_mfma_f32_16x16x32_bf16 v[2:5], v[106:109], v[196:199], v[2:5]
	v_mfma_f32_16x16x32_bf16 v[6:9], v[114:117], v[196:199], v[6:9]
	v_mfma_f32_16x16x32_bf16 v[140:143], v[106:109], v[54:57], v[140:143]
	v_mfma_f32_16x16x32_bf16 v[144:147], v[114:117], v[54:57], v[144:147]
	v_mfma_f32_16x16x32_bf16 v[148:151], v[106:109], v[94:97], v[148:151]
	v_mfma_f32_16x16x32_bf16 v[152:155], v[114:117], v[94:97], v[152:155]
	v_mfma_f32_16x16x32_bf16 v[156:159], v[106:109], v[188:191], v[156:159]
	v_mfma_f32_16x16x32_bf16 v[160:163], v[114:117], v[188:191], v[160:163]
	v_mfma_f32_16x16x32_bf16 v[2:5], v[110:113], v[200:203], v[2:5]
	v_mfma_f32_16x16x32_bf16 v[6:9], v[118:121], v[200:203], v[6:9]
	v_mfma_f32_16x16x32_bf16 v[140:143], v[110:113], v[58:61], v[140:143]
	v_mfma_f32_16x16x32_bf16 v[144:147], v[118:121], v[58:61], v[144:147]
	v_mfma_f32_16x16x32_bf16 v[148:151], v[110:113], v[184:187], v[148:151]
	v_mfma_f32_16x16x32_bf16 v[152:155], v[118:121], v[184:187], v[152:155]
	v_mfma_f32_16x16x32_bf16 v[156:159], v[110:113], v[192:195], v[156:159]
	v_mfma_f32_16x16x32_bf16 v[160:163], v[118:121], v[192:195], v[160:163]
	s_setprio 0
	s_setprio 1
	v_mfma_f32_16x16x32_bf16 v[14:17], v[164:167], v[54:57], v[14:17]
	v_mfma_f32_16x16x32_bf16 v[204:207], v[168:171], v[58:61], v[14:17]
	v_mfma_f32_16x16x32_bf16 v[14:17], v[122:125], v[94:97], v[26:29]
	v_mfma_f32_16x16x32_bf16 v[26:29], v[126:129], v[184:187], v[14:17]
	v_mfma_f32_16x16x32_bf16 v[14:17], v[164:167], v[94:97], v[30:33]
	v_mfma_f32_16x16x32_bf16 v[184:187], v[168:171], v[184:187], v[14:17]
	v_mfma_f32_16x16x32_bf16 v[14:17], v[122:125], v[188:191], v[62:65]
	v_mfma_f32_16x16x32_bf16 v[218:221], v[126:129], v[192:195], v[14:17]
	v_mfma_f32_16x16x32_bf16 v[14:17], v[164:167], v[188:191], v[102:105]
	v_mfma_f32_16x16x32_bf16 v[10:13], v[122:125], v[54:57], v[10:13]
	v_mfma_f32_16x16x32_bf16 v[188:191], v[168:171], v[192:195], v[14:17]
	v_mfma_f32_16x16x32_bf16 v[14:17], v[122:125], v[196:199], v[18:21]
	v_mfma_f32_16x16x32_bf16 v[10:13], v[126:129], v[58:61], v[10:13]
	v_mfma_f32_16x16x32_bf16 v[192:195], v[126:129], v[200:203], v[14:17]
	v_mfma_f32_16x16x32_bf16 v[14:17], v[164:167], v[196:199], v[22:25]
	v_mfma_f32_16x16x32_bf16 v[164:167], v[168:171], v[200:203], v[14:17]
	s_barrier
	s_setprio 0
	s_nop 4
	ds_read_b128 v[14:17], v222
	ds_read_b128 v[18:21], v223
	ds_read_b128 v[168:171], v224
	ds_read_b128 v[196:199], v225
	ds_read_b128 v[200:203], v226
	ds_read_b128 v[222:225], v227
	ds_read_b128 v[226:229], v228
	ds_read_b128 v[230:233], v230
	s_add_u32 s50, s86, 0x10000
	s_addc_u32 s51, s87, 0
	s_mov_b32 m0, s8
	v_lshl_add_u64 v[54:55], s[50:51], 0, v[134:135]
	ds_read_b128 v[22:25], v138 offset:32768
	ds_read_b128 v[30:33], v138 offset:33792
	ds_read_b128 v[58:61], v138 offset:34816
	ds_read_b128 v[234:237], v138 offset:35840
	ds_read_b128 v[238:241], v138 offset:36864
	ds_read_b128 v[242:245], v138 offset:37888
	ds_read_b128 v[246:249], v138 offset:38912
	ds_read_b128 v[180:183], v138 offset:39936
	global_load_lds_dwordx4 v[54:55], off
	v_lshl_add_u64 v[54:55], s[50:51], 0, v[132:133]
	s_mov_b32 m0, s9
	s_nop 0
	global_load_lds_dwordx4 v[54:55], off
	s_waitcnt vmcnt(8)
	s_waitcnt lgkmcnt(0)
	s_barrier
; #define PG8_STAGE(bufoff, gbase, voff) do { _Pragma("unroll") for (int _i = 0; _i < 2; ++_i) \
;         __builtin_amdgcn_global_load_lds((const unsigned*)((const char*)(gbase) + (voff)[_i]), (PG8_LAS unsigned*)(lds + (bufoff) + ldsw + _i * 8192), 16, 0, 0); } while (0)
; #define PG8_LDA(dst, b, h) do { _Pragma("unroll") for (int m = 0; m < 4; ++m) _Pragma("unroll") for (int k = 0; k < 2; ++k) dst[m][k] = *(const PG8_LAS bf16x8*)(lds + PG8_SA(b, h) + aoff + m * 2048 + k * 1024); } while (0)
; #define PG8_LDB(dst, b, h) do { _Pragma("unroll") for (int n = 0; n < 2; ++n) _Pragma("unroll") for (int k = 0; k < 2; ++k) dst[n][k] = *(const PG8_LAS bf16x8*)(lds + PG8_SB(b, h) + boff + n * 2048 + k * 1024); } while (0)
; #define PG8_MMA(ai, bj, At, Bt) do { __builtin_amdgcn_s_setprio(1); _Pragma("unroll") for (int m = 0; m < 4; ++m) _Pragma("unroll") for (int n = 0; n < 2; ++n) _Pragma("unroll") for (int k = 0; k < 2; ++k) \
;         acc[ai][bj][m][n] = __builtin_amdgcn_mfma_f32_16x16x32_bf16(Bt[n][k], At[m][k], acc[ai][bj][m][n], 0, 0, 0); __builtin_amdgcn_s_setprio(0); } while (0)
; #define PG8_BAR __builtin_amdgcn_s_barrier()
; template <class Epi, class Sched, bool ALIGN_EPI = false, bool SP2 = false>
; __device__ __forceinline__ void gemm_phase(PG8_LAS unsigned char* lds, const Gemm g, const Sched& S, const Epi& E, const int tid) {
;     ...
;             PG8_LDB(B0, 0, 0); PG8_LDB(B1, 0, 1); PG8_SCHED; PG8_LDA(At, 0, 0); PG8_STAGE(PG8_SA(1, 1), a1 + hstep, voffA);
;             PG8_WAIT_V(8); PG8_WAIT_L(0); PG8_BAR; PG8_MMA(0, 0, At, B0); PG8_MMA(0, 1, At, B1); PG8_BAR; PG8_SCHED;
;             PG8_LDA(At, 0, 1); PG8_STAGE(PG8_SB(0, 0), b2, voffB); PG8_STAGE(PG8_SB(0, 1), b2 + hstep, voffB); PG8_STAGE(PG8_SA(0, 0), a2, voffA);
;             PG8_WAIT_V(8); PG8_WAIT_L(0); PG8_BAR; PG8_MMA(1, 0, At, B0); PG8_MMA(1, 1, At, B1); PG8_BAR; PG8_SCHED;
;             PG8_LDB(B0, 1, 0); PG8_LDB(B1, 1, 1); PG8_SCHED; PG8_LDA(At, 1, 0); PG8_STAGE(PG8_SA(0, 1), a2 + hstep, voffA);
;             PG8_WAIT_V(8); PG8_WAIT_L(0); PG8_BAR; PG8_MMA(0, 0, At, B0); PG8_MMA(0, 1, At, B1); PG8_BAR; PG8_SCHED;
;             PG8_LDA(At, 1, 1); PG8_STAGE(PG8_SB(1, 0), b3, voffB); PG8_STAGE(PG8_SB(1, 1), b3 + hstep, voffB); PG8_STAGE(PG8_SA(1, 0), a3, voffA);
;             PG8_WAIT_V(8); PG8_WAIT_L(0); PG8_BAR; PG8_MMA(1, 0, At, B0); PG8_MMA(1, 1, At, B1); PG8_BAR; PG8_SCHED;
	s_setprio 1
	s_waitcnt lgkmcnt(0)
	v_mfma_f32_16x16x32_bf16 v[54:57], v[14:17], v[22:25], v[66:69]
	v_mfma_f32_16x16x32_bf16 v[122:125], v[18:21], v[30:33], v[54:57]
	v_mfma_f32_16x16x32_bf16 v[54:57], v[168:171], v[22:25], v[70:73]
	v_mfma_f32_16x16x32_bf16 v[114:117], v[196:199], v[30:33], v[54:57]
	v_mfma_f32_16x16x32_bf16 v[54:57], v[14:17], v[58:61], v[74:77]
	v_mfma_f32_16x16x32_bf16 v[110:113], v[18:21], v[234:237], v[54:57]
	v_mfma_f32_16x16x32_bf16 v[54:57], v[168:171], v[58:61], v[78:81]
	v_mfma_f32_16x16x32_bf16 v[102:105], v[196:199], v[234:237], v[54:57]
	v_mfma_f32_16x16x32_bf16 v[54:57], v[14:17], v[238:241], v[82:85]
	v_mfma_f32_16x16x32_bf16 v[94:97], v[18:21], v[242:245], v[54:57]
	v_mfma_f32_16x16x32_bf16 v[54:57], v[168:171], v[238:241], v[86:89]
	v_mfma_f32_16x16x32_bf16 v[86:89], v[196:199], v[242:245], v[54:57]
	v_mfma_f32_16x16x32_bf16 v[54:57], v[14:17], v[246:249], v[90:93]
	v_mfma_f32_16x16x32_bf16 v[62:65], v[18:21], v[180:183], v[54:57]
	v_mfma_f32_16x16x32_bf16 v[54:57], v[168:171], v[246:249], v[214:217]
	v_mfma_f32_16x16x32_bf16 v[54:57], v[196:199], v[180:183], v[54:57]
	s_setprio 0
	s_setprio 1
	v_mfma_f32_16x16x32_bf16 v[66:69], v[200:203], v[22:25], v[98:101]
	v_mfma_f32_16x16x32_bf16 v[22:25], v[226:229], v[22:25], v[34:37]
	v_mfma_f32_16x16x32_bf16 v[118:121], v[230:233], v[30:33], v[22:25]
	v_mfma_f32_16x16x32_bf16 v[22:25], v[200:203], v[58:61], v[38:41]
	v_mfma_f32_16x16x32_bf16 v[106:109], v[222:225], v[234:237], v[22:25]
	v_mfma_f32_16x16x32_bf16 v[22:25], v[226:229], v[58:61], v[42:45]
	v_mfma_f32_16x16x32_bf16 v[98:101], v[230:233], v[234:237], v[22:25]
	v_mfma_f32_16x16x32_bf16 v[22:25], v[200:203], v[238:241], v[46:49]
	v_mfma_f32_16x16x32_bf16 v[90:93], v[222:225], v[242:245], v[22:25]
	v_mfma_f32_16x16x32_bf16 v[22:25], v[226:229], v[238:241], v[50:53]
	v_mfma_f32_16x16x32_bf16 v[82:85], v[230:233], v[242:245], v[22:25]
	v_mfma_f32_16x16x32_bf16 v[22:25], v[200:203], v[246:249], v[172:175]
	v_mfma_f32_16x16x32_bf16 v[58:61], v[222:225], v[180:183], v[22:25]
	v_mfma_f32_16x16x32_bf16 v[22:25], v[226:229], v[246:249], v[176:179]
	v_mfma_f32_16x16x32_bf16 v[126:129], v[222:225], v[30:33], v[66:69]
	v_mfma_f32_16x16x32_bf16 v[50:53], v[230:233], v[180:183], v[22:25]
	s_barrier
	s_setprio 0
	s_mov_b32 m0, s17
	s_nop 2
	v_lshl_add_u64 v[22:23], v[136:137], 0, s[12:13]
	s_add_u32 s50, s84, 0x10080
	ds_read_b128 v[34:37], v138 offset:49152
	ds_read_b128 v[42:45], v138 offset:50176
	ds_read_b128 v[172:175], v138 offset:51200
	ds_read_b128 v[176:179], v138 offset:52224
	ds_read_b128 v[180:183], v138 offset:53248
	ds_read_b128 v[214:217], v138 offset:54272
	ds_read_b128 v[234:237], v138 offset:55296
	ds_read_b128 v[238:241], v138 offset:56320
	global_load_lds_dwordx4 v[22:23], off
	v_lshl_add_u64 v[22:23], v[208:209], 0, s[12:13]
	s_mov_b32 m0, s20
	s_addc_u32 s51, s85, 0
	global_load_lds_dwordx4 v[22:23], off
	v_lshl_add_u64 v[22:23], s[50:51], 0, v[0:1]
	s_mov_b32 m0, s26
	s_nop 0
	global_load_lds_dwordx4 v[22:23], off
	v_lshl_add_u64 v[22:23], s[50:51], 0, v[130:131]
	s_mov_b32 m0, s27
	s_nop 0
	global_load_lds_dwordx4 v[22:23], off
	v_lshl_add_u64 v[22:23], v[210:211], 0, s[12:13]
	s_mov_b32 m0, s21
	s_nop 0
	global_load_lds_dwordx4 v[22:23], off
	v_lshl_add_u64 v[22:23], v[212:213], 0, s[12:13]
	s_mov_b32 m0, s24
	s_nop 0
	global_load_lds_dwordx4 v[22:23], off
	s_waitcnt vmcnt(8)
	s_waitcnt lgkmcnt(0)
	s_barrier
	s_setprio 1
	s_waitcnt lgkmcnt(0)
	v_mfma_f32_16x16x32_bf16 v[22:25], v[14:17], v[34:37], v[140:143]
	v_mfma_f32_16x16x32_bf16 v[78:81], v[18:21], v[42:45], v[22:25]
	v_mfma_f32_16x16x32_bf16 v[22:25], v[168:171], v[34:37], v[144:147]
	v_mfma_f32_16x16x32_bf16 v[70:73], v[196:199], v[42:45], v[22:25]
	v_mfma_f32_16x16x32_bf16 v[22:25], v[14:17], v[172:175], v[148:151]
	v_mfma_f32_16x16x32_bf16 v[46:49], v[18:21], v[176:179], v[22:25]
	v_mfma_f32_16x16x32_bf16 v[22:25], v[168:171], v[172:175], v[152:155]
	v_mfma_f32_16x16x32_bf16 v[38:41], v[196:199], v[176:179], v[22:25]
	v_mfma_f32_16x16x32_bf16 v[22:25], v[14:17], v[180:183], v[156:159]
	v_mfma_f32_16x16x32_bf16 v[2:5], v[14:17], v[234:237], v[2:5]
	v_mfma_f32_16x16x32_bf16 v[30:33], v[18:21], v[214:217], v[22:25]
	v_mfma_f32_16x16x32_bf16 v[22:25], v[168:171], v[180:183], v[160:163]
	v_mfma_f32_16x16x32_bf16 v[14:17], v[18:21], v[238:241], v[2:5]
	v_mfma_f32_16x16x32_bf16 v[2:5], v[168:171], v[234:237], v[6:9]
	v_mfma_f32_16x16x32_bf16 v[22:25], v[196:199], v[214:217], v[22:25]
	v_mfma_f32_16x16x32_bf16 v[6:9], v[196:199], v[238:241], v[2:5]
	s_setprio 0
	s_setprio 1
	v_mfma_f32_16x16x32_bf16 v[2:5], v[200:203], v[34:37], v[10:13]
	v_mfma_f32_16x16x32_bf16 v[74:77], v[222:225], v[42:45], v[2:5]
	v_mfma_f32_16x16x32_bf16 v[2:5], v[226:229], v[34:37], v[204:207]
	v_mfma_f32_16x16x32_bf16 v[66:69], v[230:233], v[42:45], v[2:5]
	v_mfma_f32_16x16x32_bf16 v[2:5], v[200:203], v[172:175], v[26:29]
	v_mfma_f32_16x16x32_bf16 v[42:45], v[222:225], v[176:179], v[2:5]
	v_mfma_f32_16x16x32_bf16 v[2:5], v[226:229], v[172:175], v[184:187]
	v_mfma_f32_16x16x32_bf16 v[34:37], v[230:233], v[176:179], v[2:5]
	v_mfma_f32_16x16x32_bf16 v[2:5], v[200:203], v[180:183], v[218:221]
	v_mfma_f32_16x16x32_bf16 v[26:29], v[222:225], v[214:217], v[2:5]
	v_mfma_f32_16x16x32_bf16 v[2:5], v[226:229], v[180:183], v[188:191]
	v_mfma_f32_16x16x32_bf16 v[18:21], v[230:233], v[214:217], v[2:5]
	v_mfma_f32_16x16x32_bf16 v[2:5], v[200:203], v[234:237], v[192:195]
	v_mfma_f32_16x16x32_bf16 v[10:13], v[222:225], v[238:241], v[2:5]
	v_mfma_f32_16x16x32_bf16 v[2:5], v[226:229], v[234:237], v[164:167]
	v_mfma_f32_16x16x32_bf16 v[2:5], v[230:233], v[238:241], v[2:5]
	s_barrier
	s_setprio 0
	s_andn2_b64 vcc, exec, s[30:31]
	s_cbranch_vccnz .LBB0_372
	s_barrier

; #define PG8_STAGE(bufoff, gbase, voff) do { _Pragma("unroll") for (int _i = 0; _i < 2; ++_i) \
;         __builtin_amdgcn_global_load_lds((const unsigned*)((const char*)(gbase) + (voff)[_i]), (PG8_LAS unsigned*)(lds + (bufoff) + ldsw + _i * 8192), 16, 0, 0); } while (0)
; #define PG8_LDA(dst, b, h) do { _Pragma("unroll") for (int m = 0; m < 4; ++m) _Pragma("unroll") for (int k = 0; k < 2; ++k) dst[m][k] = *(const PG8_LAS bf16x8*)(lds + PG8_SA(b, h) + aoff + m * 2048 + k * 1024); } while (0)
; #define PG8_LDB(dst, b, h) do { _Pragma("unroll") for (int n = 0; n < 2; ++n) _Pragma("unroll") for (int k = 0; k < 2; ++k) dst[n][k] = *(const PG8_LAS bf16x8*)(lds + PG8_SB(b, h) + boff + n * 2048 + k * 1024); } while (0)
; #define PG8_MMA(ai, bj, At, Bt) do { __builtin_amdgcn_s_setprio(1); _Pragma("unroll") for (int m = 0; m < 4; ++m) _Pragma("unroll") for (int n = 0; n < 2; ++n) _Pragma("unroll") for (int k = 0; k < 2; ++k) \
;         acc[ai][bj][m][n] = __builtin_amdgcn_mfma_f32_16x16x32_bf16(Bt[n][k], At[m][k], acc[ai][bj][m][n], 0, 0, 0); __builtin_amdgcn_s_setprio(0); } while (0)
; #define PG8_BAR __builtin_amdgcn_s_barrier()
; template <class Epi, class Sched, bool ALIGN_EPI = false, bool SP2 = false>
; __device__ __forceinline__ void gemm_phase(PG8_LAS unsigned char* lds, const Gemm g, const Sched& S, const Epi& E, const int tid) {
;     ...
;             PG8_LDB(B0, 0, 0); PG8_LDB(B1, 0, 1); PG8_SCHED; PG8_LDA(At, 0, 0); PG8_STAGE(PG8_SA(1, 1), a1 + hstep, voffA);
;             PG8_WAIT_V(8); PG8_WAIT_L(0); PG8_BAR; PG8_MMA(0, 0, At, B0); PG8_MMA(0, 1, At, B1); PG8_BAR; PG8_SCHED;
;             PG8_LDA(At, 0, 1); PG8_STAGE(PG8_SB(0, 0), b2, voffB); PG8_STAGE(PG8_SB(0, 1), b2 + hstep, voffB); PG8_STAGE(PG8_SA(0, 0), a2, voffA);
;             PG8_WAIT_V(8); PG8_WAIT_L(0); PG8_BAR; PG8_MMA(1, 0, At, B0); PG8_MMA(1, 1, At, B1); PG8_BAR; PG8_SCHED;
;             PG8_LDB(B0, 1, 0); PG8_LDB(B1, 1, 1); PG8_SCHED; PG8_LDA(At, 1, 0); PG8_STAGE(PG8_SA(0, 1), a2 + hstep, voffA);
;             PG8_WAIT_V(8); PG8_WAIT_L(0); PG8_BAR; PG8_MMA(0, 0, At, B0); PG8_MMA(0, 1, At, B1); PG8_BAR; PG8_SCHED;
;             PG8_LDA(At, 1, 1); PG8_STAGE(PG8_SB(1, 0), b3, voffB); PG8_STAGE(PG8_SB(1, 1), b3 + hstep, voffB); PG8_STAGE(PG8_SA(1, 0), a3, voffA);
;             PG8_WAIT_V(8); PG8_WAIT_L(0); PG8_BAR; PG8_MMA(1, 0, At, B0); PG8_MMA(1, 1, At, B1); PG8_BAR; PG8_SCHED;
.LBB0_388:
	v_or_b32_e32 v0, 0x10000, v179
	v_add_u32_e32 v11, 0x10800, v179
	v_or_b32_e32 v13, 0x14000, v179
	v_add_u32_e32 v15, 0x14800, v179
	v_add_u32_e32 v10, 0x10400, v179
	ds_read_b128 v[18:21], v0
	ds_read_b128 v[22:25], v10
	v_add_u32_e32 v12, 0x10c00, v179
	ds_read_b128 v[26:29], v11
	ds_read_b128 v[30:33], v12
	v_add_u32_e32 v14, 0x14400, v179
	ds_read_b128 v[34:37], v13
	ds_read_b128 v[38:41], v14
	v_add_u32_e32 v16, 0x14c00, v179
	ds_read_b128 v[42:45], v15
	ds_read_b128 v[46:49], v16
	s_add_u32 s20, s30, 0x18080
	s_addc_u32 s21, s31, 0
	s_add_i32 s5, s1, 0xc000
	v_lshl_add_u64 v[74:75], s[20:21], 0, v[168:169]
	s_mov_b32 m0, s5
	s_add_i32 s4, s1, 0xe000
	ds_read_b128 v[2:5], v178
	ds_read_b128 v[6:9], v178 offset:1024
	ds_read_b128 v[50:53], v178 offset:2048
	ds_read_b128 v[54:57], v178 offset:3072
	ds_read_b128 v[58:61], v178 offset:4096
	ds_read_b128 v[62:65], v178 offset:5120
	ds_read_b128 v[66:69], v178 offset:6144
	ds_read_b128 v[70:73], v178 offset:7168
	global_load_lds_dwordx4 v[74:75], off
	v_lshl_add_u64 v[74:75], s[20:21], 0, v[164:165]
	s_mov_b32 m0, s4
	s_nop 0
	global_load_lds_dwordx4 v[74:75], off
	s_waitcnt vmcnt(8)
	s_waitcnt lgkmcnt(0)
	s_barrier
	s_setprio 1
	s_waitcnt lgkmcnt(0)
	v_mfma_f32_16x16x32_bf16 v[74:77], v[18:21], v[2:5], 0
	v_mfma_f32_16x16x32_bf16 v[78:81], v[26:29], v[2:5], 0
	v_mfma_f32_16x16x32_bf16 v[82:85], v[18:21], v[50:53], 0
	v_mfma_f32_16x16x32_bf16 v[86:89], v[26:29], v[50:53], 0
	v_mfma_f32_16x16x32_bf16 v[90:93], v[18:21], v[58:61], 0
	v_mfma_f32_16x16x32_bf16 v[94:97], v[26:29], v[58:61], 0
	v_mfma_f32_16x16x32_bf16 v[98:101], v[18:21], v[66:69], 0
	v_mfma_f32_16x16x32_bf16 v[102:105], v[26:29], v[66:69], 0
	v_mfma_f32_16x16x32_bf16 v[74:77], v[22:25], v[6:9], v[74:77]
	v_mfma_f32_16x16x32_bf16 v[78:81], v[30:33], v[6:9], v[78:81]
	v_mfma_f32_16x16x32_bf16 v[82:85], v[22:25], v[54:57], v[82:85]
	v_mfma_f32_16x16x32_bf16 v[86:89], v[30:33], v[54:57], v[86:89]
	v_mfma_f32_16x16x32_bf16 v[90:93], v[22:25], v[62:65], v[90:93]
	v_mfma_f32_16x16x32_bf16 v[94:97], v[30:33], v[62:65], v[94:97]
	v_mfma_f32_16x16x32_bf16 v[98:101], v[22:25], v[70:73], v[98:101]
	v_mfma_f32_16x16x32_bf16 v[102:105], v[30:33], v[70:73], v[102:105]
	s_setprio 0
	s_setprio 1
	v_mfma_f32_16x16x32_bf16 v[106:109], v[34:37], v[2:5], 0
	v_mfma_f32_16x16x32_bf16 v[2:5], v[42:45], v[2:5], 0
	v_mfma_f32_16x16x32_bf16 v[110:113], v[46:49], v[6:9], v[2:5]
	v_mfma_f32_16x16x32_bf16 v[2:5], v[34:37], v[50:53], 0
	v_mfma_f32_16x16x32_bf16 v[114:117], v[38:41], v[54:57], v[2:5]
	v_mfma_f32_16x16x32_bf16 v[2:5], v[42:45], v[50:53], 0
	v_mfma_f32_16x16x32_bf16 v[50:53], v[46:49], v[54:57], v[2:5]
	v_mfma_f32_16x16x32_bf16 v[2:5], v[34:37], v[58:61], 0
	v_mfma_f32_16x16x32_bf16 v[54:57], v[38:41], v[62:65], v[2:5]
	v_mfma_f32_16x16x32_bf16 v[2:5], v[42:45], v[58:61], 0
	v_mfma_f32_16x16x32_bf16 v[58:61], v[46:49], v[62:65], v[2:5]
	v_mfma_f32_16x16x32_bf16 v[2:5], v[34:37], v[66:69], 0
	v_mfma_f32_16x16x32_bf16 v[62:65], v[38:41], v[70:73], v[2:5]
	v_mfma_f32_16x16x32_bf16 v[2:5], v[42:45], v[66:69], 0
	v_mfma_f32_16x16x32_bf16 v[106:109], v[38:41], v[6:9], v[106:109]
	v_mfma_f32_16x16x32_bf16 v[66:69], v[46:49], v[70:73], v[2:5]
	s_barrier
	s_setprio 0
	s_nop 3
	v_lshl_add_u64 v[2:3], s[46:47], 0, v[166:167]
	s_mov_b64 s[26:27], 0x100
	s_mov_b32 m0, s8
	v_lshl_add_u64 v[4:5], v[2:3], 0, s[26:27]
	ds_read_b128 v[70:73], v178 offset:16384
	ds_read_b128 v[118:121], v178 offset:17408
	ds_read_b128 v[122:125], v178 offset:18432
	ds_read_b128 v[126:129], v178 offset:19456
	ds_read_b128 v[130:133], v178 offset:20480
	ds_read_b128 v[134:137], v178 offset:21504
	ds_read_b128 v[138:141], v178 offset:22528
	ds_read_b128 v[142:145], v178 offset:23552
	global_load_lds_dwordx4 v[4:5], off
	v_lshl_add_u64 v[4:5], s[46:47], 0, v[162:163]
	s_add_u32 s20, s46, 0x18100
	v_lshl_add_u64 v[6:7], v[4:5], 0, s[26:27]
	s_mov_b32 m0, s9
	s_addc_u32 s21, s47, 0
	global_load_lds_dwordx4 v[6:7], off
	v_lshl_add_u64 v[6:7], s[20:21], 0, v[166:167]
	s_mov_b32 m0, s14
	s_nop 0
	global_load_lds_dwordx4 v[6:7], off
	v_lshl_add_u64 v[6:7], s[20:21], 0, v[162:163]
	s_mov_b32 m0, s34
	s_nop 0
	global_load_lds_dwordx4 v[6:7], off
	v_lshl_add_u64 v[6:7], s[30:31], 0, v[168:169]
	v_lshl_add_u64 v[8:9], v[6:7], 0, s[26:27]
	s_mov_b32 m0, s1
	s_nop 0
	global_load_lds_dwordx4 v[8:9], off
	v_lshl_add_u64 v[8:9], s[30:31], 0, v[164:165]
	v_lshl_add_u64 v[146:147], v[8:9], 0, s[26:27]
	s_mov_b32 m0, s35
	s_nop 0
	global_load_lds_dwordx4 v[146:147], off
	s_waitcnt vmcnt(8)
	s_waitcnt lgkmcnt(0)
	s_barrier
	s_setprio 1
	s_waitcnt lgkmcnt(0)
	v_mfma_f32_16x16x32_bf16 v[146:149], v[18:21], v[70:73], 0
	v_mfma_f32_16x16x32_bf16 v[154:157], v[18:21], v[122:125], 0
	v_mfma_f32_16x16x32_bf16 v[170:173], v[18:21], v[130:133], 0
	v_mfma_f32_16x16x32_bf16 v[18:21], v[18:21], v[138:141], 0
	v_mfma_f32_16x16x32_bf16 v[180:183], v[22:25], v[142:145], v[18:21]
	v_mfma_f32_16x16x32_bf16 v[18:21], v[26:29], v[138:141], 0
	v_mfma_f32_16x16x32_bf16 v[150:153], v[26:29], v[70:73], 0
	v_mfma_f32_16x16x32_bf16 v[158:161], v[26:29], v[122:125], 0
	v_mfma_f32_16x16x32_bf16 v[174:177], v[26:29], v[130:133], 0
	v_mfma_f32_16x16x32_bf16 v[26:29], v[30:33], v[142:145], v[18:21]
	v_mfma_f32_16x16x32_bf16 v[146:149], v[22:25], v[118:121], v[146:149]
	v_mfma_f32_16x16x32_bf16 v[150:153], v[30:33], v[118:121], v[150:153]
	v_mfma_f32_16x16x32_bf16 v[154:157], v[22:25], v[126:129], v[154:157]
	v_mfma_f32_16x16x32_bf16 v[158:161], v[30:33], v[126:129], v[158:161]
	v_mfma_f32_16x16x32_bf16 v[170:173], v[22:25], v[134:137], v[170:173]
	v_mfma_f32_16x16x32_bf16 v[174:177], v[30:33], v[134:137], v[174:177]
	s_setprio 0
	s_setprio 1
	v_mfma_f32_16x16x32_bf16 v[18:21], v[34:37], v[70:73], 0
	v_mfma_f32_16x16x32_bf16 v[30:33], v[38:41], v[118:121], v[18:21]
	v_mfma_f32_16x16x32_bf16 v[18:21], v[42:45], v[70:73], 0
	v_mfma_f32_16x16x32_bf16 v[70:73], v[46:49], v[118:121], v[18:21]
	v_mfma_f32_16x16x32_bf16 v[18:21], v[34:37], v[122:125], 0
	v_mfma_f32_16x16x32_bf16 v[118:121], v[38:41], v[126:129], v[18:21]
	v_mfma_f32_16x16x32_bf16 v[18:21], v[42:45], v[122:125], 0
	v_mfma_f32_16x16x32_bf16 v[122:125], v[46:49], v[126:129], v[18:21]
	v_mfma_f32_16x16x32_bf16 v[18:21], v[34:37], v[130:133], 0
	v_mfma_f32_16x16x32_bf16 v[126:129], v[38:41], v[134:137], v[18:21]
	v_mfma_f32_16x16x32_bf16 v[18:21], v[42:45], v[130:133], 0
	v_mfma_f32_16x16x32_bf16 v[130:133], v[46:49], v[134:137], v[18:21]
	v_mfma_f32_16x16x32_bf16 v[18:21], v[34:37], v[138:141], 0
	v_mfma_f32_16x16x32_bf16 v[34:37], v[38:41], v[142:145], v[18:21]
	v_mfma_f32_16x16x32_bf16 v[18:21], v[42:45], v[138:141], 0
	v_mfma_f32_16x16x32_bf16 v[38:41], v[46:49], v[142:145], v[18:21]
	s_barrier
; #define PG8_STAGE(bufoff, gbase, voff) do { _Pragma("unroll") for (int _i = 0; _i < 2; ++_i) \
;         __builtin_amdgcn_global_load_lds((const unsigned*)((const char*)(gbase) + (voff)[_i]), (PG8_LAS unsigned*)(lds + (bufoff) + ldsw + _i * 8192), 16, 0, 0); } while (0)
; #define PG8_LDA(dst, b, h) do { _Pragma("unroll") for (int m = 0; m < 4; ++m) _Pragma("unroll") for (int k = 0; k < 2; ++k) dst[m][k] = *(const PG8_LAS bf16x8*)(lds + PG8_SA(b, h) + aoff + m * 2048 + k * 1024); } while (0)
; #define PG8_LDB(dst, b, h) do { _Pragma("unroll") for (int n = 0; n < 2; ++n) _Pragma("unroll") for (int k = 0; k < 2; ++k) dst[n][k] = *(const PG8_LAS bf16x8*)(lds + PG8_SB(b, h) + boff + n * 2048 + k * 1024); } while (0)
; #define PG8_MMA(ai, bj, At, Bt) do { __builtin_amdgcn_s_setprio(1); _Pragma("unroll") for (int m = 0; m < 4; ++m) _Pragma("unroll") for (int n = 0; n < 2; ++n) _Pragma("unroll") for (int k = 0; k < 2; ++k) \
;         acc[ai][bj][m][n] = __builtin_amdgcn_mfma_f32_16x16x32_bf16(Bt[n][k], At[m][k], acc[ai][bj][m][n], 0, 0, 0); __builtin_amdgcn_s_setprio(0); } while (0)
; #define PG8_BAR __builtin_amdgcn_s_barrier()
; template <class Epi, class Sched, bool ALIGN_EPI = false, bool SP2 = false>
; __device__ __forceinline__ void gemm_phase(PG8_LAS unsigned char* lds, const Gemm g, const Sched& S, const Epi& E, const int tid) {
;     ...
;             PG8_LDB(B0, 0, 0); PG8_LDB(B1, 0, 1); PG8_SCHED; PG8_LDA(At, 0, 0); PG8_STAGE(PG8_SA(1, 1), a1 + hstep, voffA);
;             PG8_WAIT_V(8); PG8_WAIT_L(0); PG8_BAR; PG8_MMA(0, 0, At, B0); PG8_MMA(0, 1, At, B1); PG8_BAR; PG8_SCHED;
;             PG8_LDA(At, 0, 1); PG8_STAGE(PG8_SB(0, 0), b2, voffB); PG8_STAGE(PG8_SB(0, 1), b2 + hstep, voffB); PG8_STAGE(PG8_SA(0, 0), a2, voffA);
;             PG8_WAIT_V(8); PG8_WAIT_L(0); PG8_BAR; PG8_MMA(1, 0, At, B0); PG8_MMA(1, 1, At, B1); PG8_BAR; PG8_SCHED;
;             PG8_LDB(B0, 1, 0); PG8_LDB(B1, 1, 1); PG8_SCHED; PG8_LDA(At, 1, 0); PG8_STAGE(PG8_SA(0, 1), a2 + hstep, voffA);
;             PG8_WAIT_V(8); PG8_WAIT_L(0); PG8_BAR; PG8_MMA(0, 0, At, B0); PG8_MMA(0, 1, At, B1); PG8_BAR; PG8_SCHED;
;             PG8_LDA(At, 1, 1); PG8_STAGE(PG8_SB(1, 0), b3, voffB); PG8_STAGE(PG8_SB(1, 1), b3 + hstep, voffB); PG8_STAGE(PG8_SA(1, 0), a3, voffA);
;             PG8_WAIT_V(8); PG8_WAIT_L(0); PG8_BAR; PG8_MMA(1, 0, At, B0); PG8_MMA(1, 1, At, B1); PG8_BAR; PG8_SCHED;
	s_setprio 0
	v_or_b32_e32 v17, 0x18000, v179
	s_nop 3
	v_add_u32_e32 v19, 0x18800, v179
	v_or_b32_e32 v21, 0x1c000, v179
	v_add_u32_e32 v23, 0x1c800, v179
	v_add_u32_e32 v18, 0x18400, v179
	ds_read_b128 v[42:45], v17
	ds_read_b128 v[46:49], v18
	v_add_u32_e32 v20, 0x18c00, v179
	ds_read_b128 v[134:137], v19
	ds_read_b128 v[138:141], v20
	v_add_u32_e32 v22, 0x1c400, v179
	ds_read_b128 v[142:145], v21
	ds_read_b128 v[184:187], v22
	v_add_u32_e32 v24, 0x1cc00, v179
	ds_read_b128 v[188:191], v23
	ds_read_b128 v[192:195], v24
	s_add_u32 s20, s30, 0x18100
	s_addc_u32 s21, s31, 0
	s_mov_b32 m0, s84
	v_lshl_add_u64 v[208:209], s[20:21], 0, v[168:169]
	ds_read_b128 v[196:199], v178 offset:32768
	ds_read_b128 v[200:203], v178 offset:33792
	ds_read_b128 v[204:207], v178 offset:34816
	ds_read_b128 v[214:217], v178 offset:35840
	ds_read_b128 v[218:221], v178 offset:36864
	ds_read_b128 v[222:225], v178 offset:37888
	ds_read_b128 v[226:229], v178 offset:38912
	ds_read_b128 v[230:233], v178 offset:39936
	global_load_lds_dwordx4 v[208:209], off
	v_lshl_add_u64 v[208:209], s[20:21], 0, v[164:165]
	s_mov_b32 m0, s85
	s_nop 0
	global_load_lds_dwordx4 v[208:209], off
	s_waitcnt vmcnt(8)
	s_waitcnt lgkmcnt(0)
	s_barrier
	s_setprio 1
	s_waitcnt lgkmcnt(0)
	v_mfma_f32_16x16x32_bf16 v[74:77], v[42:45], v[196:199], v[74:77]
	v_mfma_f32_16x16x32_bf16 v[78:81], v[134:137], v[196:199], v[78:81]
	v_mfma_f32_16x16x32_bf16 v[82:85], v[42:45], v[204:207], v[82:85]
	v_mfma_f32_16x16x32_bf16 v[86:89], v[134:137], v[204:207], v[86:89]
	v_mfma_f32_16x16x32_bf16 v[90:93], v[42:45], v[218:221], v[90:93]
	v_mfma_f32_16x16x32_bf16 v[94:97], v[134:137], v[218:221], v[94:97]
	v_mfma_f32_16x16x32_bf16 v[98:101], v[42:45], v[226:229], v[98:101]
	v_mfma_f32_16x16x32_bf16 v[102:105], v[134:137], v[226:229], v[102:105]
	v_mfma_f32_16x16x32_bf16 v[74:77], v[46:49], v[200:203], v[74:77]
	v_mfma_f32_16x16x32_bf16 v[78:81], v[138:141], v[200:203], v[78:81]
	v_mfma_f32_16x16x32_bf16 v[82:85], v[46:49], v[214:217], v[82:85]
	v_mfma_f32_16x16x32_bf16 v[86:89], v[138:141], v[214:217], v[86:89]
	v_mfma_f32_16x16x32_bf16 v[90:93], v[46:49], v[222:225], v[90:93]
	v_mfma_f32_16x16x32_bf16 v[94:97], v[138:141], v[222:225], v[94:97]
	v_mfma_f32_16x16x32_bf16 v[98:101], v[46:49], v[230:233], v[98:101]
	v_mfma_f32_16x16x32_bf16 v[102:105], v[138:141], v[230:233], v[102:105]
	s_setprio 0
	s_setprio 1
	v_mfma_f32_16x16x32_bf16 v[106:109], v[142:145], v[196:199], v[106:109]
	v_mfma_f32_16x16x32_bf16 v[110:113], v[188:191], v[196:199], v[110:113]
	v_mfma_f32_16x16x32_bf16 v[114:117], v[142:145], v[204:207], v[114:117]
	v_mfma_f32_16x16x32_bf16 v[50:53], v[188:191], v[204:207], v[50:53]
	v_mfma_f32_16x16x32_bf16 v[54:57], v[142:145], v[218:221], v[54:57]
	v_mfma_f32_16x16x32_bf16 v[58:61], v[188:191], v[218:221], v[58:61]
	v_mfma_f32_16x16x32_bf16 v[62:65], v[142:145], v[226:229], v[62:65]
	v_mfma_f32_16x16x32_bf16 v[66:69], v[188:191], v[226:229], v[66:69]
	v_mfma_f32_16x16x32_bf16 v[106:109], v[184:187], v[200:203], v[106:109]
	v_mfma_f32_16x16x32_bf16 v[110:113], v[192:195], v[200:203], v[110:113]
	v_mfma_f32_16x16x32_bf16 v[114:117], v[184:187], v[214:217], v[114:117]
	v_mfma_f32_16x16x32_bf16 v[50:53], v[192:195], v[214:217], v[50:53]
	v_mfma_f32_16x16x32_bf16 v[54:57], v[184:187], v[222:225], v[54:57]
	v_mfma_f32_16x16x32_bf16 v[58:61], v[192:195], v[222:225], v[58:61]
	v_mfma_f32_16x16x32_bf16 v[62:65], v[184:187], v[230:233], v[62:65]
	v_mfma_f32_16x16x32_bf16 v[66:69], v[192:195], v[230:233], v[66:69]
	s_barrier
	s_setprio 0
	s_mov_b64 s[26:27], 0x180
	s_mov_b32 m0, s88
	v_lshl_add_u64 v[208:209], v[2:3], 0, s[26:27]
	s_add_u32 s20, s46, 0x18180
	ds_read_b128 v[196:199], v178 offset:49152
	ds_read_b128 v[200:203], v178 offset:50176
	ds_read_b128 v[204:207], v178 offset:51200
	ds_read_b128 v[214:217], v178 offset:52224
	ds_read_b128 v[218:221], v178 offset:53248
	ds_read_b128 v[222:225], v178 offset:54272
	ds_read_b128 v[226:229], v178 offset:55296
	ds_read_b128 v[230:233], v178 offset:56320
	global_load_lds_dwordx4 v[208:209], off
	v_lshl_add_u64 v[208:209], v[4:5], 0, s[26:27]
	s_mov_b32 m0, s89
	s_addc_u32 s21, s47, 0
	global_load_lds_dwordx4 v[208:209], off
	v_lshl_add_u64 v[208:209], s[20:21], 0, v[166:167]
	s_mov_b32 m0, s28
	s_nop 0
	global_load_lds_dwordx4 v[208:209], off
	v_lshl_add_u64 v[208:209], s[20:21], 0, v[162:163]
	s_mov_b32 m0, s29
	s_nop 0
	global_load_lds_dwordx4 v[208:209], off
	v_lshl_add_u64 v[208:209], v[6:7], 0, s[26:27]
	s_mov_b32 m0, s90
	s_nop 0
	global_load_lds_dwordx4 v[208:209], off
	v_lshl_add_u64 v[208:209], v[8:9], 0, s[26:27]
	s_mov_b32 m0, s91
	s_nop 0
	global_load_lds_dwordx4 v[208:209], off
	s_waitcnt vmcnt(8)
	s_waitcnt lgkmcnt(0)
	s_barrier
; #define PG8_STAGE(bufoff, gbase, voff) do { _Pragma("unroll") for (int _i = 0; _i < 2; ++_i) \
;         __builtin_amdgcn_global_load_lds((const unsigned*)((const char*)(gbase) + (voff)[_i]), (PG8_LAS unsigned*)(lds + (bufoff) + ldsw + _i * 8192), 16, 0, 0); } while (0)
; #define PG8_LDA(dst, b, h) do { _Pragma("unroll") for (int m = 0; m < 4; ++m) _Pragma("unroll") for (int k = 0; k < 2; ++k) dst[m][k] = *(const PG8_LAS bf16x8*)(lds + PG8_SA(b, h) + aoff + m * 2048 + k * 1024); } while (0)
; #define PG8_LDB(dst, b, h) do { _Pragma("unroll") for (int n = 0; n < 2; ++n) _Pragma("unroll") for (int k = 0; k < 2; ++k) dst[n][k] = *(const PG8_LAS bf16x8*)(lds + PG8_SB(b, h) + boff + n * 2048 + k * 1024); } while (0)
; #define PG8_MMA(ai, bj, At, Bt) do { __builtin_amdgcn_s_setprio(1); _Pragma("unroll") for (int m = 0; m < 4; ++m) _Pragma("unroll") for (int n = 0; n < 2; ++n) _Pragma("unroll") for (int k = 0; k < 2; ++k) \
;         acc[ai][bj][m][n] = __builtin_amdgcn_mfma_f32_16x16x32_bf16(Bt[n][k], At[m][k], acc[ai][bj][m][n], 0, 0, 0); __builtin_amdgcn_s_setprio(0); } while (0)
; #define PG8_BAR __builtin_amdgcn_s_barrier()
; template <class Epi, class Sched, bool ALIGN_EPI = false, bool SP2 = false>
; __device__ __forceinline__ void gemm_phase(PG8_LAS unsigned char* lds, const Gemm g, const Sched& S, const Epi& E, const int tid) {
;     ...
;             PG8_LDB(B0, 0, 0); PG8_LDB(B1, 0, 1); PG8_SCHED; PG8_LDA(At, 0, 0); PG8_STAGE(PG8_SA(1, 1), a1 + hstep, voffA);
;             PG8_WAIT_V(8); PG8_WAIT_L(0); PG8_BAR; PG8_MMA(0, 0, At, B0); PG8_MMA(0, 1, At, B1); PG8_BAR; PG8_SCHED;
;             PG8_LDA(At, 0, 1); PG8_STAGE(PG8_SB(0, 0), b2, voffB); PG8_STAGE(PG8_SB(0, 1), b2 + hstep, voffB); PG8_STAGE(PG8_SA(0, 0), a2, voffA);
;             PG8_WAIT_V(8); PG8_WAIT_L(0); PG8_BAR; PG8_MMA(1, 0, At, B0); PG8_MMA(1, 1, At, B1); PG8_BAR; PG8_SCHED;
;             PG8_LDB(B0, 1, 0); PG8_LDB(B1, 1, 1); PG8_SCHED; PG8_LDA(At, 1, 0); PG8_STAGE(PG8_SA(0, 1), a2 + hstep, voffA);
;             PG8_WAIT_V(8); PG8_WAIT_L(0); PG8_BAR; PG8_MMA(0, 0, At, B0); PG8_MMA(0, 1, At, B1); PG8_BAR; PG8_SCHED;
;             PG8_LDA(At, 1, 1); PG8_STAGE(PG8_SB(1, 0), b3, voffB); PG8_STAGE(PG8_SB(1, 1), b3 + hstep, voffB); PG8_STAGE(PG8_SA(1, 0), a3, voffA);
;             PG8_WAIT_V(8); PG8_WAIT_L(0); PG8_BAR; PG8_MMA(1, 0, At, B0); PG8_MMA(1, 1, At, B1); PG8_BAR; PG8_SCHED;
	s_setprio 1
	s_waitcnt lgkmcnt(0)
	v_mfma_f32_16x16x32_bf16 v[146:149], v[42:45], v[196:199], v[146:149]
	v_mfma_f32_16x16x32_bf16 v[154:157], v[42:45], v[204:207], v[154:157]
	v_mfma_f32_16x16x32_bf16 v[170:173], v[42:45], v[218:221], v[170:173]
	v_mfma_f32_16x16x32_bf16 v[42:45], v[42:45], v[226:229], v[180:183]
	v_mfma_f32_16x16x32_bf16 v[26:29], v[134:137], v[226:229], v[26:29]
	v_mfma_f32_16x16x32_bf16 v[150:153], v[134:137], v[196:199], v[150:153]
	v_mfma_f32_16x16x32_bf16 v[158:161], v[134:137], v[204:207], v[158:161]
	v_mfma_f32_16x16x32_bf16 v[174:177], v[134:137], v[218:221], v[174:177]
	v_mfma_f32_16x16x32_bf16 v[42:45], v[46:49], v[230:233], v[42:45]
	v_mfma_f32_16x16x32_bf16 v[26:29], v[138:141], v[230:233], v[26:29]
	v_mfma_f32_16x16x32_bf16 v[146:149], v[46:49], v[200:203], v[146:149]
	v_mfma_f32_16x16x32_bf16 v[150:153], v[138:141], v[200:203], v[150:153]
	v_mfma_f32_16x16x32_bf16 v[154:157], v[46:49], v[214:217], v[154:157]
	v_mfma_f32_16x16x32_bf16 v[158:161], v[138:141], v[214:217], v[158:161]
	v_mfma_f32_16x16x32_bf16 v[170:173], v[46:49], v[222:225], v[170:173]
	v_mfma_f32_16x16x32_bf16 v[174:177], v[138:141], v[222:225], v[174:177]
	s_setprio 0
	s_setprio 1
	v_mfma_f32_16x16x32_bf16 v[30:33], v[142:145], v[196:199], v[30:33]
	v_mfma_f32_16x16x32_bf16 v[46:49], v[188:191], v[196:199], v[70:73]
	v_mfma_f32_16x16x32_bf16 v[70:73], v[142:145], v[204:207], v[118:121]
	v_mfma_f32_16x16x32_bf16 v[118:121], v[188:191], v[204:207], v[122:125]
	v_mfma_f32_16x16x32_bf16 v[122:125], v[142:145], v[218:221], v[126:129]
	v_mfma_f32_16x16x32_bf16 v[126:129], v[188:191], v[218:221], v[130:133]
	v_mfma_f32_16x16x32_bf16 v[34:37], v[142:145], v[226:229], v[34:37]
	v_mfma_f32_16x16x32_bf16 v[38:41], v[188:191], v[226:229], v[38:41]
	v_mfma_f32_16x16x32_bf16 v[30:33], v[184:187], v[200:203], v[30:33]
	v_mfma_f32_16x16x32_bf16 v[46:49], v[192:195], v[200:203], v[46:49]
	v_mfma_f32_16x16x32_bf16 v[70:73], v[184:187], v[214:217], v[70:73]
	v_mfma_f32_16x16x32_bf16 v[118:121], v[192:195], v[214:217], v[118:121]
	v_mfma_f32_16x16x32_bf16 v[122:125], v[184:187], v[222:225], v[122:125]
	v_mfma_f32_16x16x32_bf16 v[126:129], v[192:195], v[222:225], v[126:129]
	v_mfma_f32_16x16x32_bf16 v[34:37], v[184:187], v[230:233], v[34:37]
	v_mfma_f32_16x16x32_bf16 v[38:41], v[192:195], v[230:233], v[38:41]
	s_barrier
	s_setprio 0
	ds_read_b128 v[130:133], v0
	ds_read_b128 v[134:137], v10
	ds_read_b128 v[138:141], v11
	ds_read_b128 v[142:145], v12
	ds_read_b128 v[180:183], v13
	ds_read_b128 v[184:187], v14
	ds_read_b128 v[188:191], v15
	ds_read_b128 v[192:195], v16
	s_add_u32 s20, s30, 0x18180
	s_addc_u32 s21, s31, 0
	s_mov_b32 m0, s5
	v_lshl_add_u64 v[208:209], s[20:21], 0, v[168:169]
	ds_read_b128 v[196:199], v178
	ds_read_b128 v[200:203], v178 offset:1024
	ds_read_b128 v[204:207], v178 offset:2048
	ds_read_b128 v[214:217], v178 offset:3072
	ds_read_b128 v[218:221], v178 offset:4096
	ds_read_b128 v[222:225], v178 offset:5120
	ds_read_b128 v[226:229], v178 offset:6144
	ds_read_b128 v[230:233], v178 offset:7168
	global_load_lds_dwordx4 v[208:209], off
	v_lshl_add_u64 v[208:209], s[20:21], 0, v[164:165]
	s_mov_b32 m0, s4
	s_nop 0
	global_load_lds_dwordx4 v[208:209], off
	s_waitcnt vmcnt(8)
	s_waitcnt lgkmcnt(0)
	s_barrier
	s_setprio 1
	s_waitcnt lgkmcnt(0)
	v_mfma_f32_16x16x32_bf16 v[74:77], v[130:133], v[196:199], v[74:77]
	v_mfma_f32_16x16x32_bf16 v[78:81], v[138:141], v[196:199], v[78:81]
	v_mfma_f32_16x16x32_bf16 v[82:85], v[130:133], v[204:207], v[82:85]
	v_mfma_f32_16x16x32_bf16 v[86:89], v[138:141], v[204:207], v[86:89]
	v_mfma_f32_16x16x32_bf16 v[90:93], v[130:133], v[218:221], v[90:93]
	v_mfma_f32_16x16x32_bf16 v[94:97], v[138:141], v[218:221], v[94:97]
	v_mfma_f32_16x16x32_bf16 v[98:101], v[130:133], v[226:229], v[98:101]
	v_mfma_f32_16x16x32_bf16 v[102:105], v[138:141], v[226:229], v[102:105]
	v_mfma_f32_16x16x32_bf16 v[74:77], v[134:137], v[200:203], v[74:77]
	v_mfma_f32_16x16x32_bf16 v[78:81], v[142:145], v[200:203], v[78:81]
	v_mfma_f32_16x16x32_bf16 v[82:85], v[134:137], v[214:217], v[82:85]
	v_mfma_f32_16x16x32_bf16 v[86:89], v[142:145], v[214:217], v[86:89]
	v_mfma_f32_16x16x32_bf16 v[90:93], v[134:137], v[222:225], v[90:93]
	v_mfma_f32_16x16x32_bf16 v[94:97], v[142:145], v[222:225], v[94:97]
	v_mfma_f32_16x16x32_bf16 v[98:101], v[134:137], v[230:233], v[98:101]
	v_mfma_f32_16x16x32_bf16 v[102:105], v[142:145], v[230:233], v[102:105]
	s_setprio 0
	s_setprio 1
	v_mfma_f32_16x16x32_bf16 v[106:109], v[180:183], v[196:199], v[106:109]
	v_mfma_f32_16x16x32_bf16 v[110:113], v[188:191], v[196:199], v[110:113]
	v_mfma_f32_16x16x32_bf16 v[114:117], v[180:183], v[204:207], v[114:117]
	v_mfma_f32_16x16x32_bf16 v[50:53], v[188:191], v[204:207], v[50:53]
	v_mfma_f32_16x16x32_bf16 v[54:57], v[180:183], v[218:221], v[54:57]
	v_mfma_f32_16x16x32_bf16 v[58:61], v[188:191], v[218:221], v[58:61]
	v_mfma_f32_16x16x32_bf16 v[62:65], v[180:183], v[226:229], v[62:65]
	v_mfma_f32_16x16x32_bf16 v[66:69], v[188:191], v[226:229], v[66:69]
	v_mfma_f32_16x16x32_bf16 v[106:109], v[184:187], v[200:203], v[106:109]
	v_mfma_f32_16x16x32_bf16 v[110:113], v[192:195], v[200:203], v[110:113]
	v_mfma_f32_16x16x32_bf16 v[114:117], v[184:187], v[214:217], v[114:117]
	v_mfma_f32_16x16x32_bf16 v[50:53], v[192:195], v[214:217], v[50:53]
	v_mfma_f32_16x16x32_bf16 v[54:57], v[184:187], v[222:225], v[54:57]
	v_mfma_f32_16x16x32_bf16 v[58:61], v[192:195], v[222:225], v[58:61]
	v_mfma_f32_16x16x32_bf16 v[62:65], v[184:187], v[230:233], v[62:65]
	v_mfma_f32_16x16x32_bf16 v[66:69], v[192:195], v[230:233], v[66:69]
	s_barrier
; #define PG8_STAGE(bufoff, gbase, voff) do { _Pragma("unroll") for (int _i = 0; _i < 2; ++_i) \
;         __builtin_amdgcn_global_load_lds((const unsigned*)((const char*)(gbase) + (voff)[_i]), (PG8_LAS unsigned*)(lds + (bufoff) + ldsw + _i * 8192), 16, 0, 0); } while (0)
; #define PG8_LDA(dst, b, h) do { _Pragma("unroll") for (int m = 0; m < 4; ++m) _Pragma("unroll") for (int k = 0; k < 2; ++k) dst[m][k] = *(const PG8_LAS bf16x8*)(lds + PG8_SA(b, h) + aoff + m * 2048 + k * 1024); } while (0)
; #define PG8_LDB(dst, b, h) do { _Pragma("unroll") for (int n = 0; n < 2; ++n) _Pragma("unroll") for (int k = 0; k < 2; ++k) dst[n][k] = *(const PG8_LAS bf16x8*)(lds + PG8_SB(b, h) + boff + n * 2048 + k * 1024); } while (0)
; #define PG8_MMA(ai, bj, At, Bt) do { __builtin_amdgcn_s_setprio(1); _Pragma("unroll") for (int m = 0; m < 4; ++m) _Pragma("unroll") for (int n = 0; n < 2; ++n) _Pragma("unroll") for (int k = 0; k < 2; ++k) \
;         acc[ai][bj][m][n] = __builtin_amdgcn_mfma_f32_16x16x32_bf16(Bt[n][k], At[m][k], acc[ai][bj][m][n], 0, 0, 0); __builtin_amdgcn_s_setprio(0); } while (0)
; #define PG8_BAR __builtin_amdgcn_s_barrier()
; template <class Epi, class Sched, bool ALIGN_EPI = false, bool SP2 = false>
; __device__ __forceinline__ void gemm_phase(PG8_LAS unsigned char* lds, const Gemm g, const Sched& S, const Epi& E, const int tid) {
;     ...
;             PG8_LDB(B0, 0, 0); PG8_LDB(B1, 0, 1); PG8_SCHED; PG8_LDA(At, 0, 0); PG8_STAGE(PG8_SA(1, 1), a1 + hstep, voffA);
;             PG8_WAIT_V(8); PG8_WAIT_L(0); PG8_BAR; PG8_MMA(0, 0, At, B0); PG8_MMA(0, 1, At, B1); PG8_BAR; PG8_SCHED;
;             PG8_LDA(At, 0, 1); PG8_STAGE(PG8_SB(0, 0), b2, voffB); PG8_STAGE(PG8_SB(0, 1), b2 + hstep, voffB); PG8_STAGE(PG8_SA(0, 0), a2, voffA);
;             PG8_WAIT_V(8); PG8_WAIT_L(0); PG8_BAR; PG8_MMA(1, 0, At, B0); PG8_MMA(1, 1, At, B1); PG8_BAR; PG8_SCHED;
;             PG8_LDB(B0, 1, 0); PG8_LDB(B1, 1, 1); PG8_SCHED; PG8_LDA(At, 1, 0); PG8_STAGE(PG8_SA(0, 1), a2 + hstep, voffA);
;             PG8_WAIT_V(8); PG8_WAIT_L(0); PG8_BAR; PG8_MMA(0, 0, At, B0); PG8_MMA(0, 1, At, B1); PG8_BAR; PG8_SCHED;
;             PG8_LDA(At, 1, 1); PG8_STAGE(PG8_SB(1, 0), b3, voffB); PG8_STAGE(PG8_SB(1, 1), b3 + hstep, voffB); PG8_STAGE(PG8_SA(1, 0), a3, voffA);
;             PG8_WAIT_V(8); PG8_WAIT_L(0); PG8_BAR; PG8_MMA(1, 0, At, B0); PG8_MMA(1, 1, At, B1); PG8_BAR; PG8_SCHED;
	s_setprio 0
	s_mov_b64 s[26:27], 0x200
	s_mov_b32 m0, s8
	v_lshl_add_u64 v[208:209], v[2:3], 0, s[26:27]
	s_add_u32 s20, s46, 0x18200
	ds_read_b128 v[196:199], v178 offset:16384
	ds_read_b128 v[200:203], v178 offset:17408
	ds_read_b128 v[204:207], v178 offset:18432
	ds_read_b128 v[214:217], v178 offset:19456
	ds_read_b128 v[218:221], v178 offset:20480
	ds_read_b128 v[222:225], v178 offset:21504
	ds_read_b128 v[226:229], v178 offset:22528
	ds_read_b128 v[230:233], v178 offset:23552
	global_load_lds_dwordx4 v[208:209], off
	v_lshl_add_u64 v[208:209], v[4:5], 0, s[26:27]
	s_mov_b32 m0, s9
	s_addc_u32 s21, s47, 0
	global_load_lds_dwordx4 v[208:209], off
	v_lshl_add_u64 v[208:209], s[20:21], 0, v[166:167]
	s_mov_b32 m0, s14
	s_nop 0
	global_load_lds_dwordx4 v[208:209], off
	v_lshl_add_u64 v[208:209], s[20:21], 0, v[162:163]
	s_mov_b32 m0, s34
	s_nop 0
	global_load_lds_dwordx4 v[208:209], off
	v_lshl_add_u64 v[208:209], v[6:7], 0, s[26:27]
	s_mov_b32 m0, s1
	s_nop 0
	global_load_lds_dwordx4 v[208:209], off
	v_lshl_add_u64 v[208:209], v[8:9], 0, s[26:27]
	s_mov_b32 m0, s35
	s_nop 0
	global_load_lds_dwordx4 v[208:209], off
	s_waitcnt vmcnt(8)
	s_waitcnt lgkmcnt(0)
	s_barrier
	s_setprio 1
	s_waitcnt lgkmcnt(0)
	v_mfma_f32_16x16x32_bf16 v[42:45], v[130:133], v[226:229], v[42:45]
	v_mfma_f32_16x16x32_bf16 v[26:29], v[138:141], v[226:229], v[26:29]
	v_mfma_f32_16x16x32_bf16 v[146:149], v[130:133], v[196:199], v[146:149]
	v_mfma_f32_16x16x32_bf16 v[150:153], v[138:141], v[196:199], v[150:153]
	v_mfma_f32_16x16x32_bf16 v[154:157], v[130:133], v[204:207], v[154:157]
	v_mfma_f32_16x16x32_bf16 v[158:161], v[138:141], v[204:207], v[158:161]
	v_mfma_f32_16x16x32_bf16 v[170:173], v[130:133], v[218:221], v[170:173]
	v_mfma_f32_16x16x32_bf16 v[174:177], v[138:141], v[218:221], v[174:177]
	v_mfma_f32_16x16x32_bf16 v[42:45], v[134:137], v[230:233], v[42:45]
	v_mfma_f32_16x16x32_bf16 v[26:29], v[142:145], v[230:233], v[26:29]
	v_mfma_f32_16x16x32_bf16 v[146:149], v[134:137], v[200:203], v[146:149]
	v_mfma_f32_16x16x32_bf16 v[150:153], v[142:145], v[200:203], v[150:153]
	v_mfma_f32_16x16x32_bf16 v[154:157], v[134:137], v[214:217], v[154:157]
	v_mfma_f32_16x16x32_bf16 v[158:161], v[142:145], v[214:217], v[158:161]
	v_mfma_f32_16x16x32_bf16 v[170:173], v[134:137], v[222:225], v[170:173]
	v_mfma_f32_16x16x32_bf16 v[174:177], v[142:145], v[222:225], v[174:177]
	s_setprio 0
	s_setprio 1
	v_mfma_f32_16x16x32_bf16 v[30:33], v[180:183], v[196:199], v[30:33]
	v_mfma_f32_16x16x32_bf16 v[46:49], v[188:191], v[196:199], v[46:49]
	v_mfma_f32_16x16x32_bf16 v[70:73], v[180:183], v[204:207], v[70:73]
	v_mfma_f32_16x16x32_bf16 v[118:121], v[188:191], v[204:207], v[118:121]
	v_mfma_f32_16x16x32_bf16 v[122:125], v[180:183], v[218:221], v[122:125]
	v_mfma_f32_16x16x32_bf16 v[126:129], v[188:191], v[218:221], v[126:129]
	v_mfma_f32_16x16x32_bf16 v[34:37], v[180:183], v[226:229], v[34:37]
	v_mfma_f32_16x16x32_bf16 v[38:41], v[188:191], v[226:229], v[38:41]
	v_mfma_f32_16x16x32_bf16 v[30:33], v[184:187], v[200:203], v[30:33]
	v_mfma_f32_16x16x32_bf16 v[46:49], v[192:195], v[200:203], v[46:49]
	v_mfma_f32_16x16x32_bf16 v[70:73], v[184:187], v[214:217], v[70:73]
	v_mfma_f32_16x16x32_bf16 v[118:121], v[192:195], v[214:217], v[118:121]
	v_mfma_f32_16x16x32_bf16 v[122:125], v[184:187], v[222:225], v[122:125]
	v_mfma_f32_16x16x32_bf16 v[126:129], v[192:195], v[222:225], v[126:129]
	v_mfma_f32_16x16x32_bf16 v[34:37], v[184:187], v[230:233], v[34:37]
	v_mfma_f32_16x16x32_bf16 v[38:41], v[192:195], v[230:233], v[38:41]
	s_barrier
	s_setprio 0
	ds_read_b128 v[130:133], v17
	ds_read_b128 v[134:137], v18
	ds_read_b128 v[138:141], v19
	ds_read_b128 v[142:145], v20
	ds_read_b128 v[180:183], v21
	ds_read_b128 v[184:187], v22
	ds_read_b128 v[188:191], v23
	ds_read_b128 v[192:195], v24
	s_add_u32 s20, s30, 0x18200
	s_addc_u32 s21, s31, 0
	s_mov_b32 m0, s84
	v_lshl_add_u64 v[208:209], s[20:21], 0, v[168:169]
	ds_read_b128 v[196:199], v178 offset:32768
	ds_read_b128 v[200:203], v178 offset:33792
	ds_read_b128 v[204:207], v178 offset:34816
	ds_read_b128 v[214:217], v178 offset:35840
	ds_read_b128 v[218:221], v178 offset:36864
	ds_read_b128 v[222:225], v178 offset:37888
	ds_read_b128 v[226:229], v178 offset:38912
	ds_read_b128 v[230:233], v178 offset:39936
	global_load_lds_dwordx4 v[208:209], off
	v_lshl_add_u64 v[208:209], s[20:21], 0, v[164:165]
	s_mov_b32 m0, s85
	s_nop 0
	global_load_lds_dwordx4 v[208:209], off
	s_waitcnt vmcnt(8)
	s_waitcnt lgkmcnt(0)
	s_barrier
; #define PG8_STAGE(bufoff, gbase, voff) do { _Pragma("unroll") for (int _i = 0; _i < 2; ++_i) \
;         __builtin_amdgcn_global_load_lds((const unsigned*)((const char*)(gbase) + (voff)[_i]), (PG8_LAS unsigned*)(lds + (bufoff) + ldsw + _i * 8192), 16, 0, 0); } while (0)
; #define PG8_LDA(dst, b, h) do { _Pragma("unroll") for (int m = 0; m < 4; ++m) _Pragma("unroll") for (int k = 0; k < 2; ++k) dst[m][k] = *(const PG8_LAS bf16x8*)(lds + PG8_SA(b, h) + aoff + m * 2048 + k * 1024); } while (0)
; #define PG8_LDB(dst, b, h) do { _Pragma("unroll") for (int n = 0; n < 2; ++n) _Pragma("unroll") for (int k = 0; k < 2; ++k) dst[n][k] = *(const PG8_LAS bf16x8*)(lds + PG8_SB(b, h) + boff + n * 2048 + k * 1024); } while (0)
; #define PG8_MMA(ai, bj, At, Bt) do { __builtin_amdgcn_s_setprio(1); _Pragma("unroll") for (int m = 0; m < 4; ++m) _Pragma("unroll") for (int n = 0; n < 2; ++n) _Pragma("unroll") for (int k = 0; k < 2; ++k) \
;         acc[ai][bj][m][n] = __builtin_amdgcn_mfma_f32_16x16x32_bf16(Bt[n][k], At[m][k], acc[ai][bj][m][n], 0, 0, 0); __builtin_amdgcn_s_setprio(0); } while (0)
; #define PG8_BAR __builtin_amdgcn_s_barrier()
; template <class Epi, class Sched, bool ALIGN_EPI = false, bool SP2 = false>
; __device__ __forceinline__ void gemm_phase(PG8_LAS unsigned char* lds, const Gemm g, const Sched& S, const Epi& E, const int tid) {
;     ...
;             PG8_LDB(B0, 0, 0); PG8_LDB(B1, 0, 1); PG8_SCHED; PG8_LDA(At, 0, 0); PG8_STAGE(PG8_SA(1, 1), a1 + hstep, voffA);
;             PG8_WAIT_V(8); PG8_WAIT_L(0); PG8_BAR; PG8_MMA(0, 0, At, B0); PG8_MMA(0, 1, At, B1); PG8_BAR; PG8_SCHED;
;             PG8_LDA(At, 0, 1); PG8_STAGE(PG8_SB(0, 0), b2, voffB); PG8_STAGE(PG8_SB(0, 1), b2 + hstep, voffB); PG8_STAGE(PG8_SA(0, 0), a2, voffA);
;             PG8_WAIT_V(8); PG8_WAIT_L(0); PG8_BAR; PG8_MMA(1, 0, At, B0); PG8_MMA(1, 1, At, B1); PG8_BAR; PG8_SCHED;
;             PG8_LDB(B0, 1, 0); PG8_LDB(B1, 1, 1); PG8_SCHED; PG8_LDA(At, 1, 0); PG8_STAGE(PG8_SA(0, 1), a2 + hstep, voffA);
;             PG8_WAIT_V(8); PG8_WAIT_L(0); PG8_BAR; PG8_MMA(0, 0, At, B0); PG8_MMA(0, 1, At, B1); PG8_BAR; PG8_SCHED;
;             PG8_LDA(At, 1, 1); PG8_STAGE(PG8_SB(1, 0), b3, voffB); PG8_STAGE(PG8_SB(1, 1), b3 + hstep, voffB); PG8_STAGE(PG8_SA(1, 0), a3, voffA);
;             PG8_WAIT_V(8); PG8_WAIT_L(0); PG8_BAR; PG8_MMA(1, 0, At, B0); PG8_MMA(1, 1, At, B1); PG8_BAR; PG8_SCHED;
	s_setprio 1
	s_waitcnt lgkmcnt(0)
	v_mfma_f32_16x16x32_bf16 v[74:77], v[130:133], v[196:199], v[74:77]
	v_mfma_f32_16x16x32_bf16 v[78:81], v[138:141], v[196:199], v[78:81]
	v_mfma_f32_16x16x32_bf16 v[82:85], v[130:133], v[204:207], v[82:85]
	v_mfma_f32_16x16x32_bf16 v[86:89], v[138:141], v[204:207], v[86:89]
	v_mfma_f32_16x16x32_bf16 v[90:93], v[130:133], v[218:221], v[90:93]
	v_mfma_f32_16x16x32_bf16 v[94:97], v[138:141], v[218:221], v[94:97]
	v_mfma_f32_16x16x32_bf16 v[98:101], v[130:133], v[226:229], v[98:101]
	v_mfma_f32_16x16x32_bf16 v[102:105], v[138:141], v[226:229], v[102:105]
	v_mfma_f32_16x16x32_bf16 v[74:77], v[134:137], v[200:203], v[74:77]
	v_mfma_f32_16x16x32_bf16 v[78:81], v[142:145], v[200:203], v[78:81]
	v_mfma_f32_16x16x32_bf16 v[82:85], v[134:137], v[214:217], v[82:85]
	v_mfma_f32_16x16x32_bf16 v[86:89], v[142:145], v[214:217], v[86:89]
	v_mfma_f32_16x16x32_bf16 v[90:93], v[134:137], v[222:225], v[90:93]
	v_mfma_f32_16x16x32_bf16 v[94:97], v[142:145], v[222:225], v[94:97]
	v_mfma_f32_16x16x32_bf16 v[98:101], v[134:137], v[230:233], v[98:101]
	v_mfma_f32_16x16x32_bf16 v[102:105], v[142:145], v[230:233], v[102:105]
	s_setprio 0
	s_setprio 1
	v_mfma_f32_16x16x32_bf16 v[106:109], v[180:183], v[196:199], v[106:109]
	v_mfma_f32_16x16x32_bf16 v[110:113], v[188:191], v[196:199], v[110:113]
	v_mfma_f32_16x16x32_bf16 v[114:117], v[180:183], v[204:207], v[114:117]
	v_mfma_f32_16x16x32_bf16 v[50:53], v[188:191], v[204:207], v[50:53]
	v_mfma_f32_16x16x32_bf16 v[54:57], v[180:183], v[218:221], v[54:57]
	v_mfma_f32_16x16x32_bf16 v[58:61], v[188:191], v[218:221], v[58:61]
	v_mfma_f32_16x16x32_bf16 v[62:65], v[180:183], v[226:229], v[62:65]
	v_mfma_f32_16x16x32_bf16 v[66:69], v[188:191], v[226:229], v[66:69]
	v_mfma_f32_16x16x32_bf16 v[106:109], v[184:187], v[200:203], v[106:109]
	v_mfma_f32_16x16x32_bf16 v[110:113], v[192:195], v[200:203], v[110:113]
	v_mfma_f32_16x16x32_bf16 v[114:117], v[184:187], v[214:217], v[114:117]
	v_mfma_f32_16x16x32_bf16 v[50:53], v[192:195], v[214:217], v[50:53]
	v_mfma_f32_16x16x32_bf16 v[54:57], v[184:187], v[222:225], v[54:57]
	v_mfma_f32_16x16x32_bf16 v[58:61], v[192:195], v[222:225], v[58:61]
	v_mfma_f32_16x16x32_bf16 v[62:65], v[184:187], v[230:233], v[62:65]
	v_mfma_f32_16x16x32_bf16 v[66:69], v[192:195], v[230:233], v[66:69]
	s_barrier
	s_setprio 0
	s_mov_b64 s[26:27], 0x280
	s_mov_b32 m0, s88
	v_lshl_add_u64 v[2:3], v[2:3], 0, s[26:27]
	s_add_u32 s20, s46, 0x18280
	ds_read_b128 v[196:199], v178 offset:49152
	ds_read_b128 v[200:203], v178 offset:50176
	ds_read_b128 v[204:207], v178 offset:51200
	ds_read_b128 v[214:217], v178 offset:52224
	ds_read_b128 v[218:221], v178 offset:53248
	ds_read_b128 v[222:225], v178 offset:54272
	ds_read_b128 v[226:229], v178 offset:55296
	ds_read_b128 v[230:233], v178 offset:56320
	global_load_lds_dwordx4 v[2:3], off
	v_lshl_add_u64 v[2:3], v[4:5], 0, s[26:27]
	s_mov_b32 m0, s89
	s_addc_u32 s21, s47, 0
	global_load_lds_dwordx4 v[2:3], off
	v_lshl_add_u64 v[2:3], s[20:21], 0, v[166:167]
	s_mov_b32 m0, s28
	s_nop 0
	global_load_lds_dwordx4 v[2:3], off
	v_lshl_add_u64 v[2:3], s[20:21], 0, v[162:163]
	s_mov_b32 m0, s29
	s_nop 0
	global_load_lds_dwordx4 v[2:3], off
	v_lshl_add_u64 v[2:3], v[6:7], 0, s[26:27]
	s_mov_b32 m0, s90
	s_nop 0
	global_load_lds_dwordx4 v[2:3], off
	v_lshl_add_u64 v[2:3], v[8:9], 0, s[26:27]
	s_mov_b32 m0, s91
	s_nop 0
	global_load_lds_dwordx4 v[2:3], off
	s_waitcnt vmcnt(8)
	s_waitcnt lgkmcnt(0)
	s_barrier
	s_setprio 1
	s_waitcnt lgkmcnt(0)
	v_mfma_f32_16x16x32_bf16 v[2:5], v[130:133], v[196:199], v[146:149]
	v_mfma_f32_16x16x32_bf16 v[6:9], v[138:141], v[196:199], v[150:153]
	v_mfma_f32_16x16x32_bf16 v[42:45], v[130:133], v[226:229], v[42:45]
	v_mfma_f32_16x16x32_bf16 v[26:29], v[138:141], v[226:229], v[26:29]
	v_mfma_f32_16x16x32_bf16 v[2:5], v[134:137], v[200:203], v[2:5]
	v_mfma_f32_16x16x32_bf16 v[6:9], v[142:145], v[200:203], v[6:9]
	v_mfma_f32_16x16x32_bf16 v[146:149], v[130:133], v[204:207], v[154:157]
	v_mfma_f32_16x16x32_bf16 v[150:153], v[138:141], v[204:207], v[158:161]
	v_mfma_f32_16x16x32_bf16 v[154:157], v[130:133], v[218:221], v[170:173]
	v_mfma_f32_16x16x32_bf16 v[158:161], v[138:141], v[218:221], v[174:177]
	v_mfma_f32_16x16x32_bf16 v[42:45], v[134:137], v[230:233], v[42:45]
	v_mfma_f32_16x16x32_bf16 v[26:29], v[142:145], v[230:233], v[26:29]
	v_mfma_f32_16x16x32_bf16 v[146:149], v[134:137], v[214:217], v[146:149]
	v_mfma_f32_16x16x32_bf16 v[150:153], v[142:145], v[214:217], v[150:153]
	v_mfma_f32_16x16x32_bf16 v[154:157], v[134:137], v[222:225], v[154:157]
	v_mfma_f32_16x16x32_bf16 v[158:161], v[142:145], v[222:225], v[158:161]
	s_setprio 0
	s_setprio 1
	v_mfma_f32_16x16x32_bf16 v[30:33], v[180:183], v[196:199], v[30:33]
	v_mfma_f32_16x16x32_bf16 v[46:49], v[188:191], v[196:199], v[46:49]
	v_mfma_f32_16x16x32_bf16 v[70:73], v[180:183], v[204:207], v[70:73]
	v_mfma_f32_16x16x32_bf16 v[118:121], v[188:191], v[204:207], v[118:121]
	v_mfma_f32_16x16x32_bf16 v[122:125], v[180:183], v[218:221], v[122:125]
	v_mfma_f32_16x16x32_bf16 v[126:129], v[188:191], v[218:221], v[126:129]
	v_mfma_f32_16x16x32_bf16 v[34:37], v[180:183], v[226:229], v[34:37]
	v_mfma_f32_16x16x32_bf16 v[38:41], v[188:191], v[226:229], v[38:41]
	v_mfma_f32_16x16x32_bf16 v[30:33], v[184:187], v[200:203], v[30:33]
	v_mfma_f32_16x16x32_bf16 v[46:49], v[192:195], v[200:203], v[46:49]
	v_mfma_f32_16x16x32_bf16 v[70:73], v[184:187], v[214:217], v[70:73]
	v_mfma_f32_16x16x32_bf16 v[118:121], v[192:195], v[214:217], v[118:121]
	v_mfma_f32_16x16x32_bf16 v[122:125], v[184:187], v[222:225], v[122:125]
	v_mfma_f32_16x16x32_bf16 v[126:129], v[192:195], v[222:225], v[126:129]
	v_mfma_f32_16x16x32_bf16 v[34:37], v[184:187], v[230:233], v[34:37]
	v_mfma_f32_16x16x32_bf16 v[38:41], v[192:195], v[230:233], v[38:41]
	s_barrier
; #define PG8_STAGE(bufoff, gbase, voff) do { _Pragma("unroll") for (int _i = 0; _i < 2; ++_i) \
;         __builtin_amdgcn_global_load_lds((const unsigned*)((const char*)(gbase) + (voff)[_i]), (PG8_LAS unsigned*)(lds + (bufoff) + ldsw + _i * 8192), 16, 0, 0); } while (0)
; #define PG8_LDA(dst, b, h) do { _Pragma("unroll") for (int m = 0; m < 4; ++m) _Pragma("unroll") for (int k = 0; k < 2; ++k) dst[m][k] = *(const PG8_LAS bf16x8*)(lds + PG8_SA(b, h) + aoff + m * 2048 + k * 1024); } while (0)
; #define PG8_LDB(dst, b, h) do { _Pragma("unroll") for (int n = 0; n < 2; ++n) _Pragma("unroll") for (int k = 0; k < 2; ++k) dst[n][k] = *(const PG8_LAS bf16x8*)(lds + PG8_SB(b, h) + boff + n * 2048 + k * 1024); } while (0)
; #define PG8_MMA(ai, bj, At, Bt) do { __builtin_amdgcn_s_setprio(1); _Pragma("unroll") for (int m = 0; m < 4; ++m) _Pragma("unroll") for (int n = 0; n < 2; ++n) _Pragma("unroll") for (int k = 0; k < 2; ++k) \
;         acc[ai][bj][m][n] = __builtin_amdgcn_mfma_f32_16x16x32_bf16(Bt[n][k], At[m][k], acc[ai][bj][m][n], 0, 0, 0); __builtin_amdgcn_s_setprio(0); } while (0)
; #define PG8_BAR __builtin_amdgcn_s_barrier()
; template <class Epi, class Sched, bool ALIGN_EPI = false, bool SP2 = false>
; __device__ __forceinline__ void gemm_phase(PG8_LAS unsigned char* lds, const Gemm g, const Sched& S, const Epi& E, const int tid) {
;     ...
;             PG8_LDB(B0, 0, 0); PG8_LDB(B1, 0, 1); PG8_SCHED; PG8_LDA(At, 0, 0); PG8_STAGE(PG8_SA(1, 1), a1 + hstep, voffA);
;             PG8_WAIT_V(8); PG8_WAIT_L(0); PG8_BAR; PG8_MMA(0, 0, At, B0); PG8_MMA(0, 1, At, B1); PG8_BAR; PG8_SCHED;
;             PG8_LDA(At, 0, 1); PG8_STAGE(PG8_SB(0, 0), b2, voffB); PG8_STAGE(PG8_SB(0, 1), b2 + hstep, voffB); PG8_STAGE(PG8_SA(0, 0), a2, voffA);
;             PG8_WAIT_V(8); PG8_WAIT_L(0); PG8_BAR; PG8_MMA(1, 0, At, B0); PG8_MMA(1, 1, At, B1); PG8_BAR; PG8_SCHED;
;             PG8_LDB(B0, 1, 0); PG8_LDB(B1, 1, 1); PG8_SCHED; PG8_LDA(At, 1, 0); PG8_STAGE(PG8_SA(0, 1), a2 + hstep, voffA);
;             PG8_WAIT_V(8); PG8_WAIT_L(0); PG8_BAR; PG8_MMA(0, 0, At, B0); PG8_MMA(0, 1, At, B1); PG8_BAR; PG8_SCHED;
;             PG8_LDA(At, 1, 1); PG8_STAGE(PG8_SB(1, 0), b3, voffB); PG8_STAGE(PG8_SB(1, 1), b3 + hstep, voffB); PG8_STAGE(PG8_SA(1, 0), a3, voffA);
;             PG8_WAIT_V(8); PG8_WAIT_L(0); PG8_BAR; PG8_MMA(1, 0, At, B0); PG8_MMA(1, 1, At, B1); PG8_BAR; PG8_SCHED;
	s_setprio 0
	ds_read_b128 v[130:133], v0
	ds_read_b128 v[134:137], v10
	ds_read_b128 v[138:141], v11
	ds_read_b128 v[142:145], v12
	ds_read_b128 v[10:13], v13
	ds_read_b128 v[170:173], v14
	ds_read_b128 v[174:177], v15
	ds_read_b128 v[180:183], v16
	s_add_u32 s20, s30, 0x18280
	s_addc_u32 s21, s31, 0
	s_mov_b32 m0, s5
	v_lshl_add_u64 v[14:15], s[20:21], 0, v[168:169]
	ds_read_b128 v[184:187], v178
	ds_read_b128 v[188:191], v178 offset:1024
	ds_read_b128 v[192:195], v178 offset:2048
	ds_read_b128 v[196:199], v178 offset:3072
	ds_read_b128 v[200:203], v178 offset:4096
	ds_read_b128 v[204:207], v178 offset:5120
	ds_read_b128 v[214:217], v178 offset:6144
	ds_read_b128 v[218:221], v178 offset:7168
	global_load_lds_dwordx4 v[14:15], off
	v_lshl_add_u64 v[14:15], s[20:21], 0, v[164:165]
	s_mov_b32 m0, s4
	s_nop 0
	global_load_lds_dwordx4 v[14:15], off
	s_waitcnt vmcnt(8)
	s_waitcnt lgkmcnt(0)
	s_barrier
	s_setprio 1
	s_waitcnt lgkmcnt(0)
	v_mfma_f32_16x16x32_bf16 v[94:97], v[138:141], v[200:203], v[94:97]
	v_mfma_f32_16x16x32_bf16 v[222:225], v[142:145], v[204:207], v[94:97]
	v_mfma_f32_16x16x32_bf16 v[94:97], v[130:133], v[214:217], v[98:101]
	v_mfma_f32_16x16x32_bf16 v[74:77], v[130:133], v[184:187], v[74:77]
	v_mfma_f32_16x16x32_bf16 v[78:81], v[138:141], v[184:187], v[78:81]
	v_mfma_f32_16x16x32_bf16 v[82:85], v[130:133], v[192:195], v[82:85]
	v_mfma_f32_16x16x32_bf16 v[86:89], v[138:141], v[192:195], v[86:89]
	v_mfma_f32_16x16x32_bf16 v[90:93], v[130:133], v[200:203], v[90:93]
	v_mfma_f32_16x16x32_bf16 v[98:101], v[134:137], v[218:221], v[94:97]
	v_mfma_f32_16x16x32_bf16 v[94:97], v[138:141], v[214:217], v[102:105]
	v_mfma_f32_16x16x32_bf16 v[74:77], v[134:137], v[188:191], v[74:77]
	v_mfma_f32_16x16x32_bf16 v[78:81], v[142:145], v[188:191], v[78:81]
	v_mfma_f32_16x16x32_bf16 v[82:85], v[134:137], v[196:199], v[82:85]
	v_mfma_f32_16x16x32_bf16 v[86:89], v[142:145], v[196:199], v[86:89]
	v_mfma_f32_16x16x32_bf16 v[90:93], v[134:137], v[204:207], v[90:93]
	v_mfma_f32_16x16x32_bf16 v[102:105], v[142:145], v[218:221], v[94:97]
	s_setprio 0
	s_setprio 1
	v_mfma_f32_16x16x32_bf16 v[94:97], v[10:13], v[184:187], v[106:109]
	v_mfma_f32_16x16x32_bf16 v[226:229], v[170:173], v[188:191], v[94:97]
	v_mfma_f32_16x16x32_bf16 v[94:97], v[174:177], v[184:187], v[110:113]
	v_mfma_f32_16x16x32_bf16 v[50:53], v[174:177], v[192:195], v[50:53]
	v_mfma_f32_16x16x32_bf16 v[54:57], v[10:13], v[200:203], v[54:57]
	v_mfma_f32_16x16x32_bf16 v[58:61], v[174:177], v[200:203], v[58:61]
	v_mfma_f32_16x16x32_bf16 v[62:65], v[10:13], v[214:217], v[62:65]
	v_mfma_f32_16x16x32_bf16 v[184:187], v[180:183], v[188:191], v[94:97]
	v_mfma_f32_16x16x32_bf16 v[94:97], v[10:13], v[192:195], v[114:117]
	v_mfma_f32_16x16x32_bf16 v[50:53], v[180:183], v[196:199], v[50:53]
	v_mfma_f32_16x16x32_bf16 v[54:57], v[170:173], v[204:207], v[54:57]
	v_mfma_f32_16x16x32_bf16 v[58:61], v[180:183], v[204:207], v[58:61]
	v_mfma_f32_16x16x32_bf16 v[62:65], v[170:173], v[218:221], v[62:65]
	v_mfma_f32_16x16x32_bf16 v[66:69], v[174:177], v[214:217], v[66:69]
	v_mfma_f32_16x16x32_bf16 v[188:191], v[170:173], v[196:199], v[94:97]
	v_mfma_f32_16x16x32_bf16 v[192:195], v[180:183], v[218:221], v[66:69]
	s_barrier
	s_setprio 0
	s_mov_b32 m0, s8
	v_lshl_add_u64 v[208:209], s[44:45], 0, v[166:167]
	s_add_u32 s4, s44, 0x18000
	s_nop 0
	ds_read_b128 v[66:69], v178 offset:16384
	ds_read_b128 v[94:97], v178 offset:17408
	ds_read_b128 v[106:109], v178 offset:18432
	ds_read_b128 v[110:113], v178 offset:19456
	ds_read_b128 v[114:117], v178 offset:20480
	ds_read_b128 v[196:199], v178 offset:21504
	ds_read_b128 v[200:203], v178 offset:22528
	ds_read_b128 v[204:207], v178 offset:23552
	global_load_lds_dwordx4 v[208:209], off
	v_lshl_add_u64 v[210:211], s[44:45], 0, v[162:163]
	s_mov_b32 m0, s9
	s_addc_u32 s5, s45, 0
	global_load_lds_dwordx4 v[210:211], off
	v_lshl_add_u64 v[14:15], s[4:5], 0, v[166:167]
	s_mov_b32 m0, s14
	v_lshl_add_u64 v[212:213], s[38:39], 0, v[168:169]
	global_load_lds_dwordx4 v[14:15], off
	v_lshl_add_u64 v[14:15], s[4:5], 0, v[162:163]
	s_mov_b32 m0, s34
	v_lshl_add_u64 v[246:247], s[38:39], 0, v[164:165]
	global_load_lds_dwordx4 v[14:15], off
	s_mov_b32 m0, s1
	s_nop 0
	global_load_lds_dwordx4 v[212:213], off
	s_mov_b32 m0, s35
	s_nop 0
	global_load_lds_dwordx4 v[246:247], off
	s_waitcnt vmcnt(8)
	s_waitcnt lgkmcnt(0)
	s_barrier
	s_setprio 1
	s_waitcnt lgkmcnt(0)
	v_mfma_f32_16x16x32_bf16 v[2:5], v[130:133], v[66:69], v[2:5]
	v_mfma_f32_16x16x32_bf16 v[6:9], v[138:141], v[66:69], v[6:9]
	v_mfma_f32_16x16x32_bf16 v[2:5], v[134:137], v[94:97], v[2:5]
	v_mfma_f32_16x16x32_bf16 v[6:9], v[142:145], v[94:97], v[6:9]
	v_mfma_f32_16x16x32_bf16 v[146:149], v[130:133], v[106:109], v[146:149]
	v_mfma_f32_16x16x32_bf16 v[150:153], v[138:141], v[106:109], v[150:153]
	v_mfma_f32_16x16x32_bf16 v[154:157], v[130:133], v[114:117], v[154:157]
	v_mfma_f32_16x16x32_bf16 v[158:161], v[138:141], v[114:117], v[158:161]
	v_mfma_f32_16x16x32_bf16 v[42:45], v[130:133], v[200:203], v[42:45]
	v_mfma_f32_16x16x32_bf16 v[26:29], v[138:141], v[200:203], v[26:29]
	v_mfma_f32_16x16x32_bf16 v[146:149], v[134:137], v[110:113], v[146:149]
	v_mfma_f32_16x16x32_bf16 v[150:153], v[142:145], v[110:113], v[150:153]
	v_mfma_f32_16x16x32_bf16 v[154:157], v[134:137], v[196:199], v[154:157]
	v_mfma_f32_16x16x32_bf16 v[158:161], v[142:145], v[196:199], v[158:161]
	v_mfma_f32_16x16x32_bf16 v[130:133], v[134:137], v[204:207], v[42:45]
	v_mfma_f32_16x16x32_bf16 v[134:137], v[142:145], v[204:207], v[26:29]
	s_setprio 0
	s_setprio 1
	v_mfma_f32_16x16x32_bf16 v[26:29], v[10:13], v[66:69], v[30:33]
	v_mfma_f32_16x16x32_bf16 v[138:141], v[170:173], v[94:97], v[26:29]
	v_mfma_f32_16x16x32_bf16 v[26:29], v[174:177], v[66:69], v[46:49]
	v_mfma_f32_16x16x32_bf16 v[142:145], v[180:183], v[94:97], v[26:29]
	v_mfma_f32_16x16x32_bf16 v[26:29], v[10:13], v[106:109], v[70:73]
	v_mfma_f32_16x16x32_bf16 v[214:217], v[170:173], v[110:113], v[26:29]
	v_mfma_f32_16x16x32_bf16 v[26:29], v[174:177], v[106:109], v[118:121]
	v_mfma_f32_16x16x32_bf16 v[218:221], v[180:183], v[110:113], v[26:29]
	v_mfma_f32_16x16x32_bf16 v[26:29], v[10:13], v[114:117], v[122:125]
	v_mfma_f32_16x16x32_bf16 v[10:13], v[10:13], v[200:203], v[34:37]
	v_mfma_f32_16x16x32_bf16 v[230:233], v[170:173], v[196:199], v[26:29]
	v_mfma_f32_16x16x32_bf16 v[26:29], v[174:177], v[114:117], v[126:129]
	v_mfma_f32_16x16x32_bf16 v[170:173], v[170:173], v[204:207], v[10:13]
	v_mfma_f32_16x16x32_bf16 v[10:13], v[174:177], v[200:203], v[38:41]
	v_mfma_f32_16x16x32_bf16 v[196:199], v[180:183], v[196:199], v[26:29]
	v_mfma_f32_16x16x32_bf16 v[174:177], v[180:183], v[204:207], v[10:13]
	s_barrier
; #define PG8_STAGE(bufoff, gbase, voff) do { _Pragma("unroll") for (int _i = 0; _i < 2; ++_i) \
;         __builtin_amdgcn_global_load_lds((const unsigned*)((const char*)(gbase) + (voff)[_i]), (PG8_LAS unsigned*)(lds + (bufoff) + ldsw + _i * 8192), 16, 0, 0); } while (0)
; #define PG8_LDA(dst, b, h) do { _Pragma("unroll") for (int m = 0; m < 4; ++m) _Pragma("unroll") for (int k = 0; k < 2; ++k) dst[m][k] = *(const PG8_LAS bf16x8*)(lds + PG8_SA(b, h) + aoff + m * 2048 + k * 1024); } while (0)
; #define PG8_LDB(dst, b, h) do { _Pragma("unroll") for (int n = 0; n < 2; ++n) _Pragma("unroll") for (int k = 0; k < 2; ++k) dst[n][k] = *(const PG8_LAS bf16x8*)(lds + PG8_SB(b, h) + boff + n * 2048 + k * 1024); } while (0)
; #define PG8_MMA(ai, bj, At, Bt) do { __builtin_amdgcn_s_setprio(1); _Pragma("unroll") for (int m = 0; m < 4; ++m) _Pragma("unroll") for (int n = 0; n < 2; ++n) _Pragma("unroll") for (int k = 0; k < 2; ++k) \
;         acc[ai][bj][m][n] = __builtin_amdgcn_mfma_f32_16x16x32_bf16(Bt[n][k], At[m][k], acc[ai][bj][m][n], 0, 0, 0); __builtin_amdgcn_s_setprio(0); } while (0)
; #define PG8_BAR __builtin_amdgcn_s_barrier()
; template <class Epi, class Sched, bool ALIGN_EPI = false, bool SP2 = false>
; __device__ __forceinline__ void gemm_phase(PG8_LAS unsigned char* lds, const Gemm g, const Sched& S, const Epi& E, const int tid) {
;     ...
;             PG8_LDB(B0, 0, 0); PG8_LDB(B1, 0, 1); PG8_SCHED; PG8_LDA(At, 0, 0); PG8_STAGE(PG8_SA(1, 1), a1 + hstep, voffA);
;             PG8_WAIT_V(8); PG8_WAIT_L(0); PG8_BAR; PG8_MMA(0, 0, At, B0); PG8_MMA(0, 1, At, B1); PG8_BAR; PG8_SCHED;
;             PG8_LDA(At, 0, 1); PG8_STAGE(PG8_SB(0, 0), b2, voffB); PG8_STAGE(PG8_SB(0, 1), b2 + hstep, voffB); PG8_STAGE(PG8_SA(0, 0), a2, voffA);
;             PG8_WAIT_V(8); PG8_WAIT_L(0); PG8_BAR; PG8_MMA(1, 0, At, B0); PG8_MMA(1, 1, At, B1); PG8_BAR; PG8_SCHED;
;             PG8_LDB(B0, 1, 0); PG8_LDB(B1, 1, 1); PG8_SCHED; PG8_LDA(At, 1, 0); PG8_STAGE(PG8_SA(0, 1), a2 + hstep, voffA);
;             PG8_WAIT_V(8); PG8_WAIT_L(0); PG8_BAR; PG8_MMA(0, 0, At, B0); PG8_MMA(0, 1, At, B1); PG8_BAR; PG8_SCHED;
;             PG8_LDA(At, 1, 1); PG8_STAGE(PG8_SB(1, 0), b3, voffB); PG8_STAGE(PG8_SB(1, 1), b3 + hstep, voffB); PG8_STAGE(PG8_SA(1, 0), a3, voffA);
;             PG8_WAIT_V(8); PG8_WAIT_L(0); PG8_BAR; PG8_MMA(1, 0, At, B0); PG8_MMA(1, 1, At, B1); PG8_BAR; PG8_SCHED;
	s_setprio 0
	s_nop 3
	ds_read_b128 v[10:13], v17
	ds_read_b128 v[14:17], v18
	ds_read_b128 v[34:37], v19
	ds_read_b128 v[38:41], v20
	ds_read_b128 v[180:183], v21
	ds_read_b128 v[200:203], v22
	ds_read_b128 v[204:207], v23
	ds_read_b128 v[234:237], v24
	s_add_u32 s4, s38, 0x18000
	s_addc_u32 s5, s39, 0
	s_mov_b32 m0, s84
	v_lshl_add_u64 v[66:67], s[4:5], 0, v[168:169]
	ds_read_b128 v[18:21], v178 offset:32768
	ds_read_b128 v[22:25], v178 offset:33792
	ds_read_b128 v[26:29], v178 offset:34816
	ds_read_b128 v[30:33], v178 offset:35840
	ds_read_b128 v[42:45], v178 offset:36864
	ds_read_b128 v[46:49], v178 offset:37888
	ds_read_b128 v[238:241], v178 offset:38912
	ds_read_b128 v[242:245], v178 offset:39936
	global_load_lds_dwordx4 v[66:67], off
	v_lshl_add_u64 v[66:67], s[4:5], 0, v[164:165]
	s_mov_b32 m0, s85
	s_nop 0
	global_load_lds_dwordx4 v[66:67], off
	s_waitcnt vmcnt(8)
	s_waitcnt lgkmcnt(0)
	s_barrier
	s_setprio 1
	s_waitcnt lgkmcnt(0)
	v_mfma_f32_16x16x32_bf16 v[66:69], v[10:13], v[18:21], v[74:77]
	v_mfma_f32_16x16x32_bf16 v[126:129], v[14:17], v[22:25], v[66:69]
	v_mfma_f32_16x16x32_bf16 v[66:69], v[34:37], v[18:21], v[78:81]
	v_mfma_f32_16x16x32_bf16 v[122:125], v[38:41], v[22:25], v[66:69]
	v_mfma_f32_16x16x32_bf16 v[66:69], v[10:13], v[26:29], v[82:85]
	v_mfma_f32_16x16x32_bf16 v[110:113], v[14:17], v[30:33], v[66:69]
	v_mfma_f32_16x16x32_bf16 v[66:69], v[34:37], v[26:29], v[86:89]
	v_mfma_f32_16x16x32_bf16 v[106:109], v[38:41], v[30:33], v[66:69]
	v_mfma_f32_16x16x32_bf16 v[66:69], v[10:13], v[42:45], v[90:93]
	v_mfma_f32_16x16x32_bf16 v[94:97], v[14:17], v[46:49], v[66:69]
	v_mfma_f32_16x16x32_bf16 v[66:69], v[34:37], v[42:45], v[222:225]
	v_mfma_f32_16x16x32_bf16 v[90:93], v[38:41], v[46:49], v[66:69]
	v_mfma_f32_16x16x32_bf16 v[66:69], v[10:13], v[238:241], v[98:101]
	v_mfma_f32_16x16x32_bf16 v[70:73], v[14:17], v[242:245], v[66:69]
	v_mfma_f32_16x16x32_bf16 v[66:69], v[34:37], v[238:241], v[102:105]
	v_mfma_f32_16x16x32_bf16 v[66:69], v[38:41], v[242:245], v[66:69]
	s_setprio 0
	s_setprio 1
	v_mfma_f32_16x16x32_bf16 v[74:77], v[180:183], v[18:21], v[226:229]
	v_mfma_f32_16x16x32_bf16 v[18:21], v[204:207], v[18:21], v[184:187]
	v_mfma_f32_16x16x32_bf16 v[114:117], v[234:237], v[22:25], v[18:21]
	v_mfma_f32_16x16x32_bf16 v[18:21], v[180:183], v[26:29], v[188:191]
	v_mfma_f32_16x16x32_bf16 v[102:105], v[200:203], v[30:33], v[18:21]
	v_mfma_f32_16x16x32_bf16 v[18:21], v[204:207], v[26:29], v[50:53]
	v_mfma_f32_16x16x32_bf16 v[98:101], v[234:237], v[30:33], v[18:21]
	v_mfma_f32_16x16x32_bf16 v[18:21], v[180:183], v[42:45], v[54:57]
	v_mfma_f32_16x16x32_bf16 v[86:89], v[200:203], v[46:49], v[18:21]
	v_mfma_f32_16x16x32_bf16 v[18:21], v[204:207], v[42:45], v[58:61]
	v_mfma_f32_16x16x32_bf16 v[82:85], v[234:237], v[46:49], v[18:21]
	v_mfma_f32_16x16x32_bf16 v[18:21], v[180:183], v[238:241], v[62:65]
	v_mfma_f32_16x16x32_bf16 v[54:57], v[200:203], v[242:245], v[18:21]
	v_mfma_f32_16x16x32_bf16 v[18:21], v[204:207], v[238:241], v[192:195]
	v_mfma_f32_16x16x32_bf16 v[118:121], v[200:203], v[22:25], v[74:77]
	v_mfma_f32_16x16x32_bf16 v[50:53], v[234:237], v[242:245], v[18:21]
	s_barrier
	s_setprio 0
	s_mov_b32 m0, s88
	v_lshl_add_u64 v[26:27], v[208:209], 0, s[12:13]
	s_add_u32 s4, s44, 0x18080
	s_nop 0
	ds_read_b128 v[18:21], v178 offset:49152
	ds_read_b128 v[22:25], v178 offset:50176
	ds_read_b128 v[184:187], v178 offset:51200
	ds_read_b128 v[188:191], v178 offset:52224
	ds_read_b128 v[192:195], v178 offset:53248
	ds_read_b128 v[222:225], v178 offset:54272
	ds_read_b128 v[226:229], v178 offset:55296
	ds_read_b128 v[238:241], v178 offset:56320
	global_load_lds_dwordx4 v[26:27], off
	v_lshl_add_u64 v[26:27], v[210:211], 0, s[12:13]
	s_mov_b32 m0, s89
	s_addc_u32 s5, s45, 0
	global_load_lds_dwordx4 v[26:27], off
	v_lshl_add_u64 v[26:27], s[4:5], 0, v[166:167]
	s_mov_b32 m0, s28
	s_nop 0
	global_load_lds_dwordx4 v[26:27], off
	v_lshl_add_u64 v[26:27], s[4:5], 0, v[162:163]
	s_mov_b32 m0, s29
	s_nop 0
	global_load_lds_dwordx4 v[26:27], off
	v_lshl_add_u64 v[26:27], v[212:213], 0, s[12:13]
	s_mov_b32 m0, s90
	s_nop 0
	global_load_lds_dwordx4 v[26:27], off
	v_lshl_add_u64 v[26:27], v[246:247], 0, s[12:13]
	s_mov_b32 m0, s91
	s_nop 0
	global_load_lds_dwordx4 v[26:27], off
	s_waitcnt vmcnt(8)
	s_waitcnt lgkmcnt(0)
	s_barrier
	s_setprio 1
	s_waitcnt lgkmcnt(0)
	v_mfma_f32_16x16x32_bf16 v[2:5], v[10:13], v[18:21], v[2:5]
	v_mfma_f32_16x16x32_bf16 v[78:81], v[14:17], v[22:25], v[2:5]
	v_mfma_f32_16x16x32_bf16 v[2:5], v[34:37], v[18:21], v[6:9]
	v_mfma_f32_16x16x32_bf16 v[74:77], v[38:41], v[22:25], v[2:5]
	v_mfma_f32_16x16x32_bf16 v[2:5], v[10:13], v[184:187], v[146:149]
	v_mfma_f32_16x16x32_bf16 v[46:49], v[14:17], v[188:191], v[2:5]
	v_mfma_f32_16x16x32_bf16 v[2:5], v[34:37], v[184:187], v[150:153]
	v_mfma_f32_16x16x32_bf16 v[42:45], v[38:41], v[188:191], v[2:5]
	v_mfma_f32_16x16x32_bf16 v[2:5], v[10:13], v[192:195], v[154:157]
	v_mfma_f32_16x16x32_bf16 v[30:33], v[14:17], v[222:225], v[2:5]
	v_mfma_f32_16x16x32_bf16 v[2:5], v[34:37], v[192:195], v[158:161]
	v_mfma_f32_16x16x32_bf16 v[26:29], v[38:41], v[222:225], v[2:5]
	v_mfma_f32_16x16x32_bf16 v[2:5], v[10:13], v[226:229], v[130:133]
	v_mfma_f32_16x16x32_bf16 v[14:17], v[14:17], v[238:241], v[2:5]
	v_mfma_f32_16x16x32_bf16 v[2:5], v[34:37], v[226:229], v[134:137]
	v_mfma_f32_16x16x32_bf16 v[10:13], v[38:41], v[238:241], v[2:5]
	s_setprio 0
	s_setprio 1
	v_mfma_f32_16x16x32_bf16 v[2:5], v[180:183], v[18:21], v[138:141]
	v_mfma_f32_16x16x32_bf16 v[62:65], v[200:203], v[22:25], v[2:5]
	v_mfma_f32_16x16x32_bf16 v[2:5], v[204:207], v[18:21], v[142:145]
	v_mfma_f32_16x16x32_bf16 v[58:61], v[234:237], v[22:25], v[2:5]
	v_mfma_f32_16x16x32_bf16 v[2:5], v[180:183], v[184:187], v[214:217]
	v_mfma_f32_16x16x32_bf16 v[38:41], v[200:203], v[188:191], v[2:5]
	v_mfma_f32_16x16x32_bf16 v[2:5], v[204:207], v[184:187], v[218:221]
	v_mfma_f32_16x16x32_bf16 v[34:37], v[234:237], v[188:191], v[2:5]
	v_mfma_f32_16x16x32_bf16 v[2:5], v[180:183], v[192:195], v[230:233]
	v_mfma_f32_16x16x32_bf16 v[22:25], v[200:203], v[222:225], v[2:5]
	v_mfma_f32_16x16x32_bf16 v[2:5], v[204:207], v[192:195], v[196:199]
	v_mfma_f32_16x16x32_bf16 v[18:21], v[234:237], v[222:225], v[2:5]
	v_mfma_f32_16x16x32_bf16 v[2:5], v[180:183], v[226:229], v[170:173]
	v_mfma_f32_16x16x32_bf16 v[6:9], v[200:203], v[238:241], v[2:5]
	v_mfma_f32_16x16x32_bf16 v[2:5], v[204:207], v[226:229], v[174:177]
	v_mfma_f32_16x16x32_bf16 v[2:5], v[234:237], v[238:241], v[2:5]
	s_barrier
	s_setprio 0
	s_andn2_b64 vcc, exec, s[40:41]
	s_cbranch_vccnz .LBB0_390
	s_barrier

; #define PG8_STAGE(bufoff, gbase, voff) do { _Pragma("unroll") for (int _i = 0; _i < 2; ++_i) \
;         __builtin_amdgcn_global_load_lds((const unsigned*)((const char*)(gbase) + (voff)[_i]), (PG8_LAS unsigned*)(lds + (bufoff) + ldsw + _i * 8192), 16, 0, 0); } while (0)
; #define PG8_LDA(dst, b, h) do { _Pragma("unroll") for (int m = 0; m < 4; ++m) _Pragma("unroll") for (int k = 0; k < 2; ++k) dst[m][k] = *(const PG8_LAS bf16x8*)(lds + PG8_SA(b, h) + aoff + m * 2048 + k * 1024); } while (0)
; #define PG8_LDB(dst, b, h) do { _Pragma("unroll") for (int n = 0; n < 2; ++n) _Pragma("unroll") for (int k = 0; k < 2; ++k) dst[n][k] = *(const PG8_LAS bf16x8*)(lds + PG8_SB(b, h) + boff + n * 2048 + k * 1024); } while (0)
; #define PG8_MMA(ai, bj, At, Bt) do { __builtin_amdgcn_s_setprio(1); _Pragma("unroll") for (int m = 0; m < 4; ++m) _Pragma("unroll") for (int n = 0; n < 2; ++n) _Pragma("unroll") for (int k = 0; k < 2; ++k) \
;         acc[ai][bj][m][n] = __builtin_amdgcn_mfma_f32_16x16x32_bf16(Bt[n][k], At[m][k], acc[ai][bj][m][n], 0, 0, 0); __builtin_amdgcn_s_setprio(0); } while (0)
; #define PG8_BAR __builtin_amdgcn_s_barrier()
; template <class Epi, class Sched, bool ALIGN_EPI = false, bool SP2 = false>
; __device__ __forceinline__ void gemm_phase(PG8_LAS unsigned char* lds, const Gemm g, const Sched& S, const Epi& E, const int tid) {
;     ...
;             PG8_LDB(B0, 0, 0); PG8_LDB(B1, 0, 1); PG8_SCHED; PG8_LDA(At, 0, 0); PG8_STAGE(PG8_SA(1, 1), a1 + hstep, voffA);
;             PG8_WAIT_V(8); PG8_WAIT_L(0); PG8_BAR; PG8_MMA(0, 0, At, B0); PG8_MMA(0, 1, At, B1); PG8_BAR; PG8_SCHED;
;             PG8_LDA(At, 0, 1); PG8_STAGE(PG8_SB(0, 0), b2, voffB); PG8_STAGE(PG8_SB(0, 1), b2 + hstep, voffB); PG8_STAGE(PG8_SA(0, 0), a2, voffA);
;             PG8_WAIT_V(8); PG8_WAIT_L(0); PG8_BAR; PG8_MMA(1, 0, At, B0); PG8_MMA(1, 1, At, B1); PG8_BAR; PG8_SCHED;
;             PG8_LDB(B0, 1, 0); PG8_LDB(B1, 1, 1); PG8_SCHED; PG8_LDA(At, 1, 0); PG8_STAGE(PG8_SA(0, 1), a2 + hstep, voffA);
;             PG8_WAIT_V(8); PG8_WAIT_L(0); PG8_BAR; PG8_MMA(0, 0, At, B0); PG8_MMA(0, 1, At, B1); PG8_BAR; PG8_SCHED;
;             PG8_LDA(At, 1, 1); PG8_STAGE(PG8_SB(1, 0), b3, voffB); PG8_STAGE(PG8_SB(1, 1), b3 + hstep, voffB); PG8_STAGE(PG8_SA(1, 0), a3, voffA);
;             PG8_WAIT_V(8); PG8_WAIT_L(0); PG8_BAR; PG8_MMA(1, 0, At, B0); PG8_MMA(1, 1, At, B1); PG8_BAR; PG8_SCHED;
.LBB0_499:
	v_or_b32_e32 v140, 0x10000, v145
	v_add_u32_e32 v146, 0x10400, v145
	v_add_u32_e32 v150, 0x10800, v145
	v_add_u32_e32 v154, 0x10c00, v145
	v_or_b32_e32 v158, 0x14000, v145
	v_add_u32_e32 v162, 0x14400, v145
	v_add_u32_e32 v166, 0x14800, v145
	v_add_u32_e32 v170, 0x14c00, v145
	ds_read_b128 v[140:143], v140
	ds_read_b128 v[146:149], v146
	ds_read_b128 v[150:153], v150
	ds_read_b128 v[154:157], v154
	ds_read_b128 v[158:161], v158
	ds_read_b128 v[162:165], v162
	ds_read_b128 v[166:169], v166
	ds_read_b128 v[170:173], v170
	s_add_u32 s88, s86, 0xfffc0080
	s_addc_u32 s89, s87, -1
	s_cmp_eq_u32 s96, 12
	s_cselect_b32 s91, s39, s89
	s_cselect_b32 s90, s43, s88
	s_cselect_b32 s89, s41, s85
	s_cselect_b32 s88, s50, s51
	v_lshl_add_u64 v[178:179], s[86:87], 0, v[136:137]
	s_add_i32 m0, s0, 0xc000
	ds_read_b128 v[174:177], v144
	ds_read_b128 v[184:187], v144 offset:1024
	ds_read_b128 v[188:191], v144 offset:2048
	ds_read_b128 v[192:195], v144 offset:3072
	ds_read_b128 v[196:199], v144 offset:4096
	ds_read_b128 v[200:203], v144 offset:5120
	ds_read_b128 v[204:207], v144 offset:6144
	ds_read_b128 v[214:217], v144 offset:7168
	global_load_lds_dwordx4 v[178:179], off
	v_lshl_add_u64 v[178:179], s[86:87], 0, v[138:139]
	s_add_i32 m0, s0, 0xe000
	s_nop 0
	global_load_lds_dwordx4 v[178:179], off
	s_waitcnt vmcnt(8)
	s_waitcnt lgkmcnt(0)
	s_barrier
	s_setprio 1
	s_waitcnt lgkmcnt(0)
	v_mfma_f32_16x16x32_bf16 v[126:129], v[140:143], v[174:177], v[126:129]
	v_mfma_f32_16x16x32_bf16 v[122:125], v[150:153], v[174:177], v[122:125]
	v_mfma_f32_16x16x32_bf16 v[114:117], v[140:143], v[188:191], v[114:117]
	v_mfma_f32_16x16x32_bf16 v[106:109], v[150:153], v[188:191], v[106:109]
	v_mfma_f32_16x16x32_bf16 v[98:101], v[140:143], v[196:199], v[98:101]
	v_mfma_f32_16x16x32_bf16 v[90:93], v[150:153], v[196:199], v[90:93]
	v_mfma_f32_16x16x32_bf16 v[82:85], v[140:143], v[204:207], v[82:85]
	v_mfma_f32_16x16x32_bf16 v[74:77], v[150:153], v[204:207], v[74:77]
	v_mfma_f32_16x16x32_bf16 v[126:129], v[146:149], v[184:187], v[126:129]
	v_mfma_f32_16x16x32_bf16 v[122:125], v[154:157], v[184:187], v[122:125]
	v_mfma_f32_16x16x32_bf16 v[114:117], v[146:149], v[192:195], v[114:117]
	v_mfma_f32_16x16x32_bf16 v[106:109], v[154:157], v[192:195], v[106:109]
	v_mfma_f32_16x16x32_bf16 v[98:101], v[146:149], v[200:203], v[98:101]
	v_mfma_f32_16x16x32_bf16 v[90:93], v[154:157], v[200:203], v[90:93]
	v_mfma_f32_16x16x32_bf16 v[82:85], v[146:149], v[214:217], v[82:85]
	v_mfma_f32_16x16x32_bf16 v[74:77], v[154:157], v[214:217], v[74:77]
	s_setprio 0
	s_setprio 1
	v_mfma_f32_16x16x32_bf16 v[118:121], v[158:161], v[174:177], v[118:121]
	v_mfma_f32_16x16x32_bf16 v[110:113], v[166:169], v[174:177], v[110:113]
	v_mfma_f32_16x16x32_bf16 v[102:105], v[158:161], v[188:191], v[102:105]
	v_mfma_f32_16x16x32_bf16 v[94:97], v[166:169], v[188:191], v[94:97]
	v_mfma_f32_16x16x32_bf16 v[86:89], v[158:161], v[196:199], v[86:89]
	v_mfma_f32_16x16x32_bf16 v[78:81], v[166:169], v[196:199], v[78:81]
	v_mfma_f32_16x16x32_bf16 v[70:73], v[158:161], v[204:207], v[70:73]
	v_mfma_f32_16x16x32_bf16 v[66:69], v[166:169], v[204:207], v[66:69]
	v_mfma_f32_16x16x32_bf16 v[118:121], v[162:165], v[184:187], v[118:121]
	v_mfma_f32_16x16x32_bf16 v[110:113], v[170:173], v[184:187], v[110:113]
	v_mfma_f32_16x16x32_bf16 v[102:105], v[162:165], v[192:195], v[102:105]
	v_mfma_f32_16x16x32_bf16 v[94:97], v[170:173], v[192:195], v[94:97]
	v_mfma_f32_16x16x32_bf16 v[86:89], v[162:165], v[200:203], v[86:89]
	v_mfma_f32_16x16x32_bf16 v[78:81], v[170:173], v[200:203], v[78:81]
	v_mfma_f32_16x16x32_bf16 v[70:73], v[162:165], v[214:217], v[70:73]
	v_mfma_f32_16x16x32_bf16 v[66:69], v[170:173], v[214:217], v[66:69]
	s_barrier
	s_setprio 0
	s_mov_b32 m0, s1
	v_lshl_add_u64 v[178:179], s[88:89], 0, v[0:1]
	s_add_u32 s92, s88, 0x40000
	ds_read_b128 v[174:177], v144 offset:16384
	ds_read_b128 v[184:187], v144 offset:17408
	ds_read_b128 v[188:191], v144 offset:18432
	ds_read_b128 v[192:195], v144 offset:19456
	ds_read_b128 v[196:199], v144 offset:20480
	ds_read_b128 v[200:203], v144 offset:21504
	ds_read_b128 v[204:207], v144 offset:22528
	ds_read_b128 v[214:217], v144 offset:23552
	global_load_lds_dwordx4 v[178:179], off
	v_lshl_add_u64 v[180:181], s[88:89], 0, v[134:135]
	s_mov_b32 m0, s2
	s_addc_u32 s93, s89, 0
	global_load_lds_dwordx4 v[180:181], off
	v_lshl_add_u64 v[182:183], s[92:93], 0, v[0:1]
	s_mov_b32 m0, s4
	v_lshl_add_u64 v[218:219], s[90:91], 0, v[132:133]
	global_load_lds_dwordx4 v[182:183], off
	v_lshl_add_u64 v[182:183], s[92:93], 0, v[134:135]
	s_mov_b32 m0, s5
	s_nop 0
	global_load_lds_dwordx4 v[182:183], off
	v_lshl_add_u64 v[182:183], s[90:91], 0, v[130:131]
	s_mov_b32 m0, s0
	s_nop 0
	global_load_lds_dwordx4 v[182:183], off
	s_mov_b32 m0, s6
	s_nop 0
	global_load_lds_dwordx4 v[218:219], off
	s_waitcnt vmcnt(8)
	s_waitcnt lgkmcnt(0)
	s_barrier
; #define PG8_STAGE(bufoff, gbase, voff) do { _Pragma("unroll") for (int _i = 0; _i < 2; ++_i) \
;         __builtin_amdgcn_global_load_lds((const unsigned*)((const char*)(gbase) + (voff)[_i]), (PG8_LAS unsigned*)(lds + (bufoff) + ldsw + _i * 8192), 16, 0, 0); } while (0)
; #define PG8_LDA(dst, b, h) do { _Pragma("unroll") for (int m = 0; m < 4; ++m) _Pragma("unroll") for (int k = 0; k < 2; ++k) dst[m][k] = *(const PG8_LAS bf16x8*)(lds + PG8_SA(b, h) + aoff + m * 2048 + k * 1024); } while (0)
; #define PG8_LDB(dst, b, h) do { _Pragma("unroll") for (int n = 0; n < 2; ++n) _Pragma("unroll") for (int k = 0; k < 2; ++k) dst[n][k] = *(const PG8_LAS bf16x8*)(lds + PG8_SB(b, h) + boff + n * 2048 + k * 1024); } while (0)
; #define PG8_MMA(ai, bj, At, Bt) do { __builtin_amdgcn_s_setprio(1); _Pragma("unroll") for (int m = 0; m < 4; ++m) _Pragma("unroll") for (int n = 0; n < 2; ++n) _Pragma("unroll") for (int k = 0; k < 2; ++k) \
;         acc[ai][bj][m][n] = __builtin_amdgcn_mfma_f32_16x16x32_bf16(Bt[n][k], At[m][k], acc[ai][bj][m][n], 0, 0, 0); __builtin_amdgcn_s_setprio(0); } while (0)
; #define PG8_WAIT_V(n) asm volatile("s_waitcnt vmcnt(" #n ")" ::: "memory")
; #define PG8_WAIT_L(n) asm volatile("s_waitcnt lgkmcnt(" #n ")" ::: "memory")
; #define PG8_BAR __builtin_amdgcn_s_barrier()
; #define PG8_SCHED __builtin_amdgcn_sched_barrier(0)
; template <class Epi, class Sched, bool ALIGN_EPI = false, bool SP2 = false>
; __device__ __forceinline__ void gemm_phase(PG8_LAS unsigned char* lds, const Gemm g, const Sched& S, const Epi& E, const int tid) {
;     ...
;             PG8_WAIT_V(8); PG8_WAIT_L(0); PG8_BAR; PG8_MMA(1, 0, At, B0); PG8_MMA(1, 1, At, B1); PG8_BAR; PG8_SCHED;
;             PG8_LDB(B0, 1, 0); PG8_LDB(B1, 1, 1); PG8_SCHED; PG8_LDA(At, 1, 0); PG8_STAGE(PG8_SA(0, 1), a2 + hstep, voffA);
;             PG8_WAIT_V(8); PG8_WAIT_L(0); PG8_BAR; PG8_MMA(0, 0, At, B0); PG8_MMA(0, 1, At, B1); PG8_BAR; PG8_SCHED;
	s_setprio 1
	s_waitcnt lgkmcnt(0)
	v_mfma_f32_16x16x32_bf16 v[62:65], v[140:143], v[174:177], v[62:65]
	v_mfma_f32_16x16x32_bf16 v[58:61], v[150:153], v[174:177], v[58:61]
	v_mfma_f32_16x16x32_bf16 v[50:53], v[140:143], v[188:191], v[50:53]
	v_mfma_f32_16x16x32_bf16 v[42:45], v[150:153], v[188:191], v[42:45]
	v_mfma_f32_16x16x32_bf16 v[34:37], v[140:143], v[196:199], v[34:37]
	v_mfma_f32_16x16x32_bf16 v[26:29], v[150:153], v[196:199], v[26:29]
	v_mfma_f32_16x16x32_bf16 v[18:21], v[140:143], v[204:207], v[18:21]
	v_mfma_f32_16x16x32_bf16 v[10:13], v[150:153], v[204:207], v[10:13]
	v_mfma_f32_16x16x32_bf16 v[62:65], v[146:149], v[184:187], v[62:65]
	v_mfma_f32_16x16x32_bf16 v[58:61], v[154:157], v[184:187], v[58:61]
	v_mfma_f32_16x16x32_bf16 v[50:53], v[146:149], v[192:195], v[50:53]
	v_mfma_f32_16x16x32_bf16 v[42:45], v[154:157], v[192:195], v[42:45]
	v_mfma_f32_16x16x32_bf16 v[34:37], v[146:149], v[200:203], v[34:37]
	v_mfma_f32_16x16x32_bf16 v[26:29], v[154:157], v[200:203], v[26:29]
	v_mfma_f32_16x16x32_bf16 v[18:21], v[146:149], v[214:217], v[18:21]
	v_mfma_f32_16x16x32_bf16 v[10:13], v[154:157], v[214:217], v[10:13]
	s_setprio 0
	s_setprio 1
	v_mfma_f32_16x16x32_bf16 v[54:57], v[158:161], v[174:177], v[54:57]
	v_mfma_f32_16x16x32_bf16 v[46:49], v[166:169], v[174:177], v[46:49]
	v_mfma_f32_16x16x32_bf16 v[38:41], v[158:161], v[188:191], v[38:41]
	v_mfma_f32_16x16x32_bf16 v[30:33], v[166:169], v[188:191], v[30:33]
	v_mfma_f32_16x16x32_bf16 v[22:25], v[158:161], v[196:199], v[22:25]
	v_mfma_f32_16x16x32_bf16 v[14:17], v[166:169], v[196:199], v[14:17]
	v_mfma_f32_16x16x32_bf16 v[6:9], v[158:161], v[204:207], v[6:9]
	v_mfma_f32_16x16x32_bf16 v[2:5], v[166:169], v[204:207], v[2:5]
	v_mfma_f32_16x16x32_bf16 v[54:57], v[162:165], v[184:187], v[54:57]
	v_mfma_f32_16x16x32_bf16 v[46:49], v[170:173], v[184:187], v[46:49]
	v_mfma_f32_16x16x32_bf16 v[38:41], v[162:165], v[192:195], v[38:41]
	v_mfma_f32_16x16x32_bf16 v[30:33], v[170:173], v[192:195], v[30:33]
	v_mfma_f32_16x16x32_bf16 v[22:25], v[162:165], v[200:203], v[22:25]
	v_mfma_f32_16x16x32_bf16 v[14:17], v[170:173], v[200:203], v[14:17]
	v_mfma_f32_16x16x32_bf16 v[6:9], v[162:165], v[214:217], v[6:9]
	v_mfma_f32_16x16x32_bf16 v[2:5], v[170:173], v[214:217], v[2:5]
	s_barrier
	s_setprio 0
	v_or_b32_e32 v140, 0x18000, v145
	v_add_u32_e32 v146, 0x18400, v145
	v_add_u32_e32 v150, 0x18800, v145
	v_add_u32_e32 v154, 0x18c00, v145
	v_or_b32_e32 v158, 0x1c000, v145
	v_add_u32_e32 v162, 0x1c400, v145
	v_add_u32_e32 v166, 0x1c800, v145
	v_add_u32_e32 v170, 0x1cc00, v145
	ds_read_b128 v[140:143], v140
	ds_read_b128 v[146:149], v146
	ds_read_b128 v[150:153], v150
	ds_read_b128 v[154:157], v154
	ds_read_b128 v[158:161], v158
	ds_read_b128 v[162:165], v162
	ds_read_b128 v[166:169], v166
	ds_read_b128 v[170:173], v170
	s_add_u32 s90, s90, 0x40000
	s_addc_u32 s91, s91, 0
	s_mov_b32 m0, s8
	v_lshl_add_u64 v[220:221], s[90:91], 0, v[130:131]
	ds_read_b128 v[174:177], v144 offset:32768
	ds_read_b128 v[184:187], v144 offset:33792
	ds_read_b128 v[188:191], v144 offset:34816
	ds_read_b128 v[192:195], v144 offset:35840
	ds_read_b128 v[196:199], v144 offset:36864
	ds_read_b128 v[200:203], v144 offset:37888
	ds_read_b128 v[204:207], v144 offset:38912
	ds_read_b128 v[214:217], v144 offset:39936
	global_load_lds_dwordx4 v[220:221], off
	v_lshl_add_u64 v[220:221], s[90:91], 0, v[132:133]
	s_mov_b32 m0, s9
	s_nop 0
	global_load_lds_dwordx4 v[220:221], off
	s_waitcnt vmcnt(8)
	s_waitcnt lgkmcnt(0)
	s_barrier
	s_setprio 1
	s_waitcnt lgkmcnt(0)
	v_mfma_f32_16x16x32_bf16 v[126:129], v[140:143], v[174:177], v[126:129]
	v_mfma_f32_16x16x32_bf16 v[122:125], v[150:153], v[174:177], v[122:125]
	v_mfma_f32_16x16x32_bf16 v[114:117], v[140:143], v[188:191], v[114:117]
	v_mfma_f32_16x16x32_bf16 v[106:109], v[150:153], v[188:191], v[106:109]
	v_mfma_f32_16x16x32_bf16 v[98:101], v[140:143], v[196:199], v[98:101]
	v_mfma_f32_16x16x32_bf16 v[90:93], v[150:153], v[196:199], v[90:93]
	v_mfma_f32_16x16x32_bf16 v[82:85], v[140:143], v[204:207], v[82:85]
	v_mfma_f32_16x16x32_bf16 v[74:77], v[150:153], v[204:207], v[74:77]
	v_mfma_f32_16x16x32_bf16 v[126:129], v[146:149], v[184:187], v[126:129]
	v_mfma_f32_16x16x32_bf16 v[122:125], v[154:157], v[184:187], v[122:125]
	v_mfma_f32_16x16x32_bf16 v[114:117], v[146:149], v[192:195], v[114:117]
	v_mfma_f32_16x16x32_bf16 v[106:109], v[154:157], v[192:195], v[106:109]
	v_mfma_f32_16x16x32_bf16 v[98:101], v[146:149], v[200:203], v[98:101]
	v_mfma_f32_16x16x32_bf16 v[90:93], v[154:157], v[200:203], v[90:93]
	v_mfma_f32_16x16x32_bf16 v[82:85], v[146:149], v[214:217], v[82:85]
	v_mfma_f32_16x16x32_bf16 v[74:77], v[154:157], v[214:217], v[74:77]
	s_setprio 0
	s_setprio 1
	v_mfma_f32_16x16x32_bf16 v[118:121], v[158:161], v[174:177], v[118:121]
	v_mfma_f32_16x16x32_bf16 v[110:113], v[166:169], v[174:177], v[110:113]
	v_mfma_f32_16x16x32_bf16 v[102:105], v[158:161], v[188:191], v[102:105]
	v_mfma_f32_16x16x32_bf16 v[94:97], v[166:169], v[188:191], v[94:97]
	v_mfma_f32_16x16x32_bf16 v[86:89], v[158:161], v[196:199], v[86:89]
	v_mfma_f32_16x16x32_bf16 v[78:81], v[166:169], v[196:199], v[78:81]
	v_mfma_f32_16x16x32_bf16 v[70:73], v[158:161], v[204:207], v[70:73]
	v_mfma_f32_16x16x32_bf16 v[66:69], v[166:169], v[204:207], v[66:69]
	v_mfma_f32_16x16x32_bf16 v[118:121], v[162:165], v[184:187], v[118:121]
	v_mfma_f32_16x16x32_bf16 v[110:113], v[170:173], v[184:187], v[110:113]
	v_mfma_f32_16x16x32_bf16 v[102:105], v[162:165], v[192:195], v[102:105]
	v_mfma_f32_16x16x32_bf16 v[94:97], v[170:173], v[192:195], v[94:97]
	v_mfma_f32_16x16x32_bf16 v[86:89], v[162:165], v[200:203], v[86:89]
	v_mfma_f32_16x16x32_bf16 v[78:81], v[170:173], v[200:203], v[78:81]
	v_mfma_f32_16x16x32_bf16 v[70:73], v[162:165], v[214:217], v[70:73]
	v_mfma_f32_16x16x32_bf16 v[66:69], v[170:173], v[214:217], v[66:69]
	s_barrier
; #define PG8_STAGE(bufoff, gbase, voff) do { _Pragma("unroll") for (int _i = 0; _i < 2; ++_i) \
;         __builtin_amdgcn_global_load_lds((const unsigned*)((const char*)(gbase) + (voff)[_i]), (PG8_LAS unsigned*)(lds + (bufoff) + ldsw + _i * 8192), 16, 0, 0); } while (0)
; #define PG8_LDA(dst, b, h) do { _Pragma("unroll") for (int m = 0; m < 4; ++m) _Pragma("unroll") for (int k = 0; k < 2; ++k) dst[m][k] = *(const PG8_LAS bf16x8*)(lds + PG8_SA(b, h) + aoff + m * 2048 + k * 1024); } while (0)
; #define PG8_MMA(ai, bj, At, Bt) do { __builtin_amdgcn_s_setprio(1); _Pragma("unroll") for (int m = 0; m < 4; ++m) _Pragma("unroll") for (int n = 0; n < 2; ++n) _Pragma("unroll") for (int k = 0; k < 2; ++k) \
;         acc[ai][bj][m][n] = __builtin_amdgcn_mfma_f32_16x16x32_bf16(Bt[n][k], At[m][k], acc[ai][bj][m][n], 0, 0, 0); __builtin_amdgcn_s_setprio(0); } while (0)
; #define PG8_WAIT_V(n) asm volatile("s_waitcnt vmcnt(" #n ")" ::: "memory")
; #define PG8_WAIT_L(n) asm volatile("s_waitcnt lgkmcnt(" #n ")" ::: "memory")
; #define PG8_BAR __builtin_amdgcn_s_barrier()
; #define PG8_SCHED __builtin_amdgcn_sched_barrier(0)
; template <class Epi, class Sched, bool ALIGN_EPI = false, bool SP2 = false>
; __device__ __forceinline__ void gemm_phase(PG8_LAS unsigned char* lds, const Gemm g, const Sched& S, const Epi& E, const int tid) {
;     ...
;             PG8_WAIT_V(8); PG8_WAIT_L(0); PG8_BAR; PG8_MMA(0, 0, At, B0); PG8_MMA(0, 1, At, B1); PG8_BAR; PG8_SCHED;
;             PG8_LDA(At, 1, 1); PG8_STAGE(PG8_SB(1, 0), b3, voffB); PG8_STAGE(PG8_SB(1, 1), b3 + hstep, voffB); PG8_STAGE(PG8_SA(1, 0), a3, voffA);
;             PG8_WAIT_V(8); PG8_WAIT_L(0); PG8_BAR; PG8_MMA(1, 0, At, B0); PG8_MMA(1, 1, At, B1); PG8_BAR; PG8_SCHED;
;     ...
;         if constexpr (ALIGN_EPI) { if (wr == 0) PG8_BAR; }
	s_setprio 0
	s_mov_b32 m0, s17
	v_lshl_add_u64 v[178:179], v[178:179], 0, s[12:13]
	s_add_u32 s88, s88, 0x40080
	ds_read_b128 v[174:177], v144 offset:49152
	ds_read_b128 v[184:187], v144 offset:50176
	ds_read_b128 v[188:191], v144 offset:51200
	ds_read_b128 v[192:195], v144 offset:52224
	ds_read_b128 v[196:199], v144 offset:53248
	ds_read_b128 v[200:203], v144 offset:54272
	ds_read_b128 v[204:207], v144 offset:55296
	ds_read_b128 v[214:217], v144 offset:56320
	global_load_lds_dwordx4 v[178:179], off
	v_lshl_add_u64 v[178:179], v[180:181], 0, s[12:13]
	s_mov_b32 m0, s20
	s_addc_u32 s89, s89, 0
	global_load_lds_dwordx4 v[178:179], off
	v_lshl_add_u64 v[178:179], s[88:89], 0, v[0:1]
	s_mov_b32 m0, s26
	s_nop 0
	global_load_lds_dwordx4 v[178:179], off
	v_lshl_add_u64 v[178:179], s[88:89], 0, v[134:135]
	s_mov_b32 m0, s27
	s_nop 0
	global_load_lds_dwordx4 v[178:179], off
	v_lshl_add_u64 v[178:179], v[182:183], 0, s[12:13]
	s_mov_b32 m0, s21
	s_nop 0
	global_load_lds_dwordx4 v[178:179], off
	v_lshl_add_u64 v[178:179], v[218:219], 0, s[12:13]
	s_mov_b32 m0, s24
	s_nop 0
	global_load_lds_dwordx4 v[178:179], off
	s_waitcnt vmcnt(8)
	s_waitcnt lgkmcnt(0)
	s_barrier
	s_setprio 1
	s_waitcnt lgkmcnt(0)
	v_mfma_f32_16x16x32_bf16 v[62:65], v[140:143], v[174:177], v[62:65]
	v_mfma_f32_16x16x32_bf16 v[58:61], v[150:153], v[174:177], v[58:61]
	v_mfma_f32_16x16x32_bf16 v[50:53], v[140:143], v[188:191], v[50:53]
	v_mfma_f32_16x16x32_bf16 v[42:45], v[150:153], v[188:191], v[42:45]
	v_mfma_f32_16x16x32_bf16 v[34:37], v[140:143], v[196:199], v[34:37]
	v_mfma_f32_16x16x32_bf16 v[26:29], v[150:153], v[196:199], v[26:29]
	v_mfma_f32_16x16x32_bf16 v[18:21], v[140:143], v[204:207], v[18:21]
	v_mfma_f32_16x16x32_bf16 v[10:13], v[150:153], v[204:207], v[10:13]
	v_mfma_f32_16x16x32_bf16 v[62:65], v[146:149], v[184:187], v[62:65]
	v_mfma_f32_16x16x32_bf16 v[58:61], v[154:157], v[184:187], v[58:61]
	v_mfma_f32_16x16x32_bf16 v[50:53], v[146:149], v[192:195], v[50:53]
	v_mfma_f32_16x16x32_bf16 v[42:45], v[154:157], v[192:195], v[42:45]
	v_mfma_f32_16x16x32_bf16 v[34:37], v[146:149], v[200:203], v[34:37]
	v_mfma_f32_16x16x32_bf16 v[26:29], v[154:157], v[200:203], v[26:29]
	v_mfma_f32_16x16x32_bf16 v[18:21], v[146:149], v[214:217], v[18:21]
	v_mfma_f32_16x16x32_bf16 v[10:13], v[154:157], v[214:217], v[10:13]
	s_setprio 0
	s_setprio 1
	v_mfma_f32_16x16x32_bf16 v[54:57], v[158:161], v[174:177], v[54:57]
	v_mfma_f32_16x16x32_bf16 v[46:49], v[166:169], v[174:177], v[46:49]
	v_mfma_f32_16x16x32_bf16 v[38:41], v[158:161], v[188:191], v[38:41]
	v_mfma_f32_16x16x32_bf16 v[30:33], v[166:169], v[188:191], v[30:33]
	v_mfma_f32_16x16x32_bf16 v[22:25], v[158:161], v[196:199], v[22:25]
	v_mfma_f32_16x16x32_bf16 v[14:17], v[166:169], v[196:199], v[14:17]
	v_mfma_f32_16x16x32_bf16 v[6:9], v[158:161], v[204:207], v[6:9]
	v_mfma_f32_16x16x32_bf16 v[2:5], v[166:169], v[204:207], v[2:5]
	v_mfma_f32_16x16x32_bf16 v[54:57], v[162:165], v[184:187], v[54:57]
	v_mfma_f32_16x16x32_bf16 v[46:49], v[170:173], v[184:187], v[46:49]
	v_mfma_f32_16x16x32_bf16 v[38:41], v[162:165], v[192:195], v[38:41]
	v_mfma_f32_16x16x32_bf16 v[30:33], v[170:173], v[192:195], v[30:33]
	v_mfma_f32_16x16x32_bf16 v[22:25], v[162:165], v[200:203], v[22:25]
	v_mfma_f32_16x16x32_bf16 v[14:17], v[170:173], v[200:203], v[14:17]
	v_mfma_f32_16x16x32_bf16 v[6:9], v[162:165], v[214:217], v[6:9]
	v_mfma_f32_16x16x32_bf16 v[2:5], v[170:173], v[214:217], v[2:5]
	s_barrier
	s_setprio 0
	s_add_i32 s96, s96, 2
	s_add_u32 s86, s86, 0x100
	s_addc_u32 s87, s87, 0
	s_add_u32 s51, s51, 0x100
	s_addc_u32 s85, s85, 0
	s_cmp_gt_u32 s96, 13
	s_cbranch_scc0 .LBB0_499
	s_and_b64 vcc, exec, s[14:15]
	s_cbranch_vccz .LBB0_502
	s_barrier

; #define PG8_STAGE(bufoff, gbase, voff) do { _Pragma("unroll") for (int _i = 0; _i < 2; ++_i) \
;         __builtin_amdgcn_global_load_lds((const unsigned*)((const char*)(gbase) + (voff)[_i]), (PG8_LAS unsigned*)(lds + (bufoff) + ldsw + _i * 8192), 16, 0, 0); } while (0)
; #define PG8_LDA(dst, b, h) do { _Pragma("unroll") for (int m = 0; m < 4; ++m) _Pragma("unroll") for (int k = 0; k < 2; ++k) dst[m][k] = *(const PG8_LAS bf16x8*)(lds + PG8_SA(b, h) + aoff + m * 2048 + k * 1024); } while (0)
; #define PG8_LDB(dst, b, h) do { _Pragma("unroll") for (int n = 0; n < 2; ++n) _Pragma("unroll") for (int k = 0; k < 2; ++k) dst[n][k] = *(const PG8_LAS bf16x8*)(lds + PG8_SB(b, h) + boff + n * 2048 + k * 1024); } while (0)
; #define PG8_MMA(ai, bj, At, Bt) do { __builtin_amdgcn_s_setprio(1); _Pragma("unroll") for (int m = 0; m < 4; ++m) _Pragma("unroll") for (int n = 0; n < 2; ++n) _Pragma("unroll") for (int k = 0; k < 2; ++k) \
;         acc[ai][bj][m][n] = __builtin_amdgcn_mfma_f32_16x16x32_bf16(Bt[n][k], At[m][k], acc[ai][bj][m][n], 0, 0, 0); __builtin_amdgcn_s_setprio(0); } while (0)
; #define PG8_WAIT_V(n) asm volatile("s_waitcnt vmcnt(" #n ")" ::: "memory")
; #define PG8_WAIT_L(n) asm volatile("s_waitcnt lgkmcnt(" #n ")" ::: "memory")
; template <class Epi, class Sched, bool ALIGN_EPI = false, bool SP2 = false>
; __device__ __forceinline__ void gemm_phase(PG8_LAS unsigned char* lds, const Gemm g, const Sched& S, const Epi& E, const int tid) {
;     ...
;             const bool last = (t == nt - 2);
;             const char* a1 = cA + (size_t)(t + 1) * kstep;
;             const char* a2 = last ? nA : cA + (size_t)(t + 2) * kstep; const char* b2 = last ? nB : cB + (size_t)(t + 2) * kstep;
;             const char* a3 = a2 + kstep; const char* b3 = b2 + kstep;
;             if (last && has_next) S.a_ready(nxt);
;             if constexpr (SP2) {
;             PG8_LDB(B0, 0, 0); PG8_LDB(B1, 0, 1); PG8_SCHED; PG8_LDA(At, 0, 0); PG8_STAGE(PG8_SA(1, 1), a1 + hstep, voffA);
;             PG8_WAIT_V(8); PG8_WAIT_L(0); PG8_BAR; PG8_MMA(0, 0, At, B0); PG8_MMA(0, 1, At, B1); PG8_BAR; PG8_SCHED;
;             PG8_LDA(At, 0, 1); PG8_STAGE(PG8_SB(0, 0), b2, voffB); PG8_STAGE(PG8_SB(0, 1), b2 + hstep, voffB); PG8_STAGE(PG8_SA(0, 0), a2, voffA);
;             PG8_WAIT_V(8); PG8_WAIT_L(0); PG8_BAR; PG8_MMA(1, 0, At, B0); PG8_MMA(1, 1, At, B1); PG8_BAR; PG8_SCHED;
.LBB0_684:
	v_or_b32_e32 v130, 0x10000, v177
	v_add_u32_e32 v134, 0x10400, v177
	v_add_u32_e32 v138, 0x10800, v177
	v_add_u32_e32 v142, 0x10c00, v177
	v_or_b32_e32 v146, 0x14000, v177
	v_add_u32_e32 v157, 0x14400, v177
	ds_read_b128 v[130:133], v130
	ds_read_b128 v[134:137], v134
	ds_read_b128 v[138:141], v138
	ds_read_b128 v[142:145], v142
	ds_read_b128 v[146:149], v146
	ds_read_b128 v[164:167], v157
	v_add_u32_e32 v157, 0x14800, v177
	v_add_u32_e32 v172, 0x14c00, v177
	s_add_i32 s92, s88, 2
	ds_read_b128 v[168:171], v157
	ds_read_b128 v[172:175], v172
	s_add_u32 s93, s86, 0x80
	s_addc_u32 s89, s87, 0
	s_cmp_eq_u32 s20, s88
	s_cselect_b32 s88, s38, s93
	s_cselect_b32 s89, s39, s89
	s_cselect_b32 s95, s85, vcc_hi
	s_cselect_b32 s94, s84, vcc_lo
	v_lshl_add_u64 v[178:179], s[86:87], 0, v[160:161]
	s_add_i32 m0, s17, 0xc000
	ds_read_b128 v[184:187], v176
	ds_read_b128 v[188:191], v176 offset:1024
	ds_read_b128 v[192:195], v176 offset:2048
	ds_read_b128 v[196:199], v176 offset:3072
	ds_read_b128 v[200:203], v176 offset:4096
	ds_read_b128 v[204:207], v176 offset:5120
	ds_read_b128 v[214:217], v176 offset:6144
	ds_read_b128 v[218:221], v176 offset:7168
	global_load_lds_dwordx4 v[178:179], off
	v_lshl_add_u64 v[178:179], s[86:87], 0, v[162:163]
	s_add_i32 m0, s17, 0xe000
	s_nop 0
	global_load_lds_dwordx4 v[178:179], off
	s_waitcnt vmcnt(8)
	s_waitcnt lgkmcnt(0)
	s_barrier
	s_setprio 1
	s_waitcnt lgkmcnt(0)
	v_mfma_f32_16x16x32_bf16 v[126:129], v[130:133], v[184:187], v[126:129]
	v_mfma_f32_16x16x32_bf16 v[122:125], v[138:141], v[184:187], v[122:125]
	v_mfma_f32_16x16x32_bf16 v[110:113], v[130:133], v[192:195], v[110:113]
	v_mfma_f32_16x16x32_bf16 v[106:109], v[138:141], v[192:195], v[106:109]
	v_mfma_f32_16x16x32_bf16 v[94:97], v[130:133], v[200:203], v[94:97]
	v_mfma_f32_16x16x32_bf16 v[90:93], v[138:141], v[200:203], v[90:93]
	v_mfma_f32_16x16x32_bf16 v[78:81], v[130:133], v[214:217], v[78:81]
	v_mfma_f32_16x16x32_bf16 v[74:77], v[138:141], v[214:217], v[74:77]
	v_mfma_f32_16x16x32_bf16 v[126:129], v[134:137], v[188:191], v[126:129]
	v_mfma_f32_16x16x32_bf16 v[122:125], v[142:145], v[188:191], v[122:125]
	v_mfma_f32_16x16x32_bf16 v[110:113], v[134:137], v[196:199], v[110:113]
	v_mfma_f32_16x16x32_bf16 v[106:109], v[142:145], v[196:199], v[106:109]
	v_mfma_f32_16x16x32_bf16 v[94:97], v[134:137], v[204:207], v[94:97]
	v_mfma_f32_16x16x32_bf16 v[90:93], v[142:145], v[204:207], v[90:93]
	v_mfma_f32_16x16x32_bf16 v[78:81], v[134:137], v[218:221], v[78:81]
	v_mfma_f32_16x16x32_bf16 v[74:77], v[142:145], v[218:221], v[74:77]
	s_setprio 0
	s_setprio 1
	v_mfma_f32_16x16x32_bf16 v[118:121], v[146:149], v[184:187], v[118:121]
	v_mfma_f32_16x16x32_bf16 v[114:117], v[168:171], v[184:187], v[114:117]
	v_mfma_f32_16x16x32_bf16 v[102:105], v[146:149], v[192:195], v[102:105]
	v_mfma_f32_16x16x32_bf16 v[98:101], v[168:171], v[192:195], v[98:101]
	v_mfma_f32_16x16x32_bf16 v[86:89], v[146:149], v[200:203], v[86:89]
	v_mfma_f32_16x16x32_bf16 v[82:85], v[168:171], v[200:203], v[82:85]
	v_mfma_f32_16x16x32_bf16 v[70:73], v[146:149], v[214:217], v[70:73]
	v_mfma_f32_16x16x32_bf16 v[66:69], v[168:171], v[214:217], v[66:69]
	v_mfma_f32_16x16x32_bf16 v[118:121], v[164:167], v[188:191], v[118:121]
	v_mfma_f32_16x16x32_bf16 v[114:117], v[172:175], v[188:191], v[114:117]
	v_mfma_f32_16x16x32_bf16 v[102:105], v[164:167], v[196:199], v[102:105]
	v_mfma_f32_16x16x32_bf16 v[98:101], v[172:175], v[196:199], v[98:101]
	v_mfma_f32_16x16x32_bf16 v[86:89], v[164:167], v[204:207], v[86:89]
	v_mfma_f32_16x16x32_bf16 v[82:85], v[172:175], v[204:207], v[82:85]
	v_mfma_f32_16x16x32_bf16 v[70:73], v[164:167], v[218:221], v[70:73]
	v_mfma_f32_16x16x32_bf16 v[66:69], v[172:175], v[218:221], v[66:69]
	s_barrier
	s_setprio 0
	s_mov_b32 m0, s26
	v_lshl_add_u64 v[178:179], s[94:95], 0, v[0:1]
	v_lshl_add_u64 v[180:181], s[94:95], 0, v[150:151]
	s_add_u32 s94, s94, s40
	ds_read_b128 v[184:187], v176 offset:16384
	ds_read_b128 v[188:191], v176 offset:17408
	ds_read_b128 v[192:195], v176 offset:18432
	ds_read_b128 v[196:199], v176 offset:19456
	ds_read_b128 v[200:203], v176 offset:20480
	ds_read_b128 v[204:207], v176 offset:21504
	ds_read_b128 v[214:217], v176 offset:22528
	ds_read_b128 v[218:221], v176 offset:23552
	global_load_lds_dwordx4 v[178:179], off
	s_mov_b32 m0, s27
	s_addc_u32 s95, s95, 0
	global_load_lds_dwordx4 v[180:181], off
	v_lshl_add_u64 v[182:183], s[94:95], 0, v[0:1]
	s_mov_b32 m0, s34
	v_lshl_add_u64 v[222:223], s[94:95], 0, v[150:151]
	global_load_lds_dwordx4 v[182:183], off
	s_mov_b32 m0, s35
	v_lshl_add_u64 v[224:225], s[88:89], 0, v[154:155]
	global_load_lds_dwordx4 v[222:223], off
	s_mov_b32 m0, s17
	v_lshl_add_u64 v[226:227], s[88:89], 0, v[152:153]
	global_load_lds_dwordx4 v[224:225], off
	s_mov_b32 m0, s50
	s_nop 0
	global_load_lds_dwordx4 v[226:227], off
	s_waitcnt vmcnt(8)
	s_waitcnt lgkmcnt(0)
	s_barrier
; #define PG8_STAGE(bufoff, gbase, voff) do { _Pragma("unroll") for (int _i = 0; _i < 2; ++_i) \
;         __builtin_amdgcn_global_load_lds((const unsigned*)((const char*)(gbase) + (voff)[_i]), (PG8_LAS unsigned*)(lds + (bufoff) + ldsw + _i * 8192), 16, 0, 0); } while (0)
; #define PG8_LDA(dst, b, h) do { _Pragma("unroll") for (int m = 0; m < 4; ++m) _Pragma("unroll") for (int k = 0; k < 2; ++k) dst[m][k] = *(const PG8_LAS bf16x8*)(lds + PG8_SA(b, h) + aoff + m * 2048 + k * 1024); } while (0)
; #define PG8_LDB(dst, b, h) do { _Pragma("unroll") for (int n = 0; n < 2; ++n) _Pragma("unroll") for (int k = 0; k < 2; ++k) dst[n][k] = *(const PG8_LAS bf16x8*)(lds + PG8_SB(b, h) + boff + n * 2048 + k * 1024); } while (0)
; #define PG8_MMA(ai, bj, At, Bt) do { __builtin_amdgcn_s_setprio(1); _Pragma("unroll") for (int m = 0; m < 4; ++m) _Pragma("unroll") for (int n = 0; n < 2; ++n) _Pragma("unroll") for (int k = 0; k < 2; ++k) \
;         acc[ai][bj][m][n] = __builtin_amdgcn_mfma_f32_16x16x32_bf16(Bt[n][k], At[m][k], acc[ai][bj][m][n], 0, 0, 0); __builtin_amdgcn_s_setprio(0); } while (0)
; #define PG8_WAIT_V(n) asm volatile("s_waitcnt vmcnt(" #n ")" ::: "memory")
; #define PG8_WAIT_L(n) asm volatile("s_waitcnt lgkmcnt(" #n ")" ::: "memory")
; #define PG8_BAR __builtin_amdgcn_s_barrier()
; #define PG8_SCHED __builtin_amdgcn_sched_barrier(0)
; template <class Epi, class Sched, bool ALIGN_EPI = false, bool SP2 = false>
; __device__ __forceinline__ void gemm_phase(PG8_LAS unsigned char* lds, const Gemm g, const Sched& S, const Epi& E, const int tid) {
;     ...
;             PG8_WAIT_V(8); PG8_WAIT_L(0); PG8_BAR; PG8_MMA(1, 0, At, B0); PG8_MMA(1, 1, At, B1); PG8_BAR; PG8_SCHED;
;             PG8_LDB(B0, 1, 0); PG8_LDB(B1, 1, 1); PG8_SCHED; PG8_LDA(At, 1, 0); PG8_STAGE(PG8_SA(0, 1), a2 + hstep, voffA);
;             PG8_WAIT_V(8); PG8_WAIT_L(0); PG8_BAR; PG8_MMA(0, 0, At, B0); PG8_MMA(0, 1, At, B1); PG8_BAR; PG8_SCHED;
	s_setprio 1
	s_waitcnt lgkmcnt(0)
	v_mfma_f32_16x16x32_bf16 v[62:65], v[130:133], v[184:187], v[62:65]
	v_mfma_f32_16x16x32_bf16 v[58:61], v[138:141], v[184:187], v[58:61]
	v_mfma_f32_16x16x32_bf16 v[46:49], v[130:133], v[192:195], v[46:49]
	v_mfma_f32_16x16x32_bf16 v[42:45], v[138:141], v[192:195], v[42:45]
	v_mfma_f32_16x16x32_bf16 v[30:33], v[130:133], v[200:203], v[30:33]
	v_mfma_f32_16x16x32_bf16 v[26:29], v[138:141], v[200:203], v[26:29]
	v_mfma_f32_16x16x32_bf16 v[14:17], v[130:133], v[214:217], v[14:17]
	v_mfma_f32_16x16x32_bf16 v[10:13], v[138:141], v[214:217], v[10:13]
	v_mfma_f32_16x16x32_bf16 v[62:65], v[134:137], v[188:191], v[62:65]
	v_mfma_f32_16x16x32_bf16 v[58:61], v[142:145], v[188:191], v[58:61]
	v_mfma_f32_16x16x32_bf16 v[46:49], v[134:137], v[196:199], v[46:49]
	v_mfma_f32_16x16x32_bf16 v[42:45], v[142:145], v[196:199], v[42:45]
	v_mfma_f32_16x16x32_bf16 v[30:33], v[134:137], v[204:207], v[30:33]
	v_mfma_f32_16x16x32_bf16 v[26:29], v[142:145], v[204:207], v[26:29]
	v_mfma_f32_16x16x32_bf16 v[14:17], v[134:137], v[218:221], v[14:17]
	v_mfma_f32_16x16x32_bf16 v[10:13], v[142:145], v[218:221], v[10:13]
	s_setprio 0
	s_setprio 1
	v_mfma_f32_16x16x32_bf16 v[54:57], v[146:149], v[184:187], v[54:57]
	v_mfma_f32_16x16x32_bf16 v[50:53], v[168:171], v[184:187], v[50:53]
	v_mfma_f32_16x16x32_bf16 v[38:41], v[146:149], v[192:195], v[38:41]
	v_mfma_f32_16x16x32_bf16 v[34:37], v[168:171], v[192:195], v[34:37]
	v_mfma_f32_16x16x32_bf16 v[22:25], v[146:149], v[200:203], v[22:25]
	v_mfma_f32_16x16x32_bf16 v[18:21], v[168:171], v[200:203], v[18:21]
	v_mfma_f32_16x16x32_bf16 v[6:9], v[146:149], v[214:217], v[6:9]
	v_mfma_f32_16x16x32_bf16 v[2:5], v[168:171], v[214:217], v[2:5]
	v_mfma_f32_16x16x32_bf16 v[54:57], v[164:167], v[188:191], v[54:57]
	v_mfma_f32_16x16x32_bf16 v[50:53], v[172:175], v[188:191], v[50:53]
	v_mfma_f32_16x16x32_bf16 v[38:41], v[164:167], v[196:199], v[38:41]
	v_mfma_f32_16x16x32_bf16 v[34:37], v[172:175], v[196:199], v[34:37]
	v_mfma_f32_16x16x32_bf16 v[22:25], v[164:167], v[204:207], v[22:25]
	v_mfma_f32_16x16x32_bf16 v[18:21], v[172:175], v[204:207], v[18:21]
	v_mfma_f32_16x16x32_bf16 v[6:9], v[164:167], v[218:221], v[6:9]
	v_mfma_f32_16x16x32_bf16 v[2:5], v[172:175], v[218:221], v[2:5]
	s_barrier
	s_setprio 0
	v_or_b32_e32 v130, 0x18000, v177
	v_add_u32_e32 v134, 0x18400, v177
	v_add_u32_e32 v138, 0x18800, v177
	v_add_u32_e32 v142, 0x18c00, v177
	v_or_b32_e32 v146, 0x1c000, v177
	v_add_u32_e32 v157, 0x1c400, v177
	ds_read_b128 v[130:133], v130
	ds_read_b128 v[134:137], v134
	ds_read_b128 v[138:141], v138
	ds_read_b128 v[142:145], v142
	ds_read_b128 v[146:149], v146
	ds_read_b128 v[164:167], v157
	v_add_u32_e32 v157, 0x1c800, v177
	v_add_u32_e32 v172, 0x1cc00, v177
	ds_read_b128 v[168:171], v157
	ds_read_b128 v[172:175], v172
	s_add_u32 s88, s88, s40
	s_addc_u32 s89, s89, 0
	s_mov_b32 m0, s51
	v_lshl_add_u64 v[228:229], s[88:89], 0, v[154:155]
	ds_read_b128 v[184:187], v176 offset:32768
	ds_read_b128 v[188:191], v176 offset:33792
	ds_read_b128 v[192:195], v176 offset:34816
	ds_read_b128 v[196:199], v176 offset:35840
	ds_read_b128 v[200:203], v176 offset:36864
	ds_read_b128 v[204:207], v176 offset:37888
	ds_read_b128 v[214:217], v176 offset:38912
	ds_read_b128 v[218:221], v176 offset:39936
	global_load_lds_dwordx4 v[228:229], off
	v_lshl_add_u64 v[228:229], s[88:89], 0, v[152:153]
	s_mov_b32 m0, s90
	s_nop 0
	global_load_lds_dwordx4 v[228:229], off
	s_waitcnt vmcnt(8)
	s_waitcnt lgkmcnt(0)
	s_barrier
	s_setprio 1
	s_waitcnt lgkmcnt(0)
	v_mfma_f32_16x16x32_bf16 v[126:129], v[130:133], v[184:187], v[126:129]
	v_mfma_f32_16x16x32_bf16 v[122:125], v[138:141], v[184:187], v[122:125]
	v_mfma_f32_16x16x32_bf16 v[110:113], v[130:133], v[192:195], v[110:113]
	v_mfma_f32_16x16x32_bf16 v[106:109], v[138:141], v[192:195], v[106:109]
	v_mfma_f32_16x16x32_bf16 v[94:97], v[130:133], v[200:203], v[94:97]
	v_mfma_f32_16x16x32_bf16 v[90:93], v[138:141], v[200:203], v[90:93]
	v_mfma_f32_16x16x32_bf16 v[78:81], v[130:133], v[214:217], v[78:81]
	v_mfma_f32_16x16x32_bf16 v[74:77], v[138:141], v[214:217], v[74:77]
	v_mfma_f32_16x16x32_bf16 v[126:129], v[134:137], v[188:191], v[126:129]
	v_mfma_f32_16x16x32_bf16 v[122:125], v[142:145], v[188:191], v[122:125]
	v_mfma_f32_16x16x32_bf16 v[110:113], v[134:137], v[196:199], v[110:113]
	v_mfma_f32_16x16x32_bf16 v[106:109], v[142:145], v[196:199], v[106:109]
	v_mfma_f32_16x16x32_bf16 v[94:97], v[134:137], v[204:207], v[94:97]
	v_mfma_f32_16x16x32_bf16 v[90:93], v[142:145], v[204:207], v[90:93]
	v_mfma_f32_16x16x32_bf16 v[78:81], v[134:137], v[218:221], v[78:81]
	v_mfma_f32_16x16x32_bf16 v[74:77], v[142:145], v[218:221], v[74:77]
	s_setprio 0
	s_setprio 1
	v_mfma_f32_16x16x32_bf16 v[118:121], v[146:149], v[184:187], v[118:121]
	v_mfma_f32_16x16x32_bf16 v[114:117], v[168:171], v[184:187], v[114:117]
	v_mfma_f32_16x16x32_bf16 v[102:105], v[146:149], v[192:195], v[102:105]
	v_mfma_f32_16x16x32_bf16 v[98:101], v[168:171], v[192:195], v[98:101]
	v_mfma_f32_16x16x32_bf16 v[86:89], v[146:149], v[200:203], v[86:89]
	v_mfma_f32_16x16x32_bf16 v[82:85], v[168:171], v[200:203], v[82:85]
	v_mfma_f32_16x16x32_bf16 v[70:73], v[146:149], v[214:217], v[70:73]
	v_mfma_f32_16x16x32_bf16 v[66:69], v[168:171], v[214:217], v[66:69]
	v_mfma_f32_16x16x32_bf16 v[118:121], v[164:167], v[188:191], v[118:121]
	v_mfma_f32_16x16x32_bf16 v[114:117], v[172:175], v[188:191], v[114:117]
	v_mfma_f32_16x16x32_bf16 v[102:105], v[164:167], v[196:199], v[102:105]
	v_mfma_f32_16x16x32_bf16 v[98:101], v[172:175], v[196:199], v[98:101]
	v_mfma_f32_16x16x32_bf16 v[86:89], v[164:167], v[204:207], v[86:89]
	v_mfma_f32_16x16x32_bf16 v[82:85], v[172:175], v[204:207], v[82:85]
	v_mfma_f32_16x16x32_bf16 v[70:73], v[164:167], v[218:221], v[70:73]
	v_mfma_f32_16x16x32_bf16 v[66:69], v[172:175], v[218:221], v[66:69]
	s_barrier
; #define PG8_STAGE(bufoff, gbase, voff) do { _Pragma("unroll") for (int _i = 0; _i < 2; ++_i) \
;         __builtin_amdgcn_global_load_lds((const unsigned*)((const char*)(gbase) + (voff)[_i]), (PG8_LAS unsigned*)(lds + (bufoff) + ldsw + _i * 8192), 16, 0, 0); } while (0)
; #define PG8_LDA(dst, b, h) do { _Pragma("unroll") for (int m = 0; m < 4; ++m) _Pragma("unroll") for (int k = 0; k < 2; ++k) dst[m][k] = *(const PG8_LAS bf16x8*)(lds + PG8_SA(b, h) + aoff + m * 2048 + k * 1024); } while (0)
; #define PG8_MMA(ai, bj, At, Bt) do { __builtin_amdgcn_s_setprio(1); _Pragma("unroll") for (int m = 0; m < 4; ++m) _Pragma("unroll") for (int n = 0; n < 2; ++n) _Pragma("unroll") for (int k = 0; k < 2; ++k) \
;         acc[ai][bj][m][n] = __builtin_amdgcn_mfma_f32_16x16x32_bf16(Bt[n][k], At[m][k], acc[ai][bj][m][n], 0, 0, 0); __builtin_amdgcn_s_setprio(0); } while (0)
; #define PG8_WAIT_V(n) asm volatile("s_waitcnt vmcnt(" #n ")" ::: "memory")
; #define PG8_WAIT_L(n) asm volatile("s_waitcnt lgkmcnt(" #n ")" ::: "memory")
; #define PG8_BAR __builtin_amdgcn_s_barrier()
; #define PG8_SCHED __builtin_amdgcn_sched_barrier(0)
; template <class Epi, class Sched, bool ALIGN_EPI = false, bool SP2 = false>
; __device__ __forceinline__ void gemm_phase(PG8_LAS unsigned char* lds, const Gemm g, const Sched& S, const Epi& E, const int tid) {
;     ...
;             PG8_WAIT_V(8); PG8_WAIT_L(0); PG8_BAR; PG8_MMA(0, 0, At, B0); PG8_MMA(0, 1, At, B1); PG8_BAR; PG8_SCHED;
;             PG8_LDA(At, 1, 1); PG8_STAGE(PG8_SB(1, 0), b3, voffB); PG8_STAGE(PG8_SB(1, 1), b3 + hstep, voffB); PG8_STAGE(PG8_SA(1, 0), a3, voffA);
;             PG8_WAIT_V(8); PG8_WAIT_L(0); PG8_BAR; PG8_MMA(1, 0, At, B0); PG8_MMA(1, 1, At, B1); PG8_BAR; PG8_SCHED;
;     ...
;         if constexpr (ALIGN_EPI) { if (wr == 0) PG8_BAR; }
	s_setprio 0
	s_mov_b32 m0, s91
	v_lshl_add_u64 v[178:179], v[178:179], 0, s[12:13]
	ds_read_b128 v[184:187], v176 offset:49152
	ds_read_b128 v[188:191], v176 offset:50176
	ds_read_b128 v[192:195], v176 offset:51200
	ds_read_b128 v[196:199], v176 offset:52224
	ds_read_b128 v[200:203], v176 offset:53248
	ds_read_b128 v[204:207], v176 offset:54272
	ds_read_b128 v[214:217], v176 offset:55296
	ds_read_b128 v[218:221], v176 offset:56320
	global_load_lds_dwordx4 v[178:179], off
	v_lshl_add_u64 v[178:179], v[180:181], 0, s[12:13]
	s_mov_b32 m0, s28
	s_nop 0
	global_load_lds_dwordx4 v[178:179], off
	v_lshl_add_u64 v[178:179], v[182:183], 0, s[12:13]
	s_mov_b32 m0, s97
	s_nop 0
	global_load_lds_dwordx4 v[178:179], off
	v_lshl_add_u64 v[178:179], v[222:223], 0, s[12:13]
	s_mov_b32 m0, s15
	s_nop 0
	global_load_lds_dwordx4 v[178:179], off
	v_lshl_add_u64 v[178:179], v[224:225], 0, s[12:13]
	s_mov_b32 m0, s29
	s_nop 0
	global_load_lds_dwordx4 v[178:179], off
	v_lshl_add_u64 v[178:179], v[226:227], 0, s[12:13]
	s_mov_b32 m0, s96
	s_nop 0
	global_load_lds_dwordx4 v[178:179], off
	s_waitcnt vmcnt(8)
	s_waitcnt lgkmcnt(0)
	s_barrier
	s_setprio 1
	s_waitcnt lgkmcnt(0)
	v_mfma_f32_16x16x32_bf16 v[62:65], v[130:133], v[184:187], v[62:65]
	v_mfma_f32_16x16x32_bf16 v[58:61], v[138:141], v[184:187], v[58:61]
	v_mfma_f32_16x16x32_bf16 v[46:49], v[130:133], v[192:195], v[46:49]
	v_mfma_f32_16x16x32_bf16 v[42:45], v[138:141], v[192:195], v[42:45]
	v_mfma_f32_16x16x32_bf16 v[30:33], v[130:133], v[200:203], v[30:33]
	v_mfma_f32_16x16x32_bf16 v[26:29], v[138:141], v[200:203], v[26:29]
	v_mfma_f32_16x16x32_bf16 v[14:17], v[130:133], v[214:217], v[14:17]
	v_mfma_f32_16x16x32_bf16 v[10:13], v[138:141], v[214:217], v[10:13]
	v_mfma_f32_16x16x32_bf16 v[62:65], v[134:137], v[188:191], v[62:65]
	v_mfma_f32_16x16x32_bf16 v[58:61], v[142:145], v[188:191], v[58:61]
	v_mfma_f32_16x16x32_bf16 v[46:49], v[134:137], v[196:199], v[46:49]
	v_mfma_f32_16x16x32_bf16 v[42:45], v[142:145], v[196:199], v[42:45]
	v_mfma_f32_16x16x32_bf16 v[30:33], v[134:137], v[204:207], v[30:33]
	v_mfma_f32_16x16x32_bf16 v[26:29], v[142:145], v[204:207], v[26:29]
	v_mfma_f32_16x16x32_bf16 v[14:17], v[134:137], v[218:221], v[14:17]
	v_mfma_f32_16x16x32_bf16 v[10:13], v[142:145], v[218:221], v[10:13]
	s_setprio 0
	s_setprio 1
	v_mfma_f32_16x16x32_bf16 v[54:57], v[146:149], v[184:187], v[54:57]
	v_mfma_f32_16x16x32_bf16 v[50:53], v[168:171], v[184:187], v[50:53]
	v_mfma_f32_16x16x32_bf16 v[38:41], v[146:149], v[192:195], v[38:41]
	v_mfma_f32_16x16x32_bf16 v[34:37], v[168:171], v[192:195], v[34:37]
	v_mfma_f32_16x16x32_bf16 v[22:25], v[146:149], v[200:203], v[22:25]
	v_mfma_f32_16x16x32_bf16 v[18:21], v[168:171], v[200:203], v[18:21]
	v_mfma_f32_16x16x32_bf16 v[6:9], v[146:149], v[214:217], v[6:9]
	v_mfma_f32_16x16x32_bf16 v[2:5], v[168:171], v[214:217], v[2:5]
	v_mfma_f32_16x16x32_bf16 v[54:57], v[164:167], v[188:191], v[54:57]
	v_mfma_f32_16x16x32_bf16 v[50:53], v[172:175], v[188:191], v[50:53]
	v_mfma_f32_16x16x32_bf16 v[38:41], v[164:167], v[196:199], v[38:41]
	v_mfma_f32_16x16x32_bf16 v[34:37], v[172:175], v[196:199], v[34:37]
	v_mfma_f32_16x16x32_bf16 v[22:25], v[164:167], v[204:207], v[22:25]
	v_mfma_f32_16x16x32_bf16 v[18:21], v[172:175], v[204:207], v[18:21]
	v_mfma_f32_16x16x32_bf16 v[6:9], v[164:167], v[218:221], v[6:9]
	v_mfma_f32_16x16x32_bf16 v[2:5], v[172:175], v[218:221], v[2:5]
	s_barrier
	s_setprio 0
	s_add_u32 s86, s86, 0x100
	s_addc_u32 s87, s87, 0
	s_add_u32 vcc_lo, vcc_lo, 0x100
	s_addc_u32 vcc_hi, vcc_hi, 0
	s_cmp_ge_u32 s92, s2
	s_mov_b32 s88, s92
	s_cbranch_scc0 .LBB0_684
	s_and_b64 vcc, exec, s[30:31]
	s_cbranch_vccz .LBB0_687
	s_barrier

; #define PG8_STAGE(bufoff, gbase, voff) do { _Pragma("unroll") for (int _i = 0; _i < 2; ++_i) \
;         __builtin_amdgcn_global_load_lds((const unsigned*)((const char*)(gbase) + (voff)[_i]), (PG8_LAS unsigned*)(lds + (bufoff) + ldsw + _i * 8192), 16, 0, 0); } while (0)
; #define PG8_LDA(dst, b, h) do { _Pragma("unroll") for (int m = 0; m < 4; ++m) _Pragma("unroll") for (int k = 0; k < 2; ++k) dst[m][k] = *(const PG8_LAS bf16x8*)(lds + PG8_SA(b, h) + aoff + m * 2048 + k * 1024); } while (0)
; #define PG8_LDB(dst, b, h) do { _Pragma("unroll") for (int n = 0; n < 2; ++n) _Pragma("unroll") for (int k = 0; k < 2; ++k) dst[n][k] = *(const PG8_LAS bf16x8*)(lds + PG8_SB(b, h) + boff + n * 2048 + k * 1024); } while (0)
; #define PG8_WAIT_V(n) asm volatile("s_waitcnt vmcnt(" #n ")" ::: "memory")
; #define PG8_WAIT_L(n) asm volatile("s_waitcnt lgkmcnt(" #n ")" ::: "memory")
; #define PG8_BAR __builtin_amdgcn_s_barrier()
; #define PG8_SCHED __builtin_amdgcn_sched_barrier(0)
; template <class Epi, class Sched, bool ALIGN_EPI = false, bool SP2 = false>
; __device__ __forceinline__ void gemm_phase(PG8_LAS unsigned char* lds, const Gemm g, const Sched& S, const Epi& E, const int tid) {
;     ...
;         const bool has_next = S.next(ui + 1, nxt);
;         const char* nA = has_next ? (const char*)g.A + (size_t)nxt.pm * tstep : cA; const char* nB = has_next ? (const char*)g.Bt + (size_t)nxt.pn * tstep : cB;
;         for (int t = 0; t < nt; t += 2) {
;             const bool last = (t == nt - 2);
;             const char* a1 = cA + (size_t)(t + 1) * kstep;
;             const char* a2 = last ? nA : cA + (size_t)(t + 2) * kstep; const char* b2 = last ? nB : cB + (size_t)(t + 2) * kstep;
;             const char* a3 = a2 + kstep; const char* b3 = b2 + kstep;
;             if (last && has_next) S.a_ready(nxt);
;             if constexpr (SP2) {
;             PG8_LDB(B0, 0, 0); PG8_LDB(B1, 0, 1); PG8_SCHED; PG8_LDA(At, 0, 0); PG8_STAGE(PG8_SA(1, 1), a1 + hstep, voffA);
;             PG8_WAIT_V(8); PG8_WAIT_L(0); PG8_BAR; PG8_MMA(0, 0, At, B0); PG8_MMA(0, 1, At, B1); PG8_BAR; PG8_SCHED;
;             PG8_LDA(At, 0, 1); PG8_STAGE(PG8_SB(0, 0), b2, voffB); PG8_STAGE(PG8_SB(0, 1), b2 + hstep, voffB); PG8_STAGE(PG8_SA(0, 0), a2, voffA);
;             PG8_WAIT_V(8); PG8_WAIT_L(0); PG8_BAR; PG8_MMA(1, 0, At, B0); PG8_MMA(1, 1, At, B1); PG8_BAR; PG8_SCHED;
.LBB0_695:
	s_add_i32 s42, s41, 2
	s_mov_b32 s43, s7
	s_or_b32 s6, s41, 1
	s_lshl_b64 s[44:45], s[42:43], 7
	v_or_b32_e32 v138, 0x10000, v137
	v_add_u32_e32 v142, 0x10400, v137
	v_add_u32_e32 v146, 0x10800, v137
	v_add_u32_e32 v150, 0x10c00, v137
	v_or_b32_e32 v154, 0x14000, v137
	v_add_u32_e32 v158, 0x14400, v137
	v_add_u32_e32 v162, 0x14800, v137
	v_add_u32_e32 v166, 0x14c00, v137
	s_cmp_lg_u32 s41, s35
	ds_read_b128 v[138:141], v138
	ds_read_b128 v[142:145], v142
	ds_read_b128 v[146:149], v146
	ds_read_b128 v[150:153], v150
	ds_read_b128 v[154:157], v154
	ds_read_b128 v[158:161], v158
	ds_read_b128 v[162:165], v162
	ds_read_b128 v[166:169], v166
	s_cselect_b32 s43, s44, 0
	s_cselect_b32 s41, s45, 0
	s_add_u32 s44, s36, s43
	s_addc_u32 s45, s37, s41
	s_add_u32 s46, s30, s43
	s_addc_u32 s47, s31, s41
	s_lshl_b64 s[50:51], s[6:7], 7
	s_add_u32 s50, s38, s50
	s_addc_u32 s51, s39, s51
	v_lshl_add_u64 v[178:179], s[50:51], 0, v[134:135]
	s_add_i32 m0, s4, 0xc000
	ds_read_b128 v[170:173], v136
	ds_read_b128 v[174:177], v136 offset:1024
	ds_read_b128 v[184:187], v136 offset:2048
	ds_read_b128 v[188:191], v136 offset:3072
	ds_read_b128 v[192:195], v136 offset:4096
	ds_read_b128 v[196:199], v136 offset:5120
	ds_read_b128 v[200:203], v136 offset:6144
	ds_read_b128 v[204:207], v136 offset:7168
	global_load_lds_dwordx4 v[178:179], off
	v_lshl_add_u64 v[178:179], s[50:51], 0, v[132:133]
	s_add_i32 m0, s4, 0xe000
	s_nop 0
	global_load_lds_dwordx4 v[178:179], off
	s_waitcnt vmcnt(8)
	s_waitcnt lgkmcnt(0)
	s_barrier
	s_setprio 1
	s_waitcnt lgkmcnt(0)
	v_mfma_f32_16x16x32_bf16 v[126:129], v[138:141], v[170:173], v[126:129]
	v_mfma_f32_16x16x32_bf16 v[122:125], v[146:149], v[170:173], v[122:125]
	v_mfma_f32_16x16x32_bf16 v[118:121], v[138:141], v[184:187], v[118:121]
	v_mfma_f32_16x16x32_bf16 v[114:117], v[146:149], v[184:187], v[114:117]
	v_mfma_f32_16x16x32_bf16 v[106:109], v[138:141], v[192:195], v[106:109]
	v_mfma_f32_16x16x32_bf16 v[98:101], v[146:149], v[192:195], v[98:101]
	v_mfma_f32_16x16x32_bf16 v[90:93], v[138:141], v[200:203], v[90:93]
	v_mfma_f32_16x16x32_bf16 v[82:85], v[146:149], v[200:203], v[82:85]
	v_mfma_f32_16x16x32_bf16 v[126:129], v[142:145], v[174:177], v[126:129]
	v_mfma_f32_16x16x32_bf16 v[122:125], v[150:153], v[174:177], v[122:125]
	v_mfma_f32_16x16x32_bf16 v[118:121], v[142:145], v[188:191], v[118:121]
	v_mfma_f32_16x16x32_bf16 v[114:117], v[150:153], v[188:191], v[114:117]
	v_mfma_f32_16x16x32_bf16 v[106:109], v[142:145], v[196:199], v[106:109]
	v_mfma_f32_16x16x32_bf16 v[98:101], v[150:153], v[196:199], v[98:101]
	v_mfma_f32_16x16x32_bf16 v[90:93], v[142:145], v[204:207], v[90:93]
	v_mfma_f32_16x16x32_bf16 v[82:85], v[150:153], v[204:207], v[82:85]
	s_setprio 0
	s_setprio 1
	v_mfma_f32_16x16x32_bf16 v[110:113], v[154:157], v[170:173], v[110:113]
	v_mfma_f32_16x16x32_bf16 v[102:105], v[162:165], v[170:173], v[102:105]
	v_mfma_f32_16x16x32_bf16 v[94:97], v[154:157], v[184:187], v[94:97]
	v_mfma_f32_16x16x32_bf16 v[86:89], v[162:165], v[184:187], v[86:89]
	v_mfma_f32_16x16x32_bf16 v[78:81], v[154:157], v[192:195], v[78:81]
	v_mfma_f32_16x16x32_bf16 v[74:77], v[162:165], v[192:195], v[74:77]
	v_mfma_f32_16x16x32_bf16 v[70:73], v[154:157], v[200:203], v[70:73]
	v_mfma_f32_16x16x32_bf16 v[66:69], v[162:165], v[200:203], v[66:69]
	v_mfma_f32_16x16x32_bf16 v[110:113], v[158:161], v[174:177], v[110:113]
	v_mfma_f32_16x16x32_bf16 v[102:105], v[166:169], v[174:177], v[102:105]
	v_mfma_f32_16x16x32_bf16 v[94:97], v[158:161], v[188:191], v[94:97]
	v_mfma_f32_16x16x32_bf16 v[86:89], v[166:169], v[188:191], v[86:89]
	v_mfma_f32_16x16x32_bf16 v[78:81], v[158:161], v[196:199], v[78:81]
	v_mfma_f32_16x16x32_bf16 v[74:77], v[166:169], v[196:199], v[74:77]
	v_mfma_f32_16x16x32_bf16 v[70:73], v[158:161], v[204:207], v[70:73]
	v_mfma_f32_16x16x32_bf16 v[66:69], v[166:169], v[204:207], v[66:69]
	s_barrier
	s_setprio 0
	s_mov_b32 m0, s0
	v_lshl_add_u64 v[178:179], s[46:47], 0, v[0:1]
	v_lshl_add_u64 v[180:181], s[46:47], 0, v[130:131]
	s_add_u32 s46, s46, s40
	ds_read_b128 v[170:173], v136 offset:16384
	ds_read_b128 v[174:177], v136 offset:17408
	ds_read_b128 v[184:187], v136 offset:18432
	ds_read_b128 v[188:191], v136 offset:19456
	ds_read_b128 v[192:195], v136 offset:20480
	ds_read_b128 v[196:199], v136 offset:21504
	ds_read_b128 v[200:203], v136 offset:22528
	ds_read_b128 v[204:207], v136 offset:23552
	global_load_lds_dwordx4 v[178:179], off
	s_mov_b32 m0, s1
	s_addc_u32 s47, s47, 0
	global_load_lds_dwordx4 v[180:181], off
	v_lshl_add_u64 v[182:183], s[46:47], 0, v[0:1]
	s_mov_b32 m0, s5
	v_lshl_add_u64 v[214:215], s[46:47], 0, v[130:131]
	global_load_lds_dwordx4 v[182:183], off
	s_mov_b32 m0, s8
	v_lshl_add_u64 v[216:217], s[44:45], 0, v[134:135]
	global_load_lds_dwordx4 v[214:215], off
	s_mov_b32 m0, s4
	v_lshl_add_u64 v[218:219], s[44:45], 0, v[132:133]
	global_load_lds_dwordx4 v[216:217], off
	s_mov_b32 m0, s9
	s_nop 0
	global_load_lds_dwordx4 v[218:219], off
	s_waitcnt vmcnt(8)
	s_waitcnt lgkmcnt(0)
	s_barrier
; #define PG8_STAGE(bufoff, gbase, voff) do { _Pragma("unroll") for (int _i = 0; _i < 2; ++_i) \
;         __builtin_amdgcn_global_load_lds((const unsigned*)((const char*)(gbase) + (voff)[_i]), (PG8_LAS unsigned*)(lds + (bufoff) + ldsw + _i * 8192), 16, 0, 0); } while (0)
; #define PG8_LDA(dst, b, h) do { _Pragma("unroll") for (int m = 0; m < 4; ++m) _Pragma("unroll") for (int k = 0; k < 2; ++k) dst[m][k] = *(const PG8_LAS bf16x8*)(lds + PG8_SA(b, h) + aoff + m * 2048 + k * 1024); } while (0)
; #define PG8_LDB(dst, b, h) do { _Pragma("unroll") for (int n = 0; n < 2; ++n) _Pragma("unroll") for (int k = 0; k < 2; ++k) dst[n][k] = *(const PG8_LAS bf16x8*)(lds + PG8_SB(b, h) + boff + n * 2048 + k * 1024); } while (0)
; #define PG8_MMA(ai, bj, At, Bt) do { __builtin_amdgcn_s_setprio(1); _Pragma("unroll") for (int m = 0; m < 4; ++m) _Pragma("unroll") for (int n = 0; n < 2; ++n) _Pragma("unroll") for (int k = 0; k < 2; ++k) \
;         acc[ai][bj][m][n] = __builtin_amdgcn_mfma_f32_16x16x32_bf16(Bt[n][k], At[m][k], acc[ai][bj][m][n], 0, 0, 0); __builtin_amdgcn_s_setprio(0); } while (0)
; #define PG8_WAIT_V(n) asm volatile("s_waitcnt vmcnt(" #n ")" ::: "memory")
; #define PG8_WAIT_L(n) asm volatile("s_waitcnt lgkmcnt(" #n ")" ::: "memory")
; #define PG8_BAR __builtin_amdgcn_s_barrier()
; #define PG8_SCHED __builtin_amdgcn_sched_barrier(0)
; template <class Epi, class Sched, bool ALIGN_EPI = false, bool SP2 = false>
; __device__ __forceinline__ void gemm_phase(PG8_LAS unsigned char* lds, const Gemm g, const Sched& S, const Epi& E, const int tid) {
;     ...
;             PG8_WAIT_V(8); PG8_WAIT_L(0); PG8_BAR; PG8_MMA(1, 0, At, B0); PG8_MMA(1, 1, At, B1); PG8_BAR; PG8_SCHED;
;             PG8_LDB(B0, 1, 0); PG8_LDB(B1, 1, 1); PG8_SCHED; PG8_LDA(At, 1, 0); PG8_STAGE(PG8_SA(0, 1), a2 + hstep, voffA);
;             PG8_WAIT_V(8); PG8_WAIT_L(0); PG8_BAR; PG8_MMA(0, 0, At, B0); PG8_MMA(0, 1, At, B1); PG8_BAR; PG8_SCHED;
	s_setprio 1
	s_waitcnt lgkmcnt(0)
	v_mfma_f32_16x16x32_bf16 v[62:65], v[138:141], v[170:173], v[62:65]
	v_mfma_f32_16x16x32_bf16 v[58:61], v[146:149], v[170:173], v[58:61]
	v_mfma_f32_16x16x32_bf16 v[54:57], v[138:141], v[184:187], v[54:57]
	v_mfma_f32_16x16x32_bf16 v[50:53], v[146:149], v[184:187], v[50:53]
	v_mfma_f32_16x16x32_bf16 v[38:41], v[138:141], v[192:195], v[38:41]
	v_mfma_f32_16x16x32_bf16 v[34:37], v[146:149], v[192:195], v[34:37]
	v_mfma_f32_16x16x32_bf16 v[22:25], v[138:141], v[200:203], v[22:25]
	v_mfma_f32_16x16x32_bf16 v[18:21], v[146:149], v[200:203], v[18:21]
	v_mfma_f32_16x16x32_bf16 v[62:65], v[142:145], v[174:177], v[62:65]
	v_mfma_f32_16x16x32_bf16 v[58:61], v[150:153], v[174:177], v[58:61]
	v_mfma_f32_16x16x32_bf16 v[54:57], v[142:145], v[188:191], v[54:57]
	v_mfma_f32_16x16x32_bf16 v[50:53], v[150:153], v[188:191], v[50:53]
	v_mfma_f32_16x16x32_bf16 v[38:41], v[142:145], v[196:199], v[38:41]
	v_mfma_f32_16x16x32_bf16 v[34:37], v[150:153], v[196:199], v[34:37]
	v_mfma_f32_16x16x32_bf16 v[22:25], v[142:145], v[204:207], v[22:25]
	v_mfma_f32_16x16x32_bf16 v[18:21], v[150:153], v[204:207], v[18:21]
	s_setprio 0
	s_setprio 1
	v_mfma_f32_16x16x32_bf16 v[46:49], v[154:157], v[170:173], v[46:49]
	v_mfma_f32_16x16x32_bf16 v[42:45], v[162:165], v[170:173], v[42:45]
	v_mfma_f32_16x16x32_bf16 v[30:33], v[154:157], v[184:187], v[30:33]
	v_mfma_f32_16x16x32_bf16 v[26:29], v[162:165], v[184:187], v[26:29]
	v_mfma_f32_16x16x32_bf16 v[14:17], v[154:157], v[192:195], v[14:17]
	v_mfma_f32_16x16x32_bf16 v[10:13], v[162:165], v[192:195], v[10:13]
	v_mfma_f32_16x16x32_bf16 v[6:9], v[154:157], v[200:203], v[6:9]
	v_mfma_f32_16x16x32_bf16 v[2:5], v[162:165], v[200:203], v[2:5]
	v_mfma_f32_16x16x32_bf16 v[46:49], v[158:161], v[174:177], v[46:49]
	v_mfma_f32_16x16x32_bf16 v[42:45], v[166:169], v[174:177], v[42:45]
	v_mfma_f32_16x16x32_bf16 v[30:33], v[158:161], v[188:191], v[30:33]
	v_mfma_f32_16x16x32_bf16 v[26:29], v[166:169], v[188:191], v[26:29]
	v_mfma_f32_16x16x32_bf16 v[14:17], v[158:161], v[196:199], v[14:17]
	v_mfma_f32_16x16x32_bf16 v[10:13], v[166:169], v[196:199], v[10:13]
	v_mfma_f32_16x16x32_bf16 v[6:9], v[158:161], v[204:207], v[6:9]
	v_mfma_f32_16x16x32_bf16 v[2:5], v[166:169], v[204:207], v[2:5]
	s_barrier
	s_setprio 0
	v_or_b32_e32 v138, 0x18000, v137
	v_add_u32_e32 v142, 0x18400, v137
	v_add_u32_e32 v146, 0x18800, v137
	v_add_u32_e32 v150, 0x18c00, v137
	v_or_b32_e32 v154, 0x1c000, v137
	v_add_u32_e32 v158, 0x1c400, v137
	v_add_u32_e32 v162, 0x1c800, v137
	v_add_u32_e32 v166, 0x1cc00, v137
	ds_read_b128 v[138:141], v138
	ds_read_b128 v[142:145], v142
	ds_read_b128 v[146:149], v146
	ds_read_b128 v[150:153], v150
	ds_read_b128 v[154:157], v154
	ds_read_b128 v[158:161], v158
	ds_read_b128 v[162:165], v162
	ds_read_b128 v[166:169], v166
	s_add_u32 s44, s44, s40
	s_addc_u32 s45, s45, 0
	s_mov_b32 m0, s14
	v_lshl_add_u64 v[220:221], s[44:45], 0, v[134:135]
	ds_read_b128 v[170:173], v136 offset:32768
	ds_read_b128 v[174:177], v136 offset:33792
	ds_read_b128 v[184:187], v136 offset:34816
	ds_read_b128 v[188:191], v136 offset:35840
	ds_read_b128 v[192:195], v136 offset:36864
	ds_read_b128 v[196:199], v136 offset:37888
	ds_read_b128 v[200:203], v136 offset:38912
	ds_read_b128 v[204:207], v136 offset:39936
	global_load_lds_dwordx4 v[220:221], off
	v_lshl_add_u64 v[220:221], s[44:45], 0, v[132:133]
	s_mov_b32 m0, s15
	s_nop 0
	global_load_lds_dwordx4 v[220:221], off
	s_waitcnt vmcnt(8)
	s_waitcnt lgkmcnt(0)
	s_barrier
	s_setprio 1
	s_waitcnt lgkmcnt(0)
	v_mfma_f32_16x16x32_bf16 v[126:129], v[138:141], v[170:173], v[126:129]
	v_mfma_f32_16x16x32_bf16 v[122:125], v[146:149], v[170:173], v[122:125]
	v_mfma_f32_16x16x32_bf16 v[118:121], v[138:141], v[184:187], v[118:121]
	v_mfma_f32_16x16x32_bf16 v[114:117], v[146:149], v[184:187], v[114:117]
	v_mfma_f32_16x16x32_bf16 v[106:109], v[138:141], v[192:195], v[106:109]
	v_mfma_f32_16x16x32_bf16 v[98:101], v[146:149], v[192:195], v[98:101]
	v_mfma_f32_16x16x32_bf16 v[90:93], v[138:141], v[200:203], v[90:93]
	v_mfma_f32_16x16x32_bf16 v[82:85], v[146:149], v[200:203], v[82:85]
	v_mfma_f32_16x16x32_bf16 v[126:129], v[142:145], v[174:177], v[126:129]
	v_mfma_f32_16x16x32_bf16 v[122:125], v[150:153], v[174:177], v[122:125]
	v_mfma_f32_16x16x32_bf16 v[118:121], v[142:145], v[188:191], v[118:121]
	v_mfma_f32_16x16x32_bf16 v[114:117], v[150:153], v[188:191], v[114:117]
	v_mfma_f32_16x16x32_bf16 v[106:109], v[142:145], v[196:199], v[106:109]
	v_mfma_f32_16x16x32_bf16 v[98:101], v[150:153], v[196:199], v[98:101]
	v_mfma_f32_16x16x32_bf16 v[90:93], v[142:145], v[204:207], v[90:93]
	v_mfma_f32_16x16x32_bf16 v[82:85], v[150:153], v[204:207], v[82:85]
	s_setprio 0
	s_setprio 1
	v_mfma_f32_16x16x32_bf16 v[110:113], v[154:157], v[170:173], v[110:113]
	v_mfma_f32_16x16x32_bf16 v[102:105], v[162:165], v[170:173], v[102:105]
	v_mfma_f32_16x16x32_bf16 v[94:97], v[154:157], v[184:187], v[94:97]
	v_mfma_f32_16x16x32_bf16 v[86:89], v[162:165], v[184:187], v[86:89]
	v_mfma_f32_16x16x32_bf16 v[78:81], v[154:157], v[192:195], v[78:81]
	v_mfma_f32_16x16x32_bf16 v[74:77], v[162:165], v[192:195], v[74:77]
	v_mfma_f32_16x16x32_bf16 v[70:73], v[154:157], v[200:203], v[70:73]
	v_mfma_f32_16x16x32_bf16 v[66:69], v[162:165], v[200:203], v[66:69]
	v_mfma_f32_16x16x32_bf16 v[110:113], v[158:161], v[174:177], v[110:113]
	v_mfma_f32_16x16x32_bf16 v[102:105], v[166:169], v[174:177], v[102:105]
	v_mfma_f32_16x16x32_bf16 v[94:97], v[158:161], v[188:191], v[94:97]
	v_mfma_f32_16x16x32_bf16 v[86:89], v[166:169], v[188:191], v[86:89]
	v_mfma_f32_16x16x32_bf16 v[78:81], v[158:161], v[196:199], v[78:81]
	v_mfma_f32_16x16x32_bf16 v[74:77], v[166:169], v[196:199], v[74:77]
	v_mfma_f32_16x16x32_bf16 v[70:73], v[158:161], v[204:207], v[70:73]
	v_mfma_f32_16x16x32_bf16 v[66:69], v[166:169], v[204:207], v[66:69]
	s_barrier
; #define PG8_STAGE(bufoff, gbase, voff) do { _Pragma("unroll") for (int _i = 0; _i < 2; ++_i) \
;         __builtin_amdgcn_global_load_lds((const unsigned*)((const char*)(gbase) + (voff)[_i]), (PG8_LAS unsigned*)(lds + (bufoff) + ldsw + _i * 8192), 16, 0, 0); } while (0)
; #define PG8_LDA(dst, b, h) do { _Pragma("unroll") for (int m = 0; m < 4; ++m) _Pragma("unroll") for (int k = 0; k < 2; ++k) dst[m][k] = *(const PG8_LAS bf16x8*)(lds + PG8_SA(b, h) + aoff + m * 2048 + k * 1024); } while (0)
; #define PG8_MMA(ai, bj, At, Bt) do { __builtin_amdgcn_s_setprio(1); _Pragma("unroll") for (int m = 0; m < 4; ++m) _Pragma("unroll") for (int n = 0; n < 2; ++n) _Pragma("unroll") for (int k = 0; k < 2; ++k) \
;         acc[ai][bj][m][n] = __builtin_amdgcn_mfma_f32_16x16x32_bf16(Bt[n][k], At[m][k], acc[ai][bj][m][n], 0, 0, 0); __builtin_amdgcn_s_setprio(0); } while (0)
; #define PG8_WAIT_V(n) asm volatile("s_waitcnt vmcnt(" #n ")" ::: "memory")
; #define PG8_WAIT_L(n) asm volatile("s_waitcnt lgkmcnt(" #n ")" ::: "memory")
; #define PG8_BAR __builtin_amdgcn_s_barrier()
; #define PG8_SCHED __builtin_amdgcn_sched_barrier(0)
; template <class Epi, class Sched, bool ALIGN_EPI = false, bool SP2 = false>
; __device__ __forceinline__ void gemm_phase(PG8_LAS unsigned char* lds, const Gemm g, const Sched& S, const Epi& E, const int tid) {
;     ...
;             PG8_WAIT_V(8); PG8_WAIT_L(0); PG8_BAR; PG8_MMA(0, 0, At, B0); PG8_MMA(0, 1, At, B1); PG8_BAR; PG8_SCHED;
;             PG8_LDA(At, 1, 1); PG8_STAGE(PG8_SB(1, 0), b3, voffB); PG8_STAGE(PG8_SB(1, 1), b3 + hstep, voffB); PG8_STAGE(PG8_SA(1, 0), a3, voffA);
;             PG8_WAIT_V(8); PG8_WAIT_L(0); PG8_BAR; PG8_MMA(1, 0, At, B0); PG8_MMA(1, 1, At, B1); PG8_BAR; PG8_SCHED;
;     ...
;         if constexpr (ALIGN_EPI) { if (wr == 0) PG8_BAR; }
	s_setprio 0
	s_mov_b32 m0, s24
	v_lshl_add_u64 v[178:179], v[178:179], 0, s[12:13]
	ds_read_b128 v[170:173], v136 offset:49152
	ds_read_b128 v[174:177], v136 offset:50176
	ds_read_b128 v[184:187], v136 offset:51200
	ds_read_b128 v[188:191], v136 offset:52224
	ds_read_b128 v[192:195], v136 offset:53248
	ds_read_b128 v[196:199], v136 offset:54272
	ds_read_b128 v[200:203], v136 offset:55296
	ds_read_b128 v[204:207], v136 offset:56320
	global_load_lds_dwordx4 v[178:179], off
	v_lshl_add_u64 v[178:179], v[180:181], 0, s[12:13]
	s_mov_b32 m0, s26
	s_nop 0
	global_load_lds_dwordx4 v[178:179], off
	v_lshl_add_u64 v[178:179], v[182:183], 0, s[12:13]
	s_mov_b32 m0, s29
	s_nop 0
	global_load_lds_dwordx4 v[178:179], off
	v_lshl_add_u64 v[178:179], v[214:215], 0, s[12:13]
	s_mov_b32 m0, s34
	s_nop 0
	global_load_lds_dwordx4 v[178:179], off
	v_lshl_add_u64 v[178:179], v[216:217], 0, s[12:13]
	s_mov_b32 m0, s27
	s_nop 0
	global_load_lds_dwordx4 v[178:179], off
	v_lshl_add_u64 v[178:179], v[218:219], 0, s[12:13]
	s_mov_b32 m0, s28
	s_nop 0
	global_load_lds_dwordx4 v[178:179], off
	s_waitcnt vmcnt(8)
	s_waitcnt lgkmcnt(0)
	s_barrier
	s_setprio 1
	s_waitcnt lgkmcnt(0)
	v_mfma_f32_16x16x32_bf16 v[62:65], v[138:141], v[170:173], v[62:65]
	v_mfma_f32_16x16x32_bf16 v[58:61], v[146:149], v[170:173], v[58:61]
	v_mfma_f32_16x16x32_bf16 v[54:57], v[138:141], v[184:187], v[54:57]
	v_mfma_f32_16x16x32_bf16 v[50:53], v[146:149], v[184:187], v[50:53]
	v_mfma_f32_16x16x32_bf16 v[38:41], v[138:141], v[192:195], v[38:41]
	v_mfma_f32_16x16x32_bf16 v[34:37], v[146:149], v[192:195], v[34:37]
	v_mfma_f32_16x16x32_bf16 v[22:25], v[138:141], v[200:203], v[22:25]
	v_mfma_f32_16x16x32_bf16 v[18:21], v[146:149], v[200:203], v[18:21]
	v_mfma_f32_16x16x32_bf16 v[62:65], v[142:145], v[174:177], v[62:65]
	v_mfma_f32_16x16x32_bf16 v[58:61], v[150:153], v[174:177], v[58:61]
	v_mfma_f32_16x16x32_bf16 v[54:57], v[142:145], v[188:191], v[54:57]
	v_mfma_f32_16x16x32_bf16 v[50:53], v[150:153], v[188:191], v[50:53]
	v_mfma_f32_16x16x32_bf16 v[38:41], v[142:145], v[196:199], v[38:41]
	v_mfma_f32_16x16x32_bf16 v[34:37], v[150:153], v[196:199], v[34:37]
	v_mfma_f32_16x16x32_bf16 v[22:25], v[142:145], v[204:207], v[22:25]
	v_mfma_f32_16x16x32_bf16 v[18:21], v[150:153], v[204:207], v[18:21]
	s_setprio 0
	s_setprio 1
	v_mfma_f32_16x16x32_bf16 v[46:49], v[154:157], v[170:173], v[46:49]
	v_mfma_f32_16x16x32_bf16 v[42:45], v[162:165], v[170:173], v[42:45]
	v_mfma_f32_16x16x32_bf16 v[30:33], v[154:157], v[184:187], v[30:33]
	v_mfma_f32_16x16x32_bf16 v[26:29], v[162:165], v[184:187], v[26:29]
	v_mfma_f32_16x16x32_bf16 v[14:17], v[154:157], v[192:195], v[14:17]
	v_mfma_f32_16x16x32_bf16 v[10:13], v[162:165], v[192:195], v[10:13]
	v_mfma_f32_16x16x32_bf16 v[6:9], v[154:157], v[200:203], v[6:9]
	v_mfma_f32_16x16x32_bf16 v[2:5], v[162:165], v[200:203], v[2:5]
	v_mfma_f32_16x16x32_bf16 v[46:49], v[158:161], v[174:177], v[46:49]
	v_mfma_f32_16x16x32_bf16 v[42:45], v[166:169], v[174:177], v[42:45]
	v_mfma_f32_16x16x32_bf16 v[30:33], v[158:161], v[188:191], v[30:33]
	v_mfma_f32_16x16x32_bf16 v[26:29], v[166:169], v[188:191], v[26:29]
	v_mfma_f32_16x16x32_bf16 v[14:17], v[158:161], v[196:199], v[14:17]
	v_mfma_f32_16x16x32_bf16 v[10:13], v[166:169], v[196:199], v[10:13]
	v_mfma_f32_16x16x32_bf16 v[6:9], v[158:161], v[204:207], v[6:9]
	v_mfma_f32_16x16x32_bf16 v[2:5], v[166:169], v[204:207], v[2:5]
	s_barrier
	s_setprio 0
	s_cmp_ge_u32 s42, s21
	s_mov_b32 s41, s42
	s_cbranch_scc0 .LBB0_695
	v_readlane_b32 s26, v254, 47
	v_readlane_b32 s28, v254, 49
	s_cmpk_lt_u32 s2, 0x100
	v_readlane_b32 s27, v254, 48
	v_readlane_b32 s29, v254, 50
	s_cbranch_scc0 .LBB0_698
	s_barrier

; #define PG8_STAGE(bufoff, gbase, voff) do { _Pragma("unroll") for (int _i = 0; _i < 2; ++_i) \
;         __builtin_amdgcn_global_load_lds((const unsigned*)((const char*)(gbase) + (voff)[_i]), (PG8_LAS unsigned*)(lds + (bufoff) + ldsw + _i * 8192), 16, 0, 0); } while (0)
; #define PG8_LDA(dst, b, h) do { _Pragma("unroll") for (int m = 0; m < 4; ++m) _Pragma("unroll") for (int k = 0; k < 2; ++k) dst[m][k] = *(const PG8_LAS bf16x8*)(lds + PG8_SA(b, h) + aoff + m * 2048 + k * 1024); } while (0)
; #define PG8_LDB(dst, b, h) do { _Pragma("unroll") for (int n = 0; n < 2; ++n) _Pragma("unroll") for (int k = 0; k < 2; ++k) dst[n][k] = *(const PG8_LAS bf16x8*)(lds + PG8_SB(b, h) + boff + n * 2048 + k * 1024); } while (0)
; #define PG8_MMA(ai, bj, At, Bt) do { __builtin_amdgcn_s_setprio(1); _Pragma("unroll") for (int m = 0; m < 4; ++m) _Pragma("unroll") for (int n = 0; n < 2; ++n) _Pragma("unroll") for (int k = 0; k < 2; ++k) \
;         acc[ai][bj][m][n] = __builtin_amdgcn_mfma_f32_16x16x32_bf16(Bt[n][k], At[m][k], acc[ai][bj][m][n], 0, 0, 0); __builtin_amdgcn_s_setprio(0); } while (0)
; #define PG8_WAIT_V(n) asm volatile("s_waitcnt vmcnt(" #n ")" ::: "memory")
; #define PG8_WAIT_L(n) asm volatile("s_waitcnt lgkmcnt(" #n ")" ::: "memory")
; template <class Epi, class Sched, bool ALIGN_EPI = false, bool SP2 = false>
; __device__ __forceinline__ void gemm_phase(PG8_LAS unsigned char* lds, const Gemm g, const Sched& S, const Epi& E, const int tid) {
;     ...
;             const bool last = (t == nt - 2);
;             const char* a1 = cA + (size_t)(t + 1) * kstep;
;             const char* a2 = last ? nA : cA + (size_t)(t + 2) * kstep; const char* b2 = last ? nB : cB + (size_t)(t + 2) * kstep;
;             const char* a3 = a2 + kstep; const char* b3 = b2 + kstep;
;             if (last && has_next) S.a_ready(nxt);
;             if constexpr (SP2) {
;             PG8_LDB(B0, 0, 0); PG8_LDB(B1, 0, 1); PG8_SCHED; PG8_LDA(At, 0, 0); PG8_STAGE(PG8_SA(1, 1), a1 + hstep, voffA);
;             PG8_WAIT_V(8); PG8_WAIT_L(0); PG8_BAR; PG8_MMA(0, 0, At, B0); PG8_MMA(0, 1, At, B1); PG8_BAR; PG8_SCHED;
;             PG8_LDA(At, 0, 1); PG8_STAGE(PG8_SB(0, 0), b2, voffB); PG8_STAGE(PG8_SB(0, 1), b2 + hstep, voffB); PG8_STAGE(PG8_SA(0, 0), a2, voffA);
;             PG8_WAIT_V(8); PG8_WAIT_L(0); PG8_BAR; PG8_MMA(1, 0, At, B0); PG8_MMA(1, 1, At, B1); PG8_BAR; PG8_SCHED;
.LBB0_713:
	v_or_b32_e32 v142, 0x10000, v141
	v_add_u32_e32 v146, 0x10400, v141
	v_add_u32_e32 v150, 0x10800, v141
	v_add_u32_e32 v154, 0x10c00, v141
	v_or_b32_e32 v158, 0x14000, v141
	v_add_u32_e32 v162, 0x14400, v141
	v_add_u32_e32 v166, 0x14800, v141
	v_add_u32_e32 v170, 0x14c00, v141
	ds_read_b128 v[142:145], v142
	ds_read_b128 v[146:149], v146
	ds_read_b128 v[150:153], v150
	ds_read_b128 v[154:157], v154
	ds_read_b128 v[158:161], v158
	ds_read_b128 v[162:165], v162
	ds_read_b128 v[166:169], v166
	ds_read_b128 v[170:173], v170
	s_add_u32 s84, s30, 0xfffc0080
	s_addc_u32 s85, s31, -1
	s_cmp_eq_u32 s43, 12
	s_cselect_b32 s87, s5, s85
	s_cselect_b32 s86, s15, s84
	s_cselect_b32 s85, s20, s41
	s_cselect_b32 s84, s21, s24
	v_lshl_add_u64 v[178:179], s[30:31], 0, v[136:137]
	s_add_i32 m0, s1, 0xc000
	ds_read_b128 v[174:177], v140
	ds_read_b128 v[184:187], v140 offset:1024
	ds_read_b128 v[188:191], v140 offset:2048
	ds_read_b128 v[192:195], v140 offset:3072
	ds_read_b128 v[196:199], v140 offset:4096
	ds_read_b128 v[200:203], v140 offset:5120
	ds_read_b128 v[204:207], v140 offset:6144
	ds_read_b128 v[214:217], v140 offset:7168
	global_load_lds_dwordx4 v[178:179], off
	v_lshl_add_u64 v[178:179], s[30:31], 0, v[138:139]
	s_add_i32 m0, s1, 0xe000
	s_nop 0
	global_load_lds_dwordx4 v[178:179], off
	s_waitcnt vmcnt(8)
	s_waitcnt lgkmcnt(0)
	s_barrier
	s_setprio 1
	s_waitcnt lgkmcnt(0)
	v_mfma_f32_16x16x32_bf16 v[126:129], v[142:145], v[174:177], v[126:129]
	v_mfma_f32_16x16x32_bf16 v[118:121], v[150:153], v[174:177], v[118:121]
	v_mfma_f32_16x16x32_bf16 v[110:113], v[142:145], v[188:191], v[110:113]
	v_mfma_f32_16x16x32_bf16 v[102:105], v[150:153], v[188:191], v[102:105]
	v_mfma_f32_16x16x32_bf16 v[94:97], v[142:145], v[196:199], v[94:97]
	v_mfma_f32_16x16x32_bf16 v[86:89], v[150:153], v[196:199], v[86:89]
	v_mfma_f32_16x16x32_bf16 v[78:81], v[142:145], v[204:207], v[78:81]
	v_mfma_f32_16x16x32_bf16 v[70:73], v[150:153], v[204:207], v[70:73]
	v_mfma_f32_16x16x32_bf16 v[126:129], v[146:149], v[184:187], v[126:129]
	v_mfma_f32_16x16x32_bf16 v[118:121], v[154:157], v[184:187], v[118:121]
	v_mfma_f32_16x16x32_bf16 v[110:113], v[146:149], v[192:195], v[110:113]
	v_mfma_f32_16x16x32_bf16 v[102:105], v[154:157], v[192:195], v[102:105]
	v_mfma_f32_16x16x32_bf16 v[94:97], v[146:149], v[200:203], v[94:97]
	v_mfma_f32_16x16x32_bf16 v[86:89], v[154:157], v[200:203], v[86:89]
	v_mfma_f32_16x16x32_bf16 v[78:81], v[146:149], v[214:217], v[78:81]
	v_mfma_f32_16x16x32_bf16 v[70:73], v[154:157], v[214:217], v[70:73]
	s_setprio 0
	s_setprio 1
	v_mfma_f32_16x16x32_bf16 v[122:125], v[158:161], v[174:177], v[122:125]
	v_mfma_f32_16x16x32_bf16 v[114:117], v[166:169], v[174:177], v[114:117]
	v_mfma_f32_16x16x32_bf16 v[106:109], v[158:161], v[188:191], v[106:109]
	v_mfma_f32_16x16x32_bf16 v[98:101], v[166:169], v[188:191], v[98:101]
	v_mfma_f32_16x16x32_bf16 v[90:93], v[158:161], v[196:199], v[90:93]
	v_mfma_f32_16x16x32_bf16 v[82:85], v[166:169], v[196:199], v[82:85]
	v_mfma_f32_16x16x32_bf16 v[74:77], v[158:161], v[204:207], v[74:77]
	v_mfma_f32_16x16x32_bf16 v[66:69], v[166:169], v[204:207], v[66:69]
	v_mfma_f32_16x16x32_bf16 v[122:125], v[162:165], v[184:187], v[122:125]
	v_mfma_f32_16x16x32_bf16 v[114:117], v[170:173], v[184:187], v[114:117]
	v_mfma_f32_16x16x32_bf16 v[106:109], v[162:165], v[192:195], v[106:109]
	v_mfma_f32_16x16x32_bf16 v[98:101], v[170:173], v[192:195], v[98:101]
	v_mfma_f32_16x16x32_bf16 v[90:93], v[162:165], v[200:203], v[90:93]
	v_mfma_f32_16x16x32_bf16 v[82:85], v[170:173], v[200:203], v[82:85]
	v_mfma_f32_16x16x32_bf16 v[74:77], v[162:165], v[214:217], v[74:77]
	v_mfma_f32_16x16x32_bf16 v[66:69], v[170:173], v[214:217], v[66:69]
	s_barrier
	s_setprio 0
	s_mov_b32 m0, s6
	v_lshl_add_u64 v[178:179], s[84:85], 0, v[0:1]
	s_add_u32 s92, s84, 0x40000
	ds_read_b128 v[174:177], v140 offset:16384
	ds_read_b128 v[184:187], v140 offset:17408
	ds_read_b128 v[188:191], v140 offset:18432
	ds_read_b128 v[192:195], v140 offset:19456
	ds_read_b128 v[196:199], v140 offset:20480
	ds_read_b128 v[200:203], v140 offset:21504
	ds_read_b128 v[204:207], v140 offset:22528
	ds_read_b128 v[214:217], v140 offset:23552
	global_load_lds_dwordx4 v[178:179], off
	v_lshl_add_u64 v[180:181], s[84:85], 0, v[130:131]
	s_mov_b32 m0, s8
	s_addc_u32 s93, s85, 0
	global_load_lds_dwordx4 v[180:181], off
	v_lshl_add_u64 v[182:183], s[92:93], 0, v[0:1]
	s_mov_b32 m0, s9
	v_lshl_add_u64 v[218:219], s[86:87], 0, v[132:133]
	global_load_lds_dwordx4 v[182:183], off
	v_lshl_add_u64 v[182:183], s[92:93], 0, v[130:131]
	s_mov_b32 m0, s14
	s_nop 0
	global_load_lds_dwordx4 v[182:183], off
	v_lshl_add_u64 v[182:183], s[86:87], 0, v[134:135]
	s_mov_b32 m0, s1
	s_nop 0
	global_load_lds_dwordx4 v[182:183], off
	s_mov_b32 m0, s34
	s_nop 0
	global_load_lds_dwordx4 v[218:219], off
	s_waitcnt vmcnt(8)
	s_waitcnt lgkmcnt(0)
	s_barrier
; #define PG8_STAGE(bufoff, gbase, voff) do { _Pragma("unroll") for (int _i = 0; _i < 2; ++_i) \
;         __builtin_amdgcn_global_load_lds((const unsigned*)((const char*)(gbase) + (voff)[_i]), (PG8_LAS unsigned*)(lds + (bufoff) + ldsw + _i * 8192), 16, 0, 0); } while (0)
; #define PG8_LDA(dst, b, h) do { _Pragma("unroll") for (int m = 0; m < 4; ++m) _Pragma("unroll") for (int k = 0; k < 2; ++k) dst[m][k] = *(const PG8_LAS bf16x8*)(lds + PG8_SA(b, h) + aoff + m * 2048 + k * 1024); } while (0)
; #define PG8_LDB(dst, b, h) do { _Pragma("unroll") for (int n = 0; n < 2; ++n) _Pragma("unroll") for (int k = 0; k < 2; ++k) dst[n][k] = *(const PG8_LAS bf16x8*)(lds + PG8_SB(b, h) + boff + n * 2048 + k * 1024); } while (0)
; #define PG8_MMA(ai, bj, At, Bt) do { __builtin_amdgcn_s_setprio(1); _Pragma("unroll") for (int m = 0; m < 4; ++m) _Pragma("unroll") for (int n = 0; n < 2; ++n) _Pragma("unroll") for (int k = 0; k < 2; ++k) \
;         acc[ai][bj][m][n] = __builtin_amdgcn_mfma_f32_16x16x32_bf16(Bt[n][k], At[m][k], acc[ai][bj][m][n], 0, 0, 0); __builtin_amdgcn_s_setprio(0); } while (0)
; #define PG8_WAIT_V(n) asm volatile("s_waitcnt vmcnt(" #n ")" ::: "memory")
; #define PG8_WAIT_L(n) asm volatile("s_waitcnt lgkmcnt(" #n ")" ::: "memory")
; #define PG8_BAR __builtin_amdgcn_s_barrier()
; #define PG8_SCHED __builtin_amdgcn_sched_barrier(0)
; template <class Epi, class Sched, bool ALIGN_EPI = false, bool SP2 = false>
; __device__ __forceinline__ void gemm_phase(PG8_LAS unsigned char* lds, const Gemm g, const Sched& S, const Epi& E, const int tid) {
;     ...
;             PG8_WAIT_V(8); PG8_WAIT_L(0); PG8_BAR; PG8_MMA(1, 0, At, B0); PG8_MMA(1, 1, At, B1); PG8_BAR; PG8_SCHED;
;             PG8_LDB(B0, 1, 0); PG8_LDB(B1, 1, 1); PG8_SCHED; PG8_LDA(At, 1, 0); PG8_STAGE(PG8_SA(0, 1), a2 + hstep, voffA);
;             PG8_WAIT_V(8); PG8_WAIT_L(0); PG8_BAR; PG8_MMA(0, 0, At, B0); PG8_MMA(0, 1, At, B1); PG8_BAR; PG8_SCHED;
	s_setprio 1
	s_waitcnt lgkmcnt(0)
	v_mfma_f32_16x16x32_bf16 v[62:65], v[142:145], v[174:177], v[62:65]
	v_mfma_f32_16x16x32_bf16 v[54:57], v[150:153], v[174:177], v[54:57]
	v_mfma_f32_16x16x32_bf16 v[46:49], v[142:145], v[188:191], v[46:49]
	v_mfma_f32_16x16x32_bf16 v[38:41], v[150:153], v[188:191], v[38:41]
	v_mfma_f32_16x16x32_bf16 v[30:33], v[142:145], v[196:199], v[30:33]
	v_mfma_f32_16x16x32_bf16 v[22:25], v[150:153], v[196:199], v[22:25]
	v_mfma_f32_16x16x32_bf16 v[14:17], v[142:145], v[204:207], v[14:17]
	v_mfma_f32_16x16x32_bf16 v[6:9], v[150:153], v[204:207], v[6:9]
	v_mfma_f32_16x16x32_bf16 v[62:65], v[146:149], v[184:187], v[62:65]
	v_mfma_f32_16x16x32_bf16 v[54:57], v[154:157], v[184:187], v[54:57]
	v_mfma_f32_16x16x32_bf16 v[46:49], v[146:149], v[192:195], v[46:49]
	v_mfma_f32_16x16x32_bf16 v[38:41], v[154:157], v[192:195], v[38:41]
	v_mfma_f32_16x16x32_bf16 v[30:33], v[146:149], v[200:203], v[30:33]
	v_mfma_f32_16x16x32_bf16 v[22:25], v[154:157], v[200:203], v[22:25]
	v_mfma_f32_16x16x32_bf16 v[14:17], v[146:149], v[214:217], v[14:17]
	v_mfma_f32_16x16x32_bf16 v[6:9], v[154:157], v[214:217], v[6:9]
	s_setprio 0
	s_setprio 1
	v_mfma_f32_16x16x32_bf16 v[58:61], v[158:161], v[174:177], v[58:61]
	v_mfma_f32_16x16x32_bf16 v[50:53], v[166:169], v[174:177], v[50:53]
	v_mfma_f32_16x16x32_bf16 v[42:45], v[158:161], v[188:191], v[42:45]
	v_mfma_f32_16x16x32_bf16 v[34:37], v[166:169], v[188:191], v[34:37]
	v_mfma_f32_16x16x32_bf16 v[26:29], v[158:161], v[196:199], v[26:29]
	v_mfma_f32_16x16x32_bf16 v[18:21], v[166:169], v[196:199], v[18:21]
	v_mfma_f32_16x16x32_bf16 v[10:13], v[158:161], v[204:207], v[10:13]
	v_mfma_f32_16x16x32_bf16 v[2:5], v[166:169], v[204:207], v[2:5]
	v_mfma_f32_16x16x32_bf16 v[58:61], v[162:165], v[184:187], v[58:61]
	v_mfma_f32_16x16x32_bf16 v[50:53], v[170:173], v[184:187], v[50:53]
	v_mfma_f32_16x16x32_bf16 v[42:45], v[162:165], v[192:195], v[42:45]
	v_mfma_f32_16x16x32_bf16 v[34:37], v[170:173], v[192:195], v[34:37]
	v_mfma_f32_16x16x32_bf16 v[26:29], v[162:165], v[200:203], v[26:29]
	v_mfma_f32_16x16x32_bf16 v[18:21], v[170:173], v[200:203], v[18:21]
	v_mfma_f32_16x16x32_bf16 v[10:13], v[162:165], v[214:217], v[10:13]
	v_mfma_f32_16x16x32_bf16 v[2:5], v[170:173], v[214:217], v[2:5]
	s_barrier
	s_setprio 0
	v_or_b32_e32 v142, 0x18000, v141
	v_add_u32_e32 v146, 0x18400, v141
	v_add_u32_e32 v150, 0x18800, v141
	v_add_u32_e32 v154, 0x18c00, v141
	v_or_b32_e32 v158, 0x1c000, v141
	v_add_u32_e32 v162, 0x1c400, v141
	v_add_u32_e32 v166, 0x1c800, v141
	v_add_u32_e32 v170, 0x1cc00, v141
	ds_read_b128 v[142:145], v142
	ds_read_b128 v[146:149], v146
	ds_read_b128 v[150:153], v150
	ds_read_b128 v[154:157], v154
	ds_read_b128 v[158:161], v158
	ds_read_b128 v[162:165], v162
	ds_read_b128 v[166:169], v166
	ds_read_b128 v[170:173], v170
	s_add_u32 s86, s86, 0x40000
	s_addc_u32 s87, s87, 0
	s_mov_b32 m0, s35
	v_lshl_add_u64 v[220:221], s[86:87], 0, v[134:135]
	ds_read_b128 v[174:177], v140 offset:32768
	ds_read_b128 v[184:187], v140 offset:33792
	ds_read_b128 v[188:191], v140 offset:34816
	ds_read_b128 v[192:195], v140 offset:35840
	ds_read_b128 v[196:199], v140 offset:36864
	ds_read_b128 v[200:203], v140 offset:37888
	ds_read_b128 v[204:207], v140 offset:38912
	ds_read_b128 v[214:217], v140 offset:39936
	global_load_lds_dwordx4 v[220:221], off
	v_lshl_add_u64 v[220:221], s[86:87], 0, v[132:133]
	s_mov_b32 m0, s88
	s_nop 0
	global_load_lds_dwordx4 v[220:221], off
	s_waitcnt vmcnt(8)
	s_waitcnt lgkmcnt(0)
	s_barrier
	s_setprio 1
	s_waitcnt lgkmcnt(0)
	v_mfma_f32_16x16x32_bf16 v[126:129], v[142:145], v[174:177], v[126:129]
	v_mfma_f32_16x16x32_bf16 v[118:121], v[150:153], v[174:177], v[118:121]
	v_mfma_f32_16x16x32_bf16 v[110:113], v[142:145], v[188:191], v[110:113]
	v_mfma_f32_16x16x32_bf16 v[102:105], v[150:153], v[188:191], v[102:105]
	v_mfma_f32_16x16x32_bf16 v[94:97], v[142:145], v[196:199], v[94:97]
	v_mfma_f32_16x16x32_bf16 v[86:89], v[150:153], v[196:199], v[86:89]
	v_mfma_f32_16x16x32_bf16 v[78:81], v[142:145], v[204:207], v[78:81]
	v_mfma_f32_16x16x32_bf16 v[70:73], v[150:153], v[204:207], v[70:73]
	v_mfma_f32_16x16x32_bf16 v[126:129], v[146:149], v[184:187], v[126:129]
	v_mfma_f32_16x16x32_bf16 v[118:121], v[154:157], v[184:187], v[118:121]
	v_mfma_f32_16x16x32_bf16 v[110:113], v[146:149], v[192:195], v[110:113]
	v_mfma_f32_16x16x32_bf16 v[102:105], v[154:157], v[192:195], v[102:105]
	v_mfma_f32_16x16x32_bf16 v[94:97], v[146:149], v[200:203], v[94:97]
	v_mfma_f32_16x16x32_bf16 v[86:89], v[154:157], v[200:203], v[86:89]
	v_mfma_f32_16x16x32_bf16 v[78:81], v[146:149], v[214:217], v[78:81]
	v_mfma_f32_16x16x32_bf16 v[70:73], v[154:157], v[214:217], v[70:73]
	s_setprio 0
	s_setprio 1
	v_mfma_f32_16x16x32_bf16 v[122:125], v[158:161], v[174:177], v[122:125]
	v_mfma_f32_16x16x32_bf16 v[114:117], v[166:169], v[174:177], v[114:117]
	v_mfma_f32_16x16x32_bf16 v[106:109], v[158:161], v[188:191], v[106:109]
	v_mfma_f32_16x16x32_bf16 v[98:101], v[166:169], v[188:191], v[98:101]
	v_mfma_f32_16x16x32_bf16 v[90:93], v[158:161], v[196:199], v[90:93]
	v_mfma_f32_16x16x32_bf16 v[82:85], v[166:169], v[196:199], v[82:85]
	v_mfma_f32_16x16x32_bf16 v[74:77], v[158:161], v[204:207], v[74:77]
	v_mfma_f32_16x16x32_bf16 v[66:69], v[166:169], v[204:207], v[66:69]
	v_mfma_f32_16x16x32_bf16 v[122:125], v[162:165], v[184:187], v[122:125]
	v_mfma_f32_16x16x32_bf16 v[114:117], v[170:173], v[184:187], v[114:117]
	v_mfma_f32_16x16x32_bf16 v[106:109], v[162:165], v[192:195], v[106:109]
	v_mfma_f32_16x16x32_bf16 v[98:101], v[170:173], v[192:195], v[98:101]
	v_mfma_f32_16x16x32_bf16 v[90:93], v[162:165], v[200:203], v[90:93]
	v_mfma_f32_16x16x32_bf16 v[82:85], v[170:173], v[200:203], v[82:85]
	v_mfma_f32_16x16x32_bf16 v[74:77], v[162:165], v[214:217], v[74:77]
	v_mfma_f32_16x16x32_bf16 v[66:69], v[170:173], v[214:217], v[66:69]
	s_barrier
; #define PG8_STAGE(bufoff, gbase, voff) do { _Pragma("unroll") for (int _i = 0; _i < 2; ++_i) \
;         __builtin_amdgcn_global_load_lds((const unsigned*)((const char*)(gbase) + (voff)[_i]), (PG8_LAS unsigned*)(lds + (bufoff) + ldsw + _i * 8192), 16, 0, 0); } while (0)
; #define PG8_LDA(dst, b, h) do { _Pragma("unroll") for (int m = 0; m < 4; ++m) _Pragma("unroll") for (int k = 0; k < 2; ++k) dst[m][k] = *(const PG8_LAS bf16x8*)(lds + PG8_SA(b, h) + aoff + m * 2048 + k * 1024); } while (0)
; #define PG8_MMA(ai, bj, At, Bt) do { __builtin_amdgcn_s_setprio(1); _Pragma("unroll") for (int m = 0; m < 4; ++m) _Pragma("unroll") for (int n = 0; n < 2; ++n) _Pragma("unroll") for (int k = 0; k < 2; ++k) \
;         acc[ai][bj][m][n] = __builtin_amdgcn_mfma_f32_16x16x32_bf16(Bt[n][k], At[m][k], acc[ai][bj][m][n], 0, 0, 0); __builtin_amdgcn_s_setprio(0); } while (0)
; #define PG8_WAIT_V(n) asm volatile("s_waitcnt vmcnt(" #n ")" ::: "memory")
; #define PG8_WAIT_L(n) asm volatile("s_waitcnt lgkmcnt(" #n ")" ::: "memory")
; #define PG8_BAR __builtin_amdgcn_s_barrier()
; #define PG8_SCHED __builtin_amdgcn_sched_barrier(0)
; template <class Epi, class Sched, bool ALIGN_EPI = false, bool SP2 = false>
; __device__ __forceinline__ void gemm_phase(PG8_LAS unsigned char* lds, const Gemm g, const Sched& S, const Epi& E, const int tid) {
;     ...
;             PG8_WAIT_V(8); PG8_WAIT_L(0); PG8_BAR; PG8_MMA(0, 0, At, B0); PG8_MMA(0, 1, At, B1); PG8_BAR; PG8_SCHED;
;             PG8_LDA(At, 1, 1); PG8_STAGE(PG8_SB(1, 0), b3, voffB); PG8_STAGE(PG8_SB(1, 1), b3 + hstep, voffB); PG8_STAGE(PG8_SA(1, 0), a3, voffA);
;             PG8_WAIT_V(8); PG8_WAIT_L(0); PG8_BAR; PG8_MMA(1, 0, At, B0); PG8_MMA(1, 1, At, B1); PG8_BAR; PG8_SCHED;
;     ...
;         if constexpr (ALIGN_EPI) { if (wr == 0) PG8_BAR; }
	s_setprio 0
	s_mov_b32 m0, s0
	v_lshl_add_u64 v[178:179], v[178:179], 0, s[12:13]
	s_add_u32 s84, s84, 0x40080
	ds_read_b128 v[174:177], v140 offset:49152
	ds_read_b128 v[184:187], v140 offset:50176
	ds_read_b128 v[188:191], v140 offset:51200
	ds_read_b128 v[192:195], v140 offset:52224
	ds_read_b128 v[196:199], v140 offset:53248
	ds_read_b128 v[200:203], v140 offset:54272
	ds_read_b128 v[204:207], v140 offset:55296
	ds_read_b128 v[214:217], v140 offset:56320
	global_load_lds_dwordx4 v[178:179], off
	v_lshl_add_u64 v[178:179], v[180:181], 0, s[12:13]
	s_mov_b32 m0, s17
	s_addc_u32 s85, s85, 0
	global_load_lds_dwordx4 v[178:179], off
	v_lshl_add_u64 v[178:179], s[84:85], 0, v[0:1]
	s_mov_b32 m0, s51
	s_nop 0
	global_load_lds_dwordx4 v[178:179], off
	v_lshl_add_u64 v[178:179], s[84:85], 0, v[130:131]
	s_mov_b32 m0, s26
	s_nop 0
	global_load_lds_dwordx4 v[178:179], off
	v_lshl_add_u64 v[178:179], v[182:183], 0, s[12:13]
	s_mov_b32 m0, s91
	s_nop 0
	global_load_lds_dwordx4 v[178:179], off
	v_lshl_add_u64 v[178:179], v[218:219], 0, s[12:13]
	s_mov_b32 m0, s50
	s_nop 0
	global_load_lds_dwordx4 v[178:179], off
	s_waitcnt vmcnt(8)
	s_waitcnt lgkmcnt(0)
	s_barrier
	s_setprio 1
	s_waitcnt lgkmcnt(0)
	v_mfma_f32_16x16x32_bf16 v[62:65], v[142:145], v[174:177], v[62:65]
	v_mfma_f32_16x16x32_bf16 v[54:57], v[150:153], v[174:177], v[54:57]
	v_mfma_f32_16x16x32_bf16 v[46:49], v[142:145], v[188:191], v[46:49]
	v_mfma_f32_16x16x32_bf16 v[38:41], v[150:153], v[188:191], v[38:41]
	v_mfma_f32_16x16x32_bf16 v[30:33], v[142:145], v[196:199], v[30:33]
	v_mfma_f32_16x16x32_bf16 v[22:25], v[150:153], v[196:199], v[22:25]
	v_mfma_f32_16x16x32_bf16 v[14:17], v[142:145], v[204:207], v[14:17]
	v_mfma_f32_16x16x32_bf16 v[6:9], v[150:153], v[204:207], v[6:9]
	v_mfma_f32_16x16x32_bf16 v[62:65], v[146:149], v[184:187], v[62:65]
	v_mfma_f32_16x16x32_bf16 v[54:57], v[154:157], v[184:187], v[54:57]
	v_mfma_f32_16x16x32_bf16 v[46:49], v[146:149], v[192:195], v[46:49]
	v_mfma_f32_16x16x32_bf16 v[38:41], v[154:157], v[192:195], v[38:41]
	v_mfma_f32_16x16x32_bf16 v[30:33], v[146:149], v[200:203], v[30:33]
	v_mfma_f32_16x16x32_bf16 v[22:25], v[154:157], v[200:203], v[22:25]
	v_mfma_f32_16x16x32_bf16 v[14:17], v[146:149], v[214:217], v[14:17]
	v_mfma_f32_16x16x32_bf16 v[6:9], v[154:157], v[214:217], v[6:9]
	s_setprio 0
	s_setprio 1
	v_mfma_f32_16x16x32_bf16 v[58:61], v[158:161], v[174:177], v[58:61]
	v_mfma_f32_16x16x32_bf16 v[50:53], v[166:169], v[174:177], v[50:53]
	v_mfma_f32_16x16x32_bf16 v[42:45], v[158:161], v[188:191], v[42:45]
	v_mfma_f32_16x16x32_bf16 v[34:37], v[166:169], v[188:191], v[34:37]
	v_mfma_f32_16x16x32_bf16 v[26:29], v[158:161], v[196:199], v[26:29]
	v_mfma_f32_16x16x32_bf16 v[18:21], v[166:169], v[196:199], v[18:21]
	v_mfma_f32_16x16x32_bf16 v[10:13], v[158:161], v[204:207], v[10:13]
	v_mfma_f32_16x16x32_bf16 v[2:5], v[166:169], v[204:207], v[2:5]
	v_mfma_f32_16x16x32_bf16 v[58:61], v[162:165], v[184:187], v[58:61]
	v_mfma_f32_16x16x32_bf16 v[50:53], v[170:173], v[184:187], v[50:53]
	v_mfma_f32_16x16x32_bf16 v[42:45], v[162:165], v[192:195], v[42:45]
	v_mfma_f32_16x16x32_bf16 v[34:37], v[170:173], v[192:195], v[34:37]
	v_mfma_f32_16x16x32_bf16 v[26:29], v[162:165], v[200:203], v[26:29]
	v_mfma_f32_16x16x32_bf16 v[18:21], v[170:173], v[200:203], v[18:21]
	v_mfma_f32_16x16x32_bf16 v[10:13], v[162:165], v[214:217], v[10:13]
	v_mfma_f32_16x16x32_bf16 v[2:5], v[170:173], v[214:217], v[2:5]
	s_barrier
	s_setprio 0
	s_add_i32 s43, s43, 2
	s_add_u32 s30, s30, 0x100
	s_addc_u32 s31, s31, 0
	s_add_u32 s24, s24, 0x100
	s_addc_u32 s41, s41, 0
	s_cmp_gt_u32 s43, 13
	s_cbranch_scc0 .LBB0_713
	s_and_b64 vcc, exec, s[38:39]
	s_cbranch_vccz .LBB0_716
	s_barrier
